# 68 bf16 round+pack chains (attention probabilities, gather output) as v_cvt_pk_bf16_f32; removed slots kept as s_nop 0 so no hazard distance changes
# speedup vs baseline: 1.0000x; 1.0000x over previous
.LBB0_138:
	s_not_b32 s0, s3
	s_add_i32 s2, s1, s0
	v_readlane_b32 s0, v249, 57
	v_readlane_b32 s1, v249, 58
	s_and_b64 s[0:1], s[0:1], exec
	v_writelane_b32 v249, s3, 59
	s_cselect_b32 s0, s3, s2
	v_readlane_b32 s2, v249, 7
	s_mul_i32 s16, s0, s2
	v_readlane_b32 s0, v249, 54
	s_add_i32 s16, s16, s0
	s_cmpk_gt_i32 s16, 0x9ff
	v_readlane_b32 s3, v249, 8
	s_cbranch_scc1 .LBB0_137
	s_cmpk_gt_i32 s16, 0x3ff
	s_mov_b64 s[0:1], -1
	s_cbranch_scc0 .LBB0_260
	s_cmpk_gt_u32 s16, 0x5ff
	s_cbranch_scc0 .LBB0_250
	v_readlane_b32 s0, v249, 30
	v_readlane_b32 s1, v249, 31
	s_load_dwordx2 s[0:1], s[0:1], 0x148
	s_and_b32 s17, s16, 0x1fc
	s_bitset1_b32 s17, 14
	s_mul_i32 s2, s17, 0xe00
	s_waitcnt lgkmcnt(0)
	s_add_u32 s8, s0, s2
	s_addc_u32 s9, s1, 0
	s_cmpk_gt_u32 s16, 0x7ff
	s_mov_b64 s[0:1], -1
	s_cbranch_scc0 .LBB0_154
	v_readlane_b32 s10, v249, 30
	v_readlane_b32 s11, v249, 31
	s_add_i32 s6, s16, 0xfffff800
	s_load_dwordx4 s[0:3], s[10:11], 0x20
	s_lshr_b32 s4, s6, 2
	v_readlane_b32 s5, v249, 48
	s_add_i32 s4, s4, s5
	s_ashr_i32 s5, s4, 31
	s_lshl_b64 s[4:5], s[4:5], 18
	s_waitcnt lgkmcnt(0)
	s_add_u32 s7, s0, s4
	s_addc_u32 s1, s1, s5
	s_lshl_b32 s0, s6, 6
	s_and_b32 s0, s0, 0xc0
	s_lshl_b32 s10, s0, 2
	s_add_u32 s6, s7, s10
	s_addc_u32 s7, s1, 0
	v_mov_b32_e32 v52, v220
	s_add_u32 s1, s2, s4
	s_addc_u32 s3, s3, s5
	v_lshlrev_b32_e32 v0, 3, v52
	v_and_b32_e32 v53, 56, v0
	v_ashrrev_i32_e32 v36, 3, v52
	s_add_u32 s2, s1, s10
	v_lshlrev_b32_e32 v0, 2, v53
	v_mov_b32_e32 v1, v80
	v_ashrrev_i32_e32 v37, 31, v36
	s_addc_u32 s3, s3, 0
	v_lshl_add_u64 v[28:29], s[6:7], 0, v[0:1]
	v_lshlrev_b64 v[10:11], 10, v[36:37]
	v_lshl_add_u64 v[32:33], s[2:3], 0, v[0:1]
	v_lshl_add_u64 v[0:1], v[28:29], 0, v[10:11]
	global_load_dwordx4 v[2:5], v[0:1], off offset:16
	global_load_dwordx4 v[6:9], v[0:1], off
	s_movk_i32 s1, 0x20e
	s_movk_i32 s13, 0x90
	s_waitcnt vmcnt(0)
	s_nop 0
	s_nop 0
	s_nop 0
	s_nop 0
	s_nop 0
	v_cvt_pk_bf16_f32 v0, v6, v7
	s_nop 0
	s_nop 0
	s_nop 0
	s_nop 0
	s_nop 0
	v_cvt_pk_bf16_f32 v1, v8, v9
	s_nop 0
	s_nop 0
	s_nop 0
	s_nop 0
	s_nop 0
	v_cvt_pk_bf16_f32 v2, v2, v3
	s_nop 0
	s_nop 0
	s_nop 0
	s_nop 0
	s_nop 0
	v_lshl_add_u64 v[8:9], v[32:33], 0, v[10:11]
	v_cvt_pk_bf16_f32 v3, v4, v5
	global_load_dwordx4 v[4:7], v[8:9], off offset:16
	s_nop 0
	global_load_dwordx4 v[8:11], v[8:9], off
	s_waitcnt vmcnt(0)
	v_bfe_u32 v12, v8, 16, 1
	v_add3_u32 v37, v8, v12, s33
	v_bfe_u32 v8, v9, 16, 1
	v_add3_u32 v54, v9, v8, s33
	v_bfe_u32 v8, v10, 16, 1
	v_add3_u32 v55, v10, v8, s33
	v_bfe_u32 v8, v11, 16, 1
	v_add3_u32 v56, v11, v8, s33
	v_bfe_u32 v8, v4, 16, 1
	v_add3_u32 v57, v4, v8, s33
	v_bfe_u32 v4, v5, 16, 1
	v_add3_u32 v58, v5, v4, s33
	v_bfe_u32 v4, v6, 16, 1
	v_add3_u32 v59, v6, v4, s33
	v_bfe_u32 v4, v7, 16, 1
	v_add3_u32 v60, v7, v4, s33
	v_add_u32_e32 v4, 0x100, v52
	v_ashrrev_i32_e32 v38, 3, v4
	v_ashrrev_i32_e32 v39, 31, v38
	v_lshlrev_b64 v[14:15], 10, v[38:39]
	v_lshl_add_u64 v[4:5], v[28:29], 0, v[14:15]
	global_load_dwordx4 v[6:9], v[4:5], off offset:16
	global_load_dwordx4 v[10:13], v[4:5], off
	s_waitcnt vmcnt(0)
	s_nop 0
	s_nop 0
	s_nop 0
	s_nop 0
	s_nop 0
	v_cvt_pk_bf16_f32 v4, v10, v11
	s_nop 0
	s_nop 0
	s_nop 0
	s_nop 0
	s_nop 0
	v_cvt_pk_bf16_f32 v5, v12, v13
	s_nop 0
	s_nop 0
	s_nop 0
	s_nop 0
	s_nop 0
	v_cvt_pk_bf16_f32 v6, v6, v7
	s_nop 0
	s_nop 0
	s_nop 0
	s_nop 0
	s_nop 0
	v_lshl_add_u64 v[12:13], v[32:33], 0, v[14:15]
	v_cvt_pk_bf16_f32 v7, v8, v9
	global_load_dwordx4 v[8:11], v[12:13], off offset:16
	s_nop 0
	global_load_dwordx4 v[12:15], v[12:13], off
	s_waitcnt vmcnt(0)
	v_bfe_u32 v16, v12, 16, 1
	v_add3_u32 v39, v12, v16, s33
	v_bfe_u32 v12, v13, 16, 1
	v_add3_u32 v61, v13, v12, s33
	v_bfe_u32 v12, v14, 16, 1
	v_add3_u32 v62, v14, v12, s33
	v_bfe_u32 v12, v15, 16, 1
	v_add3_u32 v63, v15, v12, s33
	v_bfe_u32 v12, v8, 16, 1
	v_add3_u32 v64, v8, v12, s33
	v_bfe_u32 v8, v9, 16, 1
	v_add3_u32 v65, v9, v8, s33
	v_bfe_u32 v8, v10, 16, 1
	v_add3_u32 v66, v10, v8, s33
	v_bfe_u32 v8, v11, 16, 1
	v_add3_u32 v67, v11, v8, s33
	v_add_u32_e32 v8, 0x200, v52
	v_ashrrev_i32_e32 v40, 3, v8
	v_ashrrev_i32_e32 v41, 31, v40
	v_lshlrev_b64 v[18:19], 10, v[40:41]
	v_lshl_add_u64 v[8:9], v[28:29], 0, v[18:19]
	global_load_dwordx4 v[10:13], v[8:9], off offset:16
	global_load_dwordx4 v[14:17], v[8:9], off
	s_waitcnt vmcnt(0)
	s_nop 0
	s_nop 0
	s_nop 0
	s_nop 0
	s_nop 0
	v_cvt_pk_bf16_f32 v8, v14, v15
	s_nop 0
	s_nop 0
	s_nop 0
	s_nop 0
	s_nop 0
	v_cvt_pk_bf16_f32 v9, v16, v17
	s_nop 0
	s_nop 0
	s_nop 0
	s_nop 0
	s_nop 0
	v_cvt_pk_bf16_f32 v10, v10, v11
	s_nop 0
	s_nop 0
	s_nop 0
	s_nop 0
	s_nop 0
	v_lshl_add_u64 v[16:17], v[32:33], 0, v[18:19]
	v_cvt_pk_bf16_f32 v11, v12, v13
	global_load_dwordx4 v[12:15], v[16:17], off offset:16
	s_nop 0
	global_load_dwordx4 v[16:19], v[16:17], off
	s_waitcnt vmcnt(0)
	v_bfe_u32 v20, v16, 16, 1
	v_add3_u32 v41, v16, v20, s33
	v_bfe_u32 v16, v17, 16, 1
	v_add3_u32 v68, v17, v16, s33
	v_bfe_u32 v16, v18, 16, 1
	v_add3_u32 v69, v18, v16, s33
	v_bfe_u32 v16, v19, 16, 1
	v_add3_u32 v70, v19, v16, s33
	v_bfe_u32 v16, v12, 16, 1
	v_add3_u32 v71, v12, v16, s33
	v_bfe_u32 v12, v13, 16, 1
	v_add3_u32 v72, v13, v12, s33
	v_bfe_u32 v12, v14, 16, 1
	v_add3_u32 v73, v14, v12, s33
	v_bfe_u32 v12, v15, 16, 1
	v_add3_u32 v74, v15, v12, s33
	v_add_u32_e32 v12, 0x300, v52
	v_ashrrev_i32_e32 v42, 3, v12
	v_ashrrev_i32_e32 v43, 31, v42
	v_lshlrev_b64 v[22:23], 10, v[42:43]
	v_lshl_add_u64 v[12:13], v[28:29], 0, v[22:23]
	global_load_dwordx4 v[14:17], v[12:13], off offset:16
	global_load_dwordx4 v[18:21], v[12:13], off
	s_waitcnt vmcnt(0)
	s_nop 0
	s_nop 0
	s_nop 0
	s_nop 0
	s_nop 0
	v_cvt_pk_bf16_f32 v12, v18, v19
	s_nop 0
	s_nop 0
	s_nop 0
	s_nop 0
	s_nop 0
	v_cvt_pk_bf16_f32 v13, v20, v21
	s_nop 0
	s_nop 0
	s_nop 0
	s_nop 0
	s_nop 0
	v_cvt_pk_bf16_f32 v14, v14, v15
	s_nop 0
	s_nop 0
	s_nop 0
	s_nop 0
	s_nop 0
	v_lshl_add_u64 v[20:21], v[32:33], 0, v[22:23]
	v_cvt_pk_bf16_f32 v15, v16, v17
	global_load_dwordx4 v[16:19], v[20:21], off offset:16
	s_nop 0
	global_load_dwordx4 v[20:23], v[20:21], off
	s_waitcnt vmcnt(0)
	v_bfe_u32 v24, v20, 16, 1
	v_add3_u32 v43, v20, v24, s33
	v_bfe_u32 v20, v21, 16, 1
	v_add3_u32 v75, v21, v20, s33
	v_bfe_u32 v20, v22, 16, 1
	v_add3_u32 v76, v22, v20, s33
	v_bfe_u32 v20, v23, 16, 1
	v_add3_u32 v77, v23, v20, s33
	v_bfe_u32 v20, v16, 16, 1
	v_add3_u32 v78, v16, v20, s33
	v_bfe_u32 v16, v17, 16, 1
	v_add3_u32 v79, v17, v16, s33
	v_bfe_u32 v16, v18, 16, 1
	v_add3_u32 v81, v18, v16, s33
	v_bfe_u32 v16, v19, 16, 1
	v_add3_u32 v82, v19, v16, s33
	v_add_u32_e32 v16, 0x400, v52
	v_ashrrev_i32_e32 v44, 3, v16
	v_ashrrev_i32_e32 v45, 31, v44
	v_lshlrev_b64 v[26:27], 10, v[44:45]
	v_lshl_add_u64 v[16:17], v[28:29], 0, v[26:27]
	global_load_dwordx4 v[18:21], v[16:17], off offset:16
	global_load_dwordx4 v[22:25], v[16:17], off
	s_waitcnt vmcnt(0)
	s_nop 0
	s_nop 0
	s_nop 0
	s_nop 0
	s_nop 0
	v_cvt_pk_bf16_f32 v16, v22, v23
	s_nop 0
	s_nop 0
	s_nop 0
	s_nop 0
	s_nop 0
	v_cvt_pk_bf16_f32 v17, v24, v25
	s_nop 0
	s_nop 0
	s_nop 0
	s_nop 0
	s_nop 0
	v_cvt_pk_bf16_f32 v18, v18, v19
	s_nop 0
	s_nop 0
	s_nop 0
	s_nop 0
	s_nop 0
	v_lshl_add_u64 v[24:25], v[32:33], 0, v[26:27]
	v_cvt_pk_bf16_f32 v19, v20, v21
	global_load_dwordx4 v[20:23], v[24:25], off offset:16
	s_nop 0
	global_load_dwordx4 v[24:27], v[24:25], off
	s_waitcnt vmcnt(0)
	v_bfe_u32 v30, v24, 16, 1
	v_add3_u32 v45, v24, v30, s33
	v_bfe_u32 v24, v25, 16, 1
	v_add3_u32 v83, v25, v24, s33
	v_bfe_u32 v24, v26, 16, 1
	v_add3_u32 v84, v26, v24, s33
	v_bfe_u32 v24, v27, 16, 1
	v_add3_u32 v85, v27, v24, s33
	v_bfe_u32 v24, v20, 16, 1
	v_add3_u32 v86, v20, v24, s33
	v_bfe_u32 v20, v21, 16, 1
	v_add3_u32 v87, v21, v20, s33
	v_bfe_u32 v20, v22, 16, 1
	v_add3_u32 v88, v22, v20, s33
	v_bfe_u32 v20, v23, 16, 1
	v_add3_u32 v89, v23, v20, s33
	v_add_u32_e32 v20, 0x500, v52
	v_ashrrev_i32_e32 v46, 3, v20
	v_ashrrev_i32_e32 v47, 31, v46
	v_lshlrev_b64 v[26:27], 10, v[46:47]
	v_lshl_add_u64 v[20:21], v[28:29], 0, v[26:27]
	global_load_dwordx4 v[22:25], v[20:21], off offset:16
	global_load_dwordx4 v[48:51], v[20:21], off
	s_waitcnt vmcnt(0)
	s_nop 0
	s_nop 0
	s_nop 0
	s_nop 0
	s_nop 0
	v_cvt_pk_bf16_f32 v20, v48, v49
	s_nop 0
	s_nop 0
	s_nop 0
	s_nop 0
	s_nop 0
	v_cvt_pk_bf16_f32 v21, v50, v51
	s_nop 0
	s_nop 0
	s_nop 0
	s_nop 0
	s_nop 0
	v_cvt_pk_bf16_f32 v22, v22, v23
	s_nop 0
	s_nop 0
	s_nop 0
	s_nop 0
	s_nop 0
	v_lshl_add_u64 v[30:31], v[32:33], 0, v[26:27]
	v_cvt_pk_bf16_f32 v23, v24, v25
	global_load_dwordx4 v[24:27], v[30:31], off offset:16
	global_load_dwordx4 v[48:51], v[30:31], off
	s_waitcnt vmcnt(0)
	v_bfe_u32 v30, v48, 16, 1
	v_add3_u32 v47, v48, v30, s33
	v_bfe_u32 v30, v49, 16, 1
	v_add3_u32 v90, v49, v30, s33
	v_bfe_u32 v30, v50, 16, 1
	v_add3_u32 v91, v50, v30, s33
	v_bfe_u32 v30, v51, 16, 1
	v_add3_u32 v92, v51, v30, s33
	v_bfe_u32 v30, v24, 16, 1
	v_add3_u32 v93, v24, v30, s33
	v_bfe_u32 v24, v25, 16, 1
	v_add3_u32 v94, v25, v24, s33
	v_bfe_u32 v24, v26, 16, 1
	v_add3_u32 v95, v26, v24, s33
	v_bfe_u32 v24, v27, 16, 1
	v_add3_u32 v96, v27, v24, s33
	v_add_u32_e32 v24, 0x600, v52
	v_ashrrev_i32_e32 v48, 3, v24
	v_ashrrev_i32_e32 v49, 31, v48
	v_lshlrev_b64 v[30:31], 10, v[48:49]
	v_lshl_add_u64 v[24:25], v[28:29], 0, v[30:31]
	global_load_dwordx4 v[98:101], v[24:25], off offset:16
	s_nop 0
	global_load_dwordx4 v[24:27], v[24:25], off
	v_lshl_add_u64 v[30:31], v[32:33], 0, v[30:31]
	s_waitcnt vmcnt(0)
	s_nop 0
	s_nop 0
	s_nop 0
	s_nop 0
	s_nop 0
	v_cvt_pk_bf16_f32 v24, v24, v25
	s_nop 0
	s_nop 0
	s_nop 0
	s_nop 0
	s_nop 0
	v_cvt_pk_bf16_f32 v25, v26, v27
	s_nop 0
	s_nop 0
	s_nop 0
	s_nop 0
	s_nop 0
	v_cvt_pk_bf16_f32 v26, v98, v99
	v_bfe_u32 v27, v100, 16, 1
	v_bfe_u32 v34, v101, 16, 1
	v_add3_u32 v27, v100, v27, s33
	v_add3_u32 v34, v101, v34, s33
	global_load_dwordx4 v[100:103], v[30:31], off offset:16
	global_load_dwordx4 v[104:107], v[30:31], off
	v_lshrrev_b32_e32 v27, 16, v27
	v_and_or_b32 v27, v34, s29, v27
	s_waitcnt vmcnt(0)
	v_bfe_u32 v30, v104, 16, 1
	v_add3_u32 v49, v104, v30, s33
	v_bfe_u32 v30, v105, 16, 1
	v_add3_u32 v97, v105, v30, s33
	v_bfe_u32 v30, v106, 16, 1
	v_add3_u32 v98, v106, v30, s33
	v_bfe_u32 v30, v107, 16, 1
	v_add3_u32 v99, v107, v30, s33
	v_bfe_u32 v30, v100, 16, 1
	v_add3_u32 v100, v100, v30, s33
	v_bfe_u32 v30, v101, 16, 1
	v_add3_u32 v101, v101, v30, s33
	v_bfe_u32 v30, v102, 16, 1
	v_add3_u32 v102, v102, v30, s33
	v_bfe_u32 v30, v103, 16, 1
	v_add3_u32 v103, v103, v30, s33
	v_add_u32_e32 v30, 0x700, v52
	v_ashrrev_i32_e32 v50, 3, v30
	v_ashrrev_i32_e32 v51, 31, v50
	v_lshlrev_b64 v[34:35], 10, v[50:51]
	v_lshl_add_u64 v[28:29], v[28:29], 0, v[34:35]
	global_load_dwordx4 v[104:107], v[28:29], off offset:16
	s_nop 0
	global_load_dwordx4 v[28:31], v[28:29], off
	s_waitcnt vmcnt(0)
	s_nop 0
	s_nop 0
	s_nop 0
	s_nop 0
	s_nop 0
	v_cvt_pk_bf16_f32 v28, v28, v29
	s_nop 0
	s_nop 0
	s_nop 0
	s_nop 0
	s_nop 0
	v_cvt_pk_bf16_f32 v29, v30, v31
	s_nop 0
	s_nop 0
	s_nop 0
	s_nop 0
	s_nop 0
	v_cvt_pk_bf16_f32 v30, v104, v105
	v_bfe_u32 v31, v106, 16, 1
	v_bfe_u32 v51, v107, 16, 1
	v_lshl_add_u64 v[104:105], v[32:33], 0, v[34:35]
	v_add3_u32 v31, v106, v31, s33
	v_add3_u32 v51, v107, v51, s33
	global_load_dwordx4 v[32:35], v[104:105], off offset:16
	s_nop 0
	global_load_dwordx4 v[104:107], v[104:105], off
	v_lshrrev_b32_e32 v31, 16, v31
	v_and_or_b32 v31, v51, s29, v31
	s_waitcnt vmcnt(0)
	v_bfe_u32 v51, v104, 16, 1
	v_add3_u32 v51, v104, v51, s33
	v_bfe_u32 v104, v105, 16, 1
	v_add3_u32 v104, v105, v104, s33
	v_bfe_u32 v105, v106, 16, 1
	v_add3_u32 v105, v106, v105, s33
	v_bfe_u32 v106, v107, 16, 1
	v_add3_u32 v106, v107, v106, s33
	v_bfe_u32 v107, v32, 16, 1
	v_add3_u32 v107, v32, v107, s33
	v_bfe_u32 v32, v33, 16, 1
	v_add3_u32 v33, v33, v32, s33
	v_bfe_u32 v32, v34, 16, 1
	v_add3_u32 v108, v34, v32, s33
	v_bfe_u32 v32, v35, 16, 1
	v_add3_u32 v109, v35, v32, s33
	v_lshlrev_b32_e32 v32, 1, v53
	v_mad_u32_u24 v53, v53, s1, v32
	s_movk_i32 s1, 0x90
	v_mad_u64_u32 v[34:35], s[2:3], v36, s1, v[32:33]
	ds_write_b128 v34, v[0:3]
	v_lshl_add_u32 v0, v36, 1, v53
	ds_write_b16_d16_hi v0, v37 offset:36864
	ds_write_b16_d16_hi v0, v54 offset:37392
	ds_write_b16_d16_hi v0, v55 offset:37920
	ds_write_b16_d16_hi v0, v56 offset:38448
	ds_write_b16_d16_hi v0, v57 offset:38976
	ds_write_b16_d16_hi v0, v58 offset:39504
	ds_write_b16_d16_hi v0, v59 offset:40032
	ds_write_b16_d16_hi v0, v60 offset:40560
	v_mad_u64_u32 v[0:1], s[2:3], v38, s1, v[32:33]
	ds_write_b128 v0, v[4:7]
	v_lshl_add_u32 v0, v38, 1, v53
	ds_write_b16_d16_hi v0, v39 offset:36864
	ds_write_b16_d16_hi v0, v61 offset:37392
	ds_write_b16_d16_hi v0, v62 offset:37920
	ds_write_b16_d16_hi v0, v63 offset:38448
	ds_write_b16_d16_hi v0, v64 offset:38976
	ds_write_b16_d16_hi v0, v65 offset:39504
	ds_write_b16_d16_hi v0, v66 offset:40032
	ds_write_b16_d16_hi v0, v67 offset:40560
	v_mad_u64_u32 v[0:1], s[2:3], v40, s1, v[32:33]
	ds_write_b128 v0, v[8:11]
	v_lshl_add_u32 v0, v40, 1, v53
	ds_write_b16_d16_hi v0, v41 offset:36864
	ds_write_b16_d16_hi v0, v68 offset:37392
	ds_write_b16_d16_hi v0, v69 offset:37920
	ds_write_b16_d16_hi v0, v70 offset:38448
	ds_write_b16_d16_hi v0, v71 offset:38976
	ds_write_b16_d16_hi v0, v72 offset:39504
	ds_write_b16_d16_hi v0, v73 offset:40032
	ds_write_b16_d16_hi v0, v74 offset:40560
	v_mad_u64_u32 v[0:1], s[2:3], v42, s1, v[32:33]
	ds_write_b128 v0, v[12:15]
	v_lshl_add_u32 v0, v42, 1, v53
	ds_write_b16_d16_hi v0, v43 offset:36864
	ds_write_b16_d16_hi v0, v75 offset:37392
	ds_write_b16_d16_hi v0, v76 offset:37920
	ds_write_b16_d16_hi v0, v77 offset:38448
	ds_write_b16_d16_hi v0, v78 offset:38976
	ds_write_b16_d16_hi v0, v79 offset:39504
	ds_write_b16_d16_hi v0, v81 offset:40032
	ds_write_b16_d16_hi v0, v82 offset:40560
	v_mad_u64_u32 v[0:1], s[2:3], v44, s1, v[32:33]
	ds_write_b128 v0, v[16:19]
	v_lshl_add_u32 v0, v44, 1, v53
	ds_write_b16_d16_hi v0, v45 offset:36864
	ds_write_b16_d16_hi v0, v83 offset:37392
	ds_write_b16_d16_hi v0, v84 offset:37920
	ds_write_b16_d16_hi v0, v85 offset:38448
	ds_write_b16_d16_hi v0, v86 offset:38976
	ds_write_b16_d16_hi v0, v87 offset:39504
	ds_write_b16_d16_hi v0, v88 offset:40032
	ds_write_b16_d16_hi v0, v89 offset:40560
	v_mad_u64_u32 v[0:1], s[2:3], v46, s1, v[32:33]
	ds_write_b128 v0, v[20:23]
	v_lshl_add_u32 v0, v46, 1, v53
	ds_write_b16_d16_hi v0, v47 offset:36864
	ds_write_b16_d16_hi v0, v90 offset:37392
	ds_write_b16_d16_hi v0, v91 offset:37920
	ds_write_b16_d16_hi v0, v92 offset:38448
	ds_write_b16_d16_hi v0, v93 offset:38976
	ds_write_b16_d16_hi v0, v94 offset:39504
	ds_write_b16_d16_hi v0, v95 offset:40032
	ds_write_b16_d16_hi v0, v96 offset:40560
	v_mad_u64_u32 v[0:1], s[2:3], v48, s1, v[32:33]
	ds_write_b128 v0, v[24:27]
	v_lshl_add_u32 v0, v48, 1, v53
	ds_write_b16_d16_hi v0, v49 offset:36864
	ds_write_b16_d16_hi v0, v97 offset:37392
	ds_write_b16_d16_hi v0, v98 offset:37920
	ds_write_b16_d16_hi v0, v99 offset:38448
	ds_write_b16_d16_hi v0, v100 offset:38976
	ds_write_b16_d16_hi v0, v101 offset:39504
	ds_write_b16_d16_hi v0, v102 offset:40032
	ds_write_b16_d16_hi v0, v103 offset:40560
	v_mad_u64_u32 v[0:1], s[2:3], v50, s1, v[32:33]
	ds_write_b128 v0, v[28:31]
	v_lshl_add_u32 v0, v50, 1, v53
	ds_write_b16_d16_hi v0, v51 offset:36864
	ds_write_b16_d16_hi v0, v104 offset:37392
	ds_write_b16_d16_hi v0, v105 offset:37920
	ds_write_b16_d16_hi v0, v106 offset:38448
	ds_write_b16_d16_hi v0, v107 offset:38976
	ds_write_b16_d16_hi v0, v33 offset:39504
	ds_write_b16_d16_hi v0, v108 offset:40032
	ds_write_b16_d16_hi v0, v109 offset:40560
	v_ashrrev_i32_e32 v0, 2, v52
	v_cmp_gt_i32_e32 vcc, 16, v0
	s_waitcnt lgkmcnt(0)
	s_barrier
	s_and_saveexec_b64 s[4:5], vcc
	s_cbranch_execz .LBB0_153
	s_lshl_b32 s12, s0, 1
	v_readlane_b32 s0, v249, 30
	v_readlane_b32 s1, v249, 31
	s_load_dwordx2 s[6:7], s[0:1], 0x150
	s_add_u32 s2, s8, s12
	v_bfi_b32 v68, -16, v0, v52
	s_addc_u32 s3, s9, 0
	v_cmp_gt_i32_e64 s[0:1], 4, v68
	v_cmp_lt_i32_e32 vcc, 3, v68
	s_and_saveexec_b64 s[10:11], vcc
	s_xor_b64 s[10:11], exec, s[10:11]
	s_cbranch_execz .LBB0_145
	v_mov_b32_e32 v4, v80
	s_nop 0
	v_mov_b64_e32 v[0:1], v[4:5]
	v_mov_b64_e32 v[2:3], v[6:7]

.LBB0_151:
	s_or_b64 exec, exec, s[10:11]
	v_and_b32_e32 v5, 64, v229
	v_mov_b32_e32 v1, v4
	v_xor_b32_e32 v4, 16, v229
	v_add_u32_e32 v5, 64, v5
	v_cmp_lt_i32_e32 vcc, v4, v5
	v_and_b32_e32 v71, 15, v52
	v_mad_u32_u24 v79, v71, s13, v72
	v_cndmask_b32_e32 v78, v229, v4, vcc
	v_xor_b32_e32 v4, 32, v229
	v_cmp_lt_i32_e32 vcc, v4, v5
	v_mov_b32_e32 v65, v6
	v_cndmask_b32_e32 v73, v229, v4, vcc
	v_lshlrev_b32_e32 v73, 2, v73
	ds_read_b128 v[116:119], v79
	ds_read_b128 v[120:123], v79 offset:64
	ds_read_b128 v[124:127], v79 offset:2304
	ds_read_b128 v[128:131], v79 offset:2368
	ds_read_b128 v[132:135], v79 offset:4608
	ds_read_b128 v[136:139], v79 offset:4672
	ds_read_b128 v[140:143], v79 offset:6912
	ds_read_b128 v[144:147], v79 offset:6976
	ds_read_b128 v[148:151], v79 offset:9216
	ds_read_b128 v[152:155], v79 offset:9280
	ds_read_b128 v[156:159], v79 offset:11520
	ds_read_b128 v[160:163], v79 offset:11584
	s_waitcnt lgkmcnt(6)
	v_mfma_f32_16x16x32_bf16 v[60:63], v[116:119], v[0:3], 0
	v_mfma_f32_16x16x32_bf16 v[56:59], v[124:127], v[0:3], 0
	v_mfma_f32_16x16x32_bf16 v[52:55], v[132:135], v[0:3], 0
	v_mfma_f32_16x16x32_bf16 v[60:63], v[120:123], v[64:67], v[60:63]
	v_mfma_f32_16x16x32_bf16 v[56:59], v[128:131], v[64:67], v[56:59]
	v_mfma_f32_16x16x32_bf16 v[52:55], v[136:139], v[64:67], v[52:55]
	ds_read_b128 v[116:119], v79 offset:13824
	ds_read_b128 v[120:123], v79 offset:13888
	ds_read_b128 v[124:127], v79 offset:16128
	ds_read_b128 v[128:131], v79 offset:16192
	ds_read_b128 v[132:135], v79 offset:18432
	ds_read_b128 v[136:139], v79 offset:18496
	s_waitcnt lgkmcnt(6)
	v_mfma_f32_16x16x32_bf16 v[48:51], v[140:143], v[0:3], 0
	v_mfma_f32_16x16x32_bf16 v[44:47], v[148:151], v[0:3], 0
	v_mfma_f32_16x16x32_bf16 v[40:43], v[156:159], v[0:3], 0
	v_mfma_f32_16x16x32_bf16 v[48:51], v[144:147], v[64:67], v[48:51]
	v_mfma_f32_16x16x32_bf16 v[44:47], v[152:155], v[64:67], v[44:47]
	v_mfma_f32_16x16x32_bf16 v[40:43], v[160:163], v[64:67], v[40:43]
	ds_read_b128 v[140:143], v79 offset:20736
	ds_read_b128 v[144:147], v79 offset:20800
	ds_read_b128 v[148:151], v79 offset:23040
	ds_read_b128 v[152:155], v79 offset:23104
	ds_read_b128 v[156:159], v79 offset:25344
	ds_read_b128 v[160:163], v79 offset:25408
	s_waitcnt lgkmcnt(6)
	v_mfma_f32_16x16x32_bf16 v[36:39], v[116:119], v[0:3], 0
	v_mfma_f32_16x16x32_bf16 v[32:35], v[124:127], v[0:3], 0
	v_mfma_f32_16x16x32_bf16 v[28:31], v[132:135], v[0:3], 0
	v_mfma_f32_16x16x32_bf16 v[36:39], v[120:123], v[64:67], v[36:39]
	v_mfma_f32_16x16x32_bf16 v[32:35], v[128:131], v[64:67], v[32:35]
	v_mfma_f32_16x16x32_bf16 v[28:31], v[136:139], v[64:67], v[28:31]
	ds_read_b128 v[116:119], v79 offset:27648
	ds_read_b128 v[120:123], v79 offset:27712
	ds_read_b128 v[124:127], v79 offset:29952
	ds_read_b128 v[128:131], v79 offset:30016
	ds_read_b128 v[132:135], v79 offset:32256
	ds_read_b128 v[136:139], v79 offset:32320
	s_waitcnt lgkmcnt(6)
	v_mfma_f32_16x16x32_bf16 v[24:27], v[140:143], v[0:3], 0
	v_mfma_f32_16x16x32_bf16 v[20:23], v[148:151], v[0:3], 0
	v_mfma_f32_16x16x32_bf16 v[16:19], v[156:159], v[0:3], 0
	v_mfma_f32_16x16x32_bf16 v[24:27], v[144:147], v[64:67], v[24:27]
	v_mfma_f32_16x16x32_bf16 v[20:23], v[152:155], v[64:67], v[20:23]
	v_mfma_f32_16x16x32_bf16 v[16:19], v[160:163], v[64:67], v[16:19]
	s_waitcnt lgkmcnt(0)
	v_mfma_f32_16x16x32_bf16 v[12:15], v[116:119], v[0:3], 0
	v_mfma_f32_16x16x32_bf16 v[8:11], v[124:127], v[0:3], 0
	v_mfma_f32_16x16x32_bf16 v[4:7], v[132:135], v[0:3], 0
	v_mfma_f32_16x16x32_bf16 v[12:15], v[120:123], v[64:67], v[12:15]
	v_mfma_f32_16x16x32_bf16 v[8:11], v[128:131], v[64:67], v[8:11]
	v_mfma_f32_16x16x32_bf16 v[4:7], v[136:139], v[64:67], v[4:7]
	ds_read_b128 v[116:119], v79 offset:34560
	ds_read_b128 v[120:123], v79 offset:34624
	s_waitcnt lgkmcnt(0)
	v_mfma_f32_16x16x32_bf16 v[124:127], v[116:119], v[0:3], 0
	v_mfma_f32_16x16x32_bf16 v[0:3], v[120:123], v[64:67], v[124:127]
	v_mul_f32_e32 v64, 0x3e000000, v60
	v_mul_f32_e32 v65, 0x3e000000, v61
	s_mov_b32 s2, 0xff61b1e6
	v_max3_f32 v64, v64, s2, v65
	v_mul_f32_e32 v65, 0x3e000000, v62
	v_mul_f32_e32 v66, 0x3e000000, v63
	v_max3_f32 v64, v64, v65, v66
	v_mul_f32_e32 v65, 0x3e000000, v56
	v_mul_f32_e32 v66, 0x3e000000, v57
	v_max3_f32 v64, v64, v65, v66
	v_mul_f32_e32 v65, 0x3e000000, v58
	v_mul_f32_e32 v66, 0x3e000000, v59
	v_max3_f32 v64, v64, v65, v66
	v_mul_f32_e32 v65, 0x3e000000, v52
	v_mul_f32_e32 v66, 0x3e000000, v53
	v_max3_f32 v64, v64, v65, v66
	v_mul_f32_e32 v65, 0x3e000000, v54
	v_mul_f32_e32 v66, 0x3e000000, v55
	v_max3_f32 v64, v64, v65, v66
	v_mul_f32_e32 v65, 0x3e000000, v48
	v_mul_f32_e32 v66, 0x3e000000, v49
	v_max3_f32 v64, v64, v65, v66
	v_mul_f32_e32 v65, 0x3e000000, v50
	v_mul_f32_e32 v66, 0x3e000000, v51
	v_max3_f32 v64, v64, v65, v66
	v_mul_f32_e32 v65, 0x3e000000, v44
	v_mul_f32_e32 v66, 0x3e000000, v45
	v_max3_f32 v64, v64, v65, v66
	v_mul_f32_e32 v65, 0x3e000000, v46
	v_mul_f32_e32 v66, 0x3e000000, v47
	v_max3_f32 v64, v64, v65, v66
	v_mul_f32_e32 v65, 0x3e000000, v40
	v_mul_f32_e32 v66, 0x3e000000, v41
	v_max3_f32 v64, v64, v65, v66
	v_mul_f32_e32 v65, 0x3e000000, v42
	v_mul_f32_e32 v66, 0x3e000000, v43
	v_max3_f32 v64, v64, v65, v66
	v_mul_f32_e32 v65, 0x3e000000, v36
	v_mul_f32_e32 v66, 0x3e000000, v37
	v_max3_f32 v64, v64, v65, v66
	v_mul_f32_e32 v65, 0x3e000000, v38
	v_mul_f32_e32 v66, 0x3e000000, v39
	v_max3_f32 v64, v64, v65, v66
	v_mul_f32_e32 v65, 0x3e000000, v32
	v_mul_f32_e32 v66, 0x3e000000, v33
	v_max3_f32 v64, v64, v65, v66
	v_mul_f32_e32 v65, 0x3e000000, v34
	v_mul_f32_e32 v66, 0x3e000000, v35
	v_max3_f32 v64, v64, v65, v66
	v_mul_f32_e32 v65, 0x3e000000, v28
	v_mul_f32_e32 v66, 0x3e000000, v29
	v_max3_f32 v64, v64, v65, v66
	v_mul_f32_e32 v65, 0x3e000000, v30
	v_mul_f32_e32 v66, 0x3e000000, v31
	v_max3_f32 v64, v64, v65, v66
	v_mul_f32_e32 v65, 0x3e000000, v24
	v_mul_f32_e32 v66, 0x3e000000, v25
	v_max3_f32 v64, v64, v65, v66
	v_mul_f32_e32 v65, 0x3e000000, v26
	v_mul_f32_e32 v66, 0x3e000000, v27
	v_max3_f32 v64, v64, v65, v66
	v_mul_f32_e32 v65, 0x3e000000, v20
	v_mul_f32_e32 v66, 0x3e000000, v21
	v_max3_f32 v64, v64, v65, v66
	v_mul_f32_e32 v65, 0x3e000000, v22
	v_mul_f32_e32 v66, 0x3e000000, v23
	v_max3_f32 v64, v64, v65, v66
	v_mul_f32_e32 v65, 0x3e000000, v16
	v_mul_f32_e32 v66, 0x3e000000, v17
	v_max3_f32 v64, v64, v65, v66
	v_mul_f32_e32 v65, 0x3e000000, v18
	v_mul_f32_e32 v66, 0x3e000000, v19
	v_max3_f32 v64, v64, v65, v66
	v_mul_f32_e32 v65, 0x3e000000, v12
	v_mul_f32_e32 v66, 0x3e000000, v13
	v_max3_f32 v64, v64, v65, v66
	v_mul_f32_e32 v65, 0x3e000000, v14
	v_mul_f32_e32 v66, 0x3e000000, v15
	v_max3_f32 v64, v64, v65, v66
	v_mul_f32_e32 v65, 0x3e000000, v8
	v_mul_f32_e32 v66, 0x3e000000, v9
	v_max3_f32 v64, v64, v65, v66
	v_mul_f32_e32 v65, 0x3e000000, v10
	v_mul_f32_e32 v66, 0x3e000000, v11
	v_max3_f32 v64, v64, v65, v66
	v_mul_f32_e32 v65, 0x3e000000, v4
	v_mul_f32_e32 v66, 0x3e000000, v5
	v_max3_f32 v64, v64, v65, v66
	v_mul_f32_e32 v65, 0x3e000000, v6
	v_mul_f32_e32 v66, 0x3e000000, v7
	v_max3_f32 v64, v64, v65, v66
	v_mul_f32_e32 v65, 0x3e000000, v0
	v_mul_f32_e32 v66, 0x3e000000, v1
	v_max3_f32 v64, v64, v65, v66
	v_mul_f32_e32 v65, 0x3e000000, v2
	v_mul_f32_e32 v66, 0x3e000000, v3
	v_max3_f32 v64, v64, v65, v66
	v_lshlrev_b32_e32 v74, 2, v78
	ds_bpermute_b32 v65, v74, v64
	s_mov_b32 s2, 0x3e000000
	v_sub_u32_e32 v72, v72, v70
	s_waitcnt lgkmcnt(0)
	v_max_f32_e32 v65, v65, v65
	v_max_f32_e32 v64, v64, v65
	ds_bpermute_b32 v65, v73, v64
	s_waitcnt lgkmcnt(0)
	v_max_f32_e32 v65, v65, v65
	v_max_f32_e32 v75, v64, v65
	v_fma_f32 v60, v60, s2, -v75
	v_fma_f32 v61, v61, s2, -v75
	v_mul_f32_e32 v60, 0x3fb8aa3b, v60
	v_mul_f32_e32 v61, 0x3fb8aa3b, v61
	v_exp_f32_e32 v60, v60
	v_exp_f32_e32 v64, v61
	v_fma_f32 v61, v62, s2, -v75
	v_mul_f32_e32 v61, 0x3fb8aa3b, v61
	v_exp_f32_e32 v61, v61
	v_add_f32_e32 v65, 0, v60
	v_fma_f32 v63, v63, s2, -v75
	v_add_f32_e32 v65, v64, v65
	v_mul_f32_e32 v63, 0x3fb8aa3b, v63
	v_add_f32_e32 v62, v61, v65
	v_exp_f32_e32 v65, v63
	v_fma_f32 v56, v56, s2, -v75
	v_mul_f32_e32 v56, 0x3fb8aa3b, v56
	v_fma_f32 v57, v57, s2, -v75
	v_add_f32_e32 v63, v65, v62
	v_exp_f32_e32 v62, v56
	v_mul_f32_e32 v57, 0x3fb8aa3b, v57
	v_exp_f32_e32 v66, v57
	v_fma_f32 v57, v58, s2, -v75
	v_mul_f32_e32 v57, 0x3fb8aa3b, v57
	v_add_f32_e32 v56, v62, v63
	v_exp_f32_e32 v63, v57
	v_fma_f32 v57, v59, s2, -v75
	v_mul_f32_e32 v57, 0x3fb8aa3b, v57
	v_fma_f32 v52, v52, s2, -v75
	v_exp_f32_e32 v67, v57
	v_mul_f32_e32 v52, 0x3fb8aa3b, v52
	v_exp_f32_e32 v52, v52
	v_add_f32_e32 v56, v66, v56
	v_add_f32_e32 v56, v63, v56
	v_fma_f32 v53, v53, s2, -v75
	v_add_f32_e32 v56, v67, v56
	v_mul_f32_e32 v53, 0x3fb8aa3b, v53
	v_add_f32_e32 v57, v52, v56
	v_exp_f32_e32 v56, v53
	v_fma_f32 v53, v54, s2, -v75
	v_mul_f32_e32 v53, 0x3fb8aa3b, v53
	v_exp_f32_e32 v53, v53
	v_fma_f32 v55, v55, s2, -v75
	v_add_f32_e32 v57, v56, v57
	v_mul_f32_e32 v55, 0x3fb8aa3b, v55
	v_add_f32_e32 v54, v53, v57
	v_exp_f32_e32 v57, v55
	v_fma_f32 v48, v48, s2, -v75
	v_mul_f32_e32 v48, 0x3fb8aa3b, v48
	v_fma_f32 v49, v49, s2, -v75
	v_add_f32_e32 v55, v57, v54
	v_exp_f32_e32 v54, v48
	v_mul_f32_e32 v49, 0x3fb8aa3b, v49
	v_exp_f32_e32 v58, v49
	v_fma_f32 v49, v50, s2, -v75
	v_mul_f32_e32 v49, 0x3fb8aa3b, v49
	v_add_f32_e32 v48, v54, v55
	v_exp_f32_e32 v55, v49
	v_fma_f32 v49, v51, s2, -v75
	v_mul_f32_e32 v49, 0x3fb8aa3b, v49
	v_fma_f32 v44, v44, s2, -v75
	v_exp_f32_e32 v59, v49
	v_mul_f32_e32 v44, 0x3fb8aa3b, v44
	v_exp_f32_e32 v44, v44
	v_add_f32_e32 v48, v58, v48
	v_add_f32_e32 v48, v55, v48
	v_fma_f32 v45, v45, s2, -v75
	v_add_f32_e32 v48, v59, v48
	v_mul_f32_e32 v45, 0x3fb8aa3b, v45
	v_add_f32_e32 v49, v44, v48
	v_exp_f32_e32 v48, v45
	v_fma_f32 v45, v46, s2, -v75
	v_mul_f32_e32 v45, 0x3fb8aa3b, v45
	v_exp_f32_e32 v45, v45
	v_fma_f32 v47, v47, s2, -v75
	v_add_f32_e32 v49, v48, v49
	v_mul_f32_e32 v47, 0x3fb8aa3b, v47
	v_add_f32_e32 v46, v45, v49
	v_exp_f32_e32 v49, v47
	v_fma_f32 v40, v40, s2, -v75
	v_mul_f32_e32 v40, 0x3fb8aa3b, v40
	v_fma_f32 v41, v41, s2, -v75
	v_add_f32_e32 v47, v49, v46
	v_exp_f32_e32 v46, v40
	v_mul_f32_e32 v41, 0x3fb8aa3b, v41
	v_exp_f32_e32 v50, v41
	v_fma_f32 v41, v42, s2, -v75
	v_mul_f32_e32 v41, 0x3fb8aa3b, v41
	v_add_f32_e32 v40, v46, v47
	v_exp_f32_e32 v47, v41
	v_fma_f32 v41, v43, s2, -v75
	v_mul_f32_e32 v41, 0x3fb8aa3b, v41
	v_fma_f32 v36, v36, s2, -v75
	v_exp_f32_e32 v51, v41
	v_mul_f32_e32 v36, 0x3fb8aa3b, v36
	v_exp_f32_e32 v36, v36
	v_add_f32_e32 v40, v50, v40
	v_add_f32_e32 v40, v47, v40
	v_fma_f32 v37, v37, s2, -v75
	v_add_f32_e32 v40, v51, v40
	v_mul_f32_e32 v37, 0x3fb8aa3b, v37
	v_add_f32_e32 v41, v36, v40
	v_exp_f32_e32 v40, v37
	v_fma_f32 v37, v38, s2, -v75
	v_mul_f32_e32 v37, 0x3fb8aa3b, v37
	v_exp_f32_e32 v37, v37
	v_fma_f32 v39, v39, s2, -v75
	v_add_f32_e32 v41, v40, v41
	v_mul_f32_e32 v39, 0x3fb8aa3b, v39
	v_add_f32_e32 v38, v37, v41
	v_exp_f32_e32 v41, v39
	v_fma_f32 v32, v32, s2, -v75
	v_mul_f32_e32 v32, 0x3fb8aa3b, v32
	v_fma_f32 v33, v33, s2, -v75
	v_add_f32_e32 v39, v41, v38
	v_exp_f32_e32 v38, v32
	v_mul_f32_e32 v33, 0x3fb8aa3b, v33
	v_exp_f32_e32 v42, v33
	v_fma_f32 v33, v34, s2, -v75
	v_mul_f32_e32 v33, 0x3fb8aa3b, v33
	v_add_f32_e32 v32, v38, v39
	v_exp_f32_e32 v39, v33
	v_fma_f32 v33, v35, s2, -v75
	v_mul_f32_e32 v33, 0x3fb8aa3b, v33
	v_fma_f32 v28, v28, s2, -v75
	v_exp_f32_e32 v43, v33
	v_mul_f32_e32 v28, 0x3fb8aa3b, v28
	v_exp_f32_e32 v28, v28
	v_add_f32_e32 v32, v42, v32
	v_add_f32_e32 v32, v39, v32
	v_fma_f32 v29, v29, s2, -v75
	v_add_f32_e32 v32, v43, v32
	v_mul_f32_e32 v29, 0x3fb8aa3b, v29
	v_add_f32_e32 v33, v28, v32
	v_exp_f32_e32 v32, v29
	v_fma_f32 v29, v30, s2, -v75
	v_mul_f32_e32 v29, 0x3fb8aa3b, v29
	v_exp_f32_e32 v29, v29
	v_fma_f32 v31, v31, s2, -v75
	v_add_f32_e32 v33, v32, v33
	v_mul_f32_e32 v31, 0x3fb8aa3b, v31
	v_add_f32_e32 v30, v29, v33
	v_exp_f32_e32 v33, v31
	v_fma_f32 v24, v24, s2, -v75
	v_mul_f32_e32 v24, 0x3fb8aa3b, v24
	v_fma_f32 v25, v25, s2, -v75
	v_add_f32_e32 v31, v33, v30
	v_exp_f32_e32 v30, v24
	v_mul_f32_e32 v25, 0x3fb8aa3b, v25
	v_exp_f32_e32 v34, v25
	v_fma_f32 v25, v26, s2, -v75
	v_mul_f32_e32 v25, 0x3fb8aa3b, v25
	v_add_f32_e32 v24, v30, v31
	v_exp_f32_e32 v31, v25
	v_fma_f32 v25, v27, s2, -v75
	v_mul_f32_e32 v25, 0x3fb8aa3b, v25
	v_fma_f32 v20, v20, s2, -v75
	v_exp_f32_e32 v35, v25
	v_mul_f32_e32 v20, 0x3fb8aa3b, v20
	v_exp_f32_e32 v20, v20
	v_add_f32_e32 v24, v34, v24
	v_add_f32_e32 v24, v31, v24
	v_fma_f32 v21, v21, s2, -v75
	v_add_f32_e32 v24, v35, v24
	v_mul_f32_e32 v21, 0x3fb8aa3b, v21
	v_add_f32_e32 v25, v20, v24
	v_exp_f32_e32 v24, v21
	v_fma_f32 v21, v22, s2, -v75
	v_mul_f32_e32 v21, 0x3fb8aa3b, v21
	v_exp_f32_e32 v21, v21
	v_fma_f32 v23, v23, s2, -v75
	v_add_f32_e32 v25, v24, v25
	v_mul_f32_e32 v23, 0x3fb8aa3b, v23
	v_add_f32_e32 v22, v21, v25
	v_exp_f32_e32 v25, v23
	v_fma_f32 v16, v16, s2, -v75
	v_mul_f32_e32 v16, 0x3fb8aa3b, v16
	v_fma_f32 v17, v17, s2, -v75
	v_add_f32_e32 v23, v25, v22
	v_exp_f32_e32 v22, v16
	v_mul_f32_e32 v17, 0x3fb8aa3b, v17
	v_exp_f32_e32 v26, v17
	v_fma_f32 v17, v18, s2, -v75
	v_mul_f32_e32 v17, 0x3fb8aa3b, v17
	v_add_f32_e32 v16, v22, v23
	v_exp_f32_e32 v23, v17
	v_fma_f32 v17, v19, s2, -v75
	v_mul_f32_e32 v17, 0x3fb8aa3b, v17
	v_fma_f32 v12, v12, s2, -v75
	v_exp_f32_e32 v27, v17
	v_mul_f32_e32 v12, 0x3fb8aa3b, v12
	v_exp_f32_e32 v12, v12
	v_add_f32_e32 v16, v26, v16
	v_add_f32_e32 v16, v23, v16
	v_fma_f32 v13, v13, s2, -v75
	v_add_f32_e32 v16, v27, v16
	v_mul_f32_e32 v13, 0x3fb8aa3b, v13
	v_add_f32_e32 v17, v12, v16
	v_exp_f32_e32 v16, v13
	v_fma_f32 v13, v14, s2, -v75
	v_mul_f32_e32 v13, 0x3fb8aa3b, v13
	v_exp_f32_e32 v13, v13
	v_fma_f32 v15, v15, s2, -v75
	v_add_f32_e32 v17, v16, v17
	v_mul_f32_e32 v15, 0x3fb8aa3b, v15
	v_add_f32_e32 v14, v13, v17
	v_exp_f32_e32 v17, v15
	v_fma_f32 v8, v8, s2, -v75
	v_mul_f32_e32 v8, 0x3fb8aa3b, v8
	v_fma_f32 v9, v9, s2, -v75
	v_add_f32_e32 v15, v17, v14
	v_exp_f32_e32 v14, v8
	v_mul_f32_e32 v9, 0x3fb8aa3b, v9
	v_exp_f32_e32 v18, v9
	v_fma_f32 v9, v10, s2, -v75
	v_mul_f32_e32 v9, 0x3fb8aa3b, v9
	v_add_f32_e32 v8, v14, v15
	v_exp_f32_e32 v15, v9
	v_fma_f32 v9, v11, s2, -v75
	v_mul_f32_e32 v9, 0x3fb8aa3b, v9
	v_fma_f32 v4, v4, s2, -v75
	v_exp_f32_e32 v19, v9
	v_mul_f32_e32 v4, 0x3fb8aa3b, v4
	v_exp_f32_e32 v4, v4
	v_add_f32_e32 v8, v18, v8
	v_add_f32_e32 v8, v15, v8
	v_fma_f32 v5, v5, s2, -v75
	v_add_f32_e32 v8, v19, v8
	v_mul_f32_e32 v5, 0x3fb8aa3b, v5
	v_add_f32_e32 v9, v4, v8
	v_exp_f32_e32 v8, v5
	v_fma_f32 v5, v6, s2, -v75
	v_mul_f32_e32 v5, 0x3fb8aa3b, v5
	v_exp_f32_e32 v5, v5
	v_fma_f32 v7, v7, s2, -v75
	v_add_f32_e32 v9, v8, v9
	v_mul_f32_e32 v7, 0x3fb8aa3b, v7
	v_fma_f32 v0, v0, s2, -v75
	v_add_f32_e32 v6, v5, v9
	v_exp_f32_e32 v9, v7
	v_mul_f32_e32 v0, 0x3fb8aa3b, v0
	v_exp_f32_e32 v0, v0
	v_fma_f32 v1, v1, s2, -v75
	v_add_f32_e32 v6, v9, v6
	v_mul_f32_e32 v1, 0x3fb8aa3b, v1
	v_add_f32_e32 v7, v0, v6
	v_exp_f32_e32 v6, v1
	v_fma_f32 v1, v2, s2, -v75
	v_mul_f32_e32 v1, 0x3fb8aa3b, v1
	v_exp_f32_e32 v1, v1
	v_fma_f32 v3, v3, s2, -v75
	v_add_f32_e32 v7, v6, v7
	v_mul_f32_e32 v3, 0x3fb8aa3b, v3
	v_add_f32_e32 v2, v1, v7
	v_exp_f32_e32 v7, v3
	s_nop 0
	v_add_f32_e32 v2, v7, v2
	ds_bpermute_b32 v3, v74, v2
	s_waitcnt lgkmcnt(0)
	v_add_f32_e32 v2, v2, v3
	ds_bpermute_b32 v3, v73, v2
	s_waitcnt lgkmcnt(0)
	v_add_f32_e32 v2, v2, v3
	v_div_scale_f32 v3, s[2:3], v2, v2, 1.0
	v_rcp_f32_e32 v10, v3
	v_div_scale_f32 v11, vcc, 1.0, v2, 1.0
	s_movk_i32 s2, 0x210
	v_fma_f32 v73, -v3, v10, 1.0
	v_fmac_f32_e32 v10, v73, v10
	v_mul_f32_e32 v73, v11, v10
	v_fma_f32 v74, -v3, v73, v11
	v_fmac_f32_e32 v73, v74, v10
	v_fma_f32 v3, -v3, v73, v11
	v_div_fmas_f32 v3, v3, v10, v73
	v_div_fixup_f32 v2, v3, v2, 1.0
	v_pk_mul_f32 v[10:11], v[60:61], v[2:3] op_sel_hi:[1,0]
	v_pk_mul_f32 v[60:61], v[64:65], v[2:3] op_sel_hi:[1,0]
	v_pk_mul_f32 v[64:65], v[66:67], v[2:3] op_sel_hi:[1,0]
	v_pk_mul_f32 v[62:63], v[62:63], v[2:3] op_sel_hi:[1,0]
	v_bfe_u32 v3, v65, 16, 1
	v_bfe_u32 v66, v64, 16, 1
	v_bfe_u32 v67, v61, 16, 1
	v_bfe_u32 v73, v60, 16, 1
	v_add3_u32 v65, v65, v3, s33
	v_bfe_u32 v3, v10, 16, 1
	v_mad_u32_u24 v71, v71, s2, v72
	v_add3_u32 v73, v60, v73, s33
	v_add3_u32 v74, v61, v67, s33
	v_add3_u32 v64, v64, v66, s33
	v_bfe_u32 v60, v11, 16, 1
	v_bfe_u32 v61, v62, 16, 1
	v_bfe_u32 v66, v63, 16, 1
	v_add3_u32 v10, v10, v3, s33
	v_add_u32_e32 v3, 0x9000, v71
	v_add3_u32 v66, v63, v66, s33
	v_add3_u32 v67, v62, v61, s33
	v_add3_u32 v11, v11, v60, s33
	ds_read2_b64 v[60:63], v3 offset1:4
	v_lshrrev_b32_e32 v10, 16, v10
	v_lshrrev_b32_e32 v11, 16, v11
	v_lshrrev_b32_e32 v72, 16, v67
	v_lshrrev_b32_e32 v66, 16, v66
	v_and_or_b32 v67, v65, s29, v66
	v_and_or_b32 v66, v64, s29, v72
	v_and_or_b32 v65, v74, s29, v11
	v_and_or_b32 v64, v73, s29, v10
	v_add_u32_e32 v10, 0xb000, v71
	s_waitcnt lgkmcnt(0)
	v_mfma_f32_16x16x32_bf16 v[72:75], v[60:63], v[64:67], 0
	ds_read2_b64 v[60:63], v10 offset0:32 offset1:36
	s_waitcnt lgkmcnt(0)
	v_mfma_f32_16x16x32_bf16 v[76:79], v[60:63], v[64:67], 0
	v_add_u32_e32 v60, 0xd000, v71
	v_add_u32_e32 v61, 0xf000, v71
	ds_read2_b64 v[82:85], v60 offset0:64 offset1:68
	ds_read2_b64 v[86:89], v61 offset0:96 offset1:100
	s_waitcnt lgkmcnt(1)
	v_mfma_f32_16x16x32_bf16 v[82:85], v[82:85], v[64:67], 0
	s_waitcnt lgkmcnt(0)
	v_mfma_f32_16x16x32_bf16 v[62:65], v[86:89], v[64:67], 0
	ds_read2_b64 v[116:119], v3 offset0:8 offset1:12
	ds_read2_b64 v[120:123], v10 offset0:40 offset1:44
	ds_read2_b64 v[124:127], v60 offset0:72 offset1:76
	ds_read2_b64 v[128:131], v61 offset0:104 offset1:108
	v_mul_f32_e64 v56, v56, v2
	v_mul_f32_e64 v57, v57, v2
	v_pk_mul_f32 v[58:59], v[58:59], v[2:3] op_sel_hi:[1,0]
	v_pk_mul_f32 v[52:53], v[52:53], v[2:3] op_sel_hi:[1,0]
	v_pk_mul_f32 v[54:55], v[54:55], v[2:3] op_sel_hi:[1,0]
	v_bfe_u32 v11, v59, 16, 1
	v_bfe_u32 v66, v58, 16, 1
	v_bfe_u32 v67, v57, 16, 1
	v_bfe_u32 v71, v56, 16, 1
	v_add3_u32 v56, v56, v71, s33
	v_add3_u32 v57, v57, v67, s33
	v_add3_u32 v58, v58, v66, s33
	v_add3_u32 v11, v59, v11, s33
	v_bfe_u32 v59, v52, 16, 1
	v_bfe_u32 v66, v53, 16, 1
	v_bfe_u32 v67, v54, 16, 1
	v_bfe_u32 v71, v55, 16, 1
	v_add3_u32 v71, v55, v71, s33
	v_add3_u32 v67, v54, v67, s33
	v_add3_u32 v66, v53, v66, s33
	v_add3_u32 v59, v52, v59, s33
	v_lshrrev_b32_e32 v81, 16, v59
	v_lshrrev_b32_e32 v66, 16, v66
	v_lshrrev_b32_e32 v67, 16, v67
	v_lshrrev_b32_e32 v59, 16, v71
	v_and_or_b32 v59, v11, s29, v59
	v_and_or_b32 v58, v58, s29, v67
	v_and_or_b32 v57, v57, s29, v66
	v_and_or_b32 v56, v56, s29, v81
	s_waitcnt lgkmcnt(3)
	s_nop 1
	v_mfma_f32_16x16x32_bf16 v[52:55], v[116:119], v[56:59], v[72:75]
	s_waitcnt lgkmcnt(2)
	v_mfma_f32_16x16x32_bf16 v[72:75], v[120:123], v[56:59], v[76:79]
	s_waitcnt lgkmcnt(1)
	v_mfma_f32_16x16x32_bf16 v[76:79], v[124:127], v[56:59], v[82:85]
	s_waitcnt lgkmcnt(0)
	v_mfma_f32_16x16x32_bf16 v[56:59], v[128:131], v[56:59], v[62:65]
	ds_read2_b64 v[132:135], v3 offset0:16 offset1:20
	ds_read2_b64 v[136:139], v10 offset0:48 offset1:52
	ds_read2_b64 v[140:143], v60 offset0:80 offset1:84
	ds_read2_b64 v[144:147], v61 offset0:112 offset1:116
	v_mul_f32_e64 v48, v48, v2
	v_mul_f32_e64 v49, v49, v2
	v_pk_mul_f32 v[50:51], v[50:51], v[2:3] op_sel_hi:[1,0]
	v_pk_mul_f32 v[44:45], v[44:45], v[2:3] op_sel_hi:[1,0]
	v_pk_mul_f32 v[46:47], v[46:47], v[2:3] op_sel_hi:[1,0]
	v_bfe_u32 v11, v51, 16, 1
	v_bfe_u32 v62, v50, 16, 1
	s_nop 0
	v_bfe_u32 v64, v48, 16, 1
	v_add3_u32 v48, v48, v64, s33
	s_nop 0
	v_add3_u32 v50, v50, v62, s33
	v_add3_u32 v11, v51, v11, s33
	v_bfe_u32 v51, v44, 16, 1
	s_nop 0
	v_bfe_u32 v63, v46, 16, 1
	v_bfe_u32 v64, v47, 16, 1
	v_add3_u32 v64, v47, v64, s33
	v_add3_u32 v63, v46, v63, s33
	s_nop 0
	v_add3_u32 v51, v44, v51, s33
	v_lshrrev_b32_e32 v65, 16, v51
	s_nop 0
	v_lshrrev_b32_e32 v63, 16, v63
	v_lshrrev_b32_e32 v51, 16, v64
	v_and_or_b32 v51, v11, s29, v51
	v_and_or_b32 v50, v50, s29, v63
	v_cvt_pk_bf16_f32 v49, v45, v49
	v_and_or_b32 v48, v48, s29, v65
	s_waitcnt lgkmcnt(3)
	s_nop 1
	v_mfma_f32_16x16x32_bf16 v[44:47], v[132:135], v[48:51], v[52:55]
	s_waitcnt lgkmcnt(2)
	v_mfma_f32_16x16x32_bf16 v[52:55], v[136:139], v[48:51], v[72:75]
	s_waitcnt lgkmcnt(1)
	v_mfma_f32_16x16x32_bf16 v[62:65], v[140:143], v[48:51], v[76:79]
	s_waitcnt lgkmcnt(0)
	v_mfma_f32_16x16x32_bf16 v[48:51], v[144:147], v[48:51], v[56:59]
	ds_read2_b64 v[116:119], v3 offset0:24 offset1:28
	ds_read2_b64 v[120:123], v10 offset0:56 offset1:60
	ds_read2_b64 v[124:127], v60 offset0:88 offset1:92
	ds_read2_b64 v[128:131], v61 offset0:120 offset1:124
	v_mul_f32_e64 v40, v40, v2
	v_mul_f32_e64 v41, v41, v2
	v_pk_mul_f32 v[42:43], v[42:43], v[2:3] op_sel_hi:[1,0]
	v_pk_mul_f32 v[36:37], v[36:37], v[2:3] op_sel_hi:[1,0]
	v_pk_mul_f32 v[38:39], v[38:39], v[2:3] op_sel_hi:[1,0]
	v_bfe_u32 v11, v43, 16, 1
	v_bfe_u32 v56, v42, 16, 1
	v_bfe_u32 v57, v41, 16, 1
	v_bfe_u32 v58, v40, 16, 1
	v_add3_u32 v40, v40, v58, s33
	v_add3_u32 v41, v41, v57, s33
	v_add3_u32 v42, v42, v56, s33
	v_add3_u32 v11, v43, v11, s33
	v_bfe_u32 v43, v36, 16, 1
	v_bfe_u32 v56, v37, 16, 1
	v_bfe_u32 v57, v38, 16, 1
	v_bfe_u32 v58, v39, 16, 1
	v_add3_u32 v58, v39, v58, s33
	v_add3_u32 v57, v38, v57, s33
	v_add3_u32 v56, v37, v56, s33
	v_add3_u32 v43, v36, v43, s33
	v_lshrrev_b32_e32 v59, 16, v43
	v_lshrrev_b32_e32 v56, 16, v56
	v_lshrrev_b32_e32 v57, 16, v57
	v_lshrrev_b32_e32 v43, 16, v58
	v_and_or_b32 v43, v11, s29, v43
	v_and_or_b32 v42, v42, s29, v57
	v_and_or_b32 v41, v41, s29, v56
	v_and_or_b32 v40, v40, s29, v59
	s_waitcnt lgkmcnt(3)
	s_nop 1
	v_mfma_f32_16x16x32_bf16 v[36:39], v[116:119], v[40:43], v[44:47]
	s_waitcnt lgkmcnt(2)
	v_mfma_f32_16x16x32_bf16 v[44:47], v[120:123], v[40:43], v[52:55]
	s_waitcnt lgkmcnt(1)
	v_mfma_f32_16x16x32_bf16 v[52:55], v[124:127], v[40:43], v[62:65]
	s_waitcnt lgkmcnt(0)
	v_mfma_f32_16x16x32_bf16 v[40:43], v[128:131], v[40:43], v[48:51]
	ds_read2_b64 v[132:135], v3 offset0:32 offset1:36
	ds_read2_b64 v[136:139], v10 offset0:64 offset1:68
	ds_read2_b64 v[140:143], v60 offset0:96 offset1:100
	ds_read2_b64 v[144:147], v61 offset0:128 offset1:132
	v_mul_f32_e64 v32, v32, v2
	v_mul_f32_e64 v33, v33, v2
	v_pk_mul_f32 v[34:35], v[34:35], v[2:3] op_sel_hi:[1,0]
	v_pk_mul_f32 v[28:29], v[28:29], v[2:3] op_sel_hi:[1,0]
	v_pk_mul_f32 v[30:31], v[30:31], v[2:3] op_sel_hi:[1,0]
	v_bfe_u32 v11, v35, 16, 1
	v_bfe_u32 v48, v34, 16, 1
	v_bfe_u32 v49, v33, 16, 1
	v_bfe_u32 v50, v32, 16, 1
	v_add3_u32 v32, v32, v50, s33
	v_add3_u32 v33, v33, v49, s33
	v_add3_u32 v34, v34, v48, s33
	v_add3_u32 v11, v35, v11, s33
	v_bfe_u32 v35, v28, 16, 1
	v_bfe_u32 v48, v29, 16, 1
	v_bfe_u32 v49, v30, 16, 1
	v_bfe_u32 v50, v31, 16, 1
	v_add3_u32 v50, v31, v50, s33
	v_add3_u32 v49, v30, v49, s33
	v_add3_u32 v48, v29, v48, s33
	v_add3_u32 v35, v28, v35, s33
	v_lshrrev_b32_e32 v51, 16, v35
	v_lshrrev_b32_e32 v48, 16, v48
	v_lshrrev_b32_e32 v49, 16, v49
	v_lshrrev_b32_e32 v35, 16, v50
	v_and_or_b32 v35, v11, s29, v35
	v_and_or_b32 v34, v34, s29, v49
	v_and_or_b32 v33, v33, s29, v48
	v_and_or_b32 v32, v32, s29, v51
	s_waitcnt lgkmcnt(3)
	s_nop 1
	v_mfma_f32_16x16x32_bf16 v[28:31], v[132:135], v[32:35], v[36:39]
	s_waitcnt lgkmcnt(2)
	v_mfma_f32_16x16x32_bf16 v[36:39], v[136:139], v[32:35], v[44:47]
	s_waitcnt lgkmcnt(1)
	v_mfma_f32_16x16x32_bf16 v[44:47], v[140:143], v[32:35], v[52:55]
	s_waitcnt lgkmcnt(0)
	v_mfma_f32_16x16x32_bf16 v[32:35], v[144:147], v[32:35], v[40:43]
	ds_read2_b64 v[116:119], v3 offset0:40 offset1:44
	ds_read2_b64 v[120:123], v10 offset0:72 offset1:76
	ds_read2_b64 v[124:127], v60 offset0:104 offset1:108
	ds_read2_b64 v[128:131], v61 offset0:136 offset1:140
	v_mul_f32_e64 v24, v24, v2
	v_mul_f32_e64 v25, v25, v2
	v_pk_mul_f32 v[26:27], v[26:27], v[2:3] op_sel_hi:[1,0]
	v_pk_mul_f32 v[20:21], v[20:21], v[2:3] op_sel_hi:[1,0]
	v_pk_mul_f32 v[22:23], v[22:23], v[2:3] op_sel_hi:[1,0]
	v_bfe_u32 v11, v27, 16, 1
	v_bfe_u32 v40, v26, 16, 1
	v_bfe_u32 v41, v25, 16, 1
	v_bfe_u32 v42, v24, 16, 1
	v_add3_u32 v24, v24, v42, s33
	v_add3_u32 v25, v25, v41, s33
	v_add3_u32 v26, v26, v40, s33
	v_add3_u32 v11, v27, v11, s33
	v_bfe_u32 v27, v20, 16, 1
	v_bfe_u32 v40, v21, 16, 1
	v_bfe_u32 v41, v22, 16, 1
	v_bfe_u32 v42, v23, 16, 1
	v_add3_u32 v42, v23, v42, s33
	v_add3_u32 v41, v22, v41, s33
	v_add3_u32 v40, v21, v40, s33
	v_add3_u32 v27, v20, v27, s33
	v_lshrrev_b32_e32 v43, 16, v27
	v_lshrrev_b32_e32 v40, 16, v40
	v_lshrrev_b32_e32 v41, 16, v41
	v_lshrrev_b32_e32 v27, 16, v42
	v_and_or_b32 v27, v11, s29, v27
	v_and_or_b32 v26, v26, s29, v41
	v_and_or_b32 v25, v25, s29, v40
	v_and_or_b32 v24, v24, s29, v43
	s_waitcnt lgkmcnt(3)
	s_nop 1
	v_mfma_f32_16x16x32_bf16 v[20:23], v[116:119], v[24:27], v[28:31]
	s_waitcnt lgkmcnt(2)
	v_mfma_f32_16x16x32_bf16 v[28:31], v[120:123], v[24:27], v[36:39]
	s_waitcnt lgkmcnt(1)
	v_mfma_f32_16x16x32_bf16 v[36:39], v[124:127], v[24:27], v[44:47]
	s_waitcnt lgkmcnt(0)
	v_mfma_f32_16x16x32_bf16 v[24:27], v[128:131], v[24:27], v[32:35]
	ds_read2_b64 v[132:135], v3 offset0:48 offset1:52
	ds_read2_b64 v[136:139], v10 offset0:80 offset1:84
	ds_read2_b64 v[140:143], v60 offset0:112 offset1:116
	ds_read2_b64 v[144:147], v61 offset0:144 offset1:148
	v_mul_f32_e64 v16, v16, v2
	v_mul_f32_e64 v17, v17, v2
	v_pk_mul_f32 v[18:19], v[18:19], v[2:3] op_sel_hi:[1,0]
	v_pk_mul_f32 v[12:13], v[12:13], v[2:3] op_sel_hi:[1,0]
	v_pk_mul_f32 v[14:15], v[14:15], v[2:3] op_sel_hi:[1,0]
	v_bfe_u32 v11, v19, 16, 1
	v_bfe_u32 v32, v18, 16, 1
	v_bfe_u32 v33, v17, 16, 1
	v_bfe_u32 v34, v16, 16, 1
	v_add3_u32 v16, v16, v34, s33
	v_add3_u32 v17, v17, v33, s33
	v_add3_u32 v18, v18, v32, s33
	v_add3_u32 v11, v19, v11, s33
	v_bfe_u32 v19, v12, 16, 1
	v_bfe_u32 v32, v13, 16, 1
	v_bfe_u32 v33, v14, 16, 1
	v_bfe_u32 v34, v15, 16, 1
	v_add3_u32 v34, v15, v34, s33
	v_add3_u32 v33, v14, v33, s33
	v_add3_u32 v32, v13, v32, s33
	v_add3_u32 v19, v12, v19, s33
	v_lshrrev_b32_e32 v35, 16, v19
	v_lshrrev_b32_e32 v32, 16, v32
	v_lshrrev_b32_e32 v33, 16, v33
	v_lshrrev_b32_e32 v19, 16, v34
	v_and_or_b32 v19, v11, s29, v19
	v_and_or_b32 v18, v18, s29, v33
	v_and_or_b32 v17, v17, s29, v32
	v_and_or_b32 v16, v16, s29, v35
	s_waitcnt lgkmcnt(3)
	s_nop 1
	v_mfma_f32_16x16x32_bf16 v[12:15], v[132:135], v[16:19], v[20:23]
	s_waitcnt lgkmcnt(2)
	v_mfma_f32_16x16x32_bf16 v[20:23], v[136:139], v[16:19], v[28:31]
	s_waitcnt lgkmcnt(1)
	v_mfma_f32_16x16x32_bf16 v[28:31], v[140:143], v[16:19], v[36:39]
	s_waitcnt lgkmcnt(0)
	v_mfma_f32_16x16x32_bf16 v[16:19], v[144:147], v[16:19], v[24:27]
	ds_read2_b64 v[116:119], v3 offset0:56 offset1:60
	ds_read2_b64 v[120:123], v10 offset0:88 offset1:92
	ds_read2_b64 v[124:127], v60 offset0:120 offset1:124
	ds_read2_b64 v[128:131], v61 offset0:152 offset1:156
	v_mul_f32_e64 v8, v8, v2
	v_mul_f32_e64 v9, v9, v2
	v_pk_mul_f32 v[6:7], v[6:7], v[2:3] op_sel_hi:[1,0]
	v_pk_mul_f32 v[4:5], v[4:5], v[2:3] op_sel_hi:[1,0]
	v_pk_mul_f32 v[0:1], v[0:1], v[2:3] op_sel_hi:[1,0]
	s_nop 0
	s_nop 0
	v_bfe_u32 v25, v8, 16, 1
	v_add3_u32 v8, v8, v25, s33
	s_nop 0
	s_nop 0
	v_bfe_u32 v2, v4, 16, 1
	v_bfe_u32 v24, v0, 16, 1
	s_nop 0
	s_nop 0
	v_add3_u32 v24, v0, v24, s33
	v_add3_u32 v4, v4, v2, s33
	v_bfe_u32 v11, v6, 16, 1
	v_add3_u32 v6, v6, v11, s33
	s_nop 0
	s_nop 0
	v_lshrrev_b32_e32 v4, 16, v4
	s_nop 0
	v_lshrrev_b32_e32 v11, 16, v24
	s_nop 0
	v_cvt_pk_bf16_f32 v27, v1, v7
	v_and_or_b32 v26, v6, s29, v11
	v_cvt_pk_bf16_f32 v25, v5, v9
	v_and_or_b32 v24, v8, s29, v4
	s_waitcnt lgkmcnt(3)
	s_nop 1
	v_mfma_f32_16x16x32_bf16 v[12:15], v[116:119], v[24:27], v[12:15]
	s_waitcnt lgkmcnt(2)
	v_mfma_f32_16x16x32_bf16 v[8:11], v[120:123], v[24:27], v[20:23]
	s_waitcnt lgkmcnt(1)
	v_mfma_f32_16x16x32_bf16 v[4:7], v[124:127], v[24:27], v[28:31]
	s_waitcnt lgkmcnt(0)
	v_mfma_f32_16x16x32_bf16 v[0:3], v[128:131], v[24:27], v[16:19]
	s_and_b64 exec, exec, s[0:1]
	s_cbranch_execz .LBB0_153
	s_lshl_b32 s0, s17, 11
	v_bfe_u32 v18, v12, 16, 1
	s_add_u32 s0, s6, s0
	v_add3_u32 v12, v12, v18, s33
	v_bfe_u32 v18, v13, 16, 1
	s_addc_u32 s1, s7, 0
	v_add3_u32 v13, v13, v18, s33
	v_lshrrev_b32_e32 v12, 16, v12
	s_add_u32 s0, s0, s12
	v_and_or_b32 v12, v13, s29, v12
	s_nop 0
	s_addc_u32 s1, s1, 0
	v_lshlrev_b64 v[16:17], 11, v[68:69]
	s_nop 0
	s_nop 0
	v_lshl_add_u64 v[16:17], s[0:1], 0, v[16:17]
	v_mov_b32_e32 v71, v80
	s_nop 0
	s_nop 0
	v_lshl_add_u64 v[16:17], v[16:17], 0, v[70:71]
	v_cvt_pk_bf16_f32 v13, v14, v15
	global_store_dwordx2 v[16:17], v[12:13], off offset:1536
	v_bfe_u32 v12, v8, 16, 1
	v_add3_u32 v8, v8, v12, s33
	v_bfe_u32 v12, v9, 16, 1
	v_add3_u32 v9, v9, v12, s33
	v_lshrrev_b32_e32 v8, 16, v8
	v_and_or_b32 v8, v9, s29, v8
	s_nop 0
	s_nop 0
	s_nop 0
	s_nop 0
	s_nop 0
	v_cvt_pk_bf16_f32 v9, v10, v11
	global_store_dwordx2 v[16:17], v[8:9], off offset:1568
	v_bfe_u32 v8, v4, 16, 1
	v_add3_u32 v4, v4, v8, s33
	v_bfe_u32 v8, v5, 16, 1
	v_add3_u32 v5, v5, v8, s33
	v_lshrrev_b32_e32 v4, 16, v4
	v_and_or_b32 v4, v5, s29, v4
	s_nop 0
	s_nop 0
	s_nop 0
	s_nop 0
	s_nop 0
	v_cvt_pk_bf16_f32 v5, v6, v7
	global_store_dwordx2 v[16:17], v[4:5], off offset:1600
	v_bfe_u32 v4, v0, 16, 1
	v_add3_u32 v0, v0, v4, s33
	v_bfe_u32 v4, v1, 16, 1
	v_add3_u32 v1, v1, v4, s33
	v_lshrrev_b32_e32 v0, 16, v0
	v_and_or_b32 v0, v1, s29, v0
	s_nop 0
	s_nop 0
	s_nop 0
	s_nop 0
	s_nop 0
	v_cvt_pk_bf16_f32 v1, v2, v3
	global_store_dwordx2 v[16:17], v[0:1], off offset:1632

.LBB0_219:
	v_lshlrev_b64 v[38:39], 10, v[64:65]
	v_lshl_add_u64 v[38:39], s[6:7], 0, v[38:39]
	v_mov_b32_e32 v61, v80
	v_lshl_add_u64 v[38:39], v[38:39], 0, v[60:61]
	global_load_dwordx4 v[40:43], v[38:39], off offset:16
	global_load_dwordx4 v[44:47], v[38:39], off
	s_waitcnt vmcnt(0)
	s_nop 0
	s_nop 0
	s_nop 0
	s_nop 0
	s_nop 0
	v_cvt_pk_bf16_f32 v38, v44, v45
	s_nop 0
	s_nop 0
	s_nop 0
	s_nop 0
	s_nop 0
	v_cvt_pk_bf16_f32 v39, v46, v47
	s_nop 0
	s_nop 0
	s_nop 0
	s_nop 0
	s_nop 0
	v_cvt_pk_bf16_f32 v40, v40, v41
	v_bfe_u32 v11, v42, 16, 1
	v_add3_u32 v11, v42, v11, s33
	v_bfe_u32 v19, v43, 16, 1
	v_add3_u32 v19, v43, v19, s33
	v_lshrrev_b32_e32 v11, 16, v11
	v_and_or_b32 v42, v19, s29, v11

.LBB0_235:
	v_lshlrev_b64 v[50:51], 10, v[66:67]
	v_lshl_add_u64 v[50:51], s[6:7], 0, v[50:51]
	v_mov_b32_e32 v61, v80
	v_lshl_add_u64 v[50:51], v[50:51], 0, v[60:61]
	global_load_dwordx4 v[52:55], v[50:51], off offset:16
	global_load_dwordx4 v[68:71], v[50:51], off
	s_waitcnt vmcnt(0)
	s_nop 0
	s_nop 0
	s_nop 0
	s_nop 0
	s_nop 0
	v_cvt_pk_bf16_f32 v50, v68, v69
	s_nop 0
	s_nop 0
	s_nop 0
	s_nop 0
	s_nop 0
	v_cvt_pk_bf16_f32 v51, v70, v71
	s_nop 0
	s_nop 0
	s_nop 0
	s_nop 0
	s_nop 0
	v_cvt_pk_bf16_f32 v52, v52, v53
	v_bfe_u32 v11, v54, 16, 1
	v_add3_u32 v11, v54, v11, s33
	v_bfe_u32 v19, v55, 16, 1
	v_add3_u32 v19, v55, v19, s33
	v_lshrrev_b32_e32 v11, 16, v11
	v_and_or_b32 v54, v19, s29, v11

.LBB0_247:
	s_or_b64 exec, exec, s[2:3]
	v_and_b32_e32 v33, 64, v229
	v_xor_b32_e32 v32, 16, v229
	v_add_u32_e32 v33, 64, v33
	v_cmp_lt_i32_e32 vcc, v32, v33
	v_mul_f32_e32 v37, 0x3e000000, v37
	v_mul_f32_e32 v38, 0x3e000000, v38
	v_cndmask_b32_e32 v34, v229, v32, vcc
	v_xor_b32_e32 v32, 32, v229
	v_cmp_lt_i32_e32 vcc, v32, v33
	v_lshlrev_b32_e32 v47, 2, v34
	v_mul_f32_e32 v34, 0x3e000000, v36
	v_cndmask_b32_e32 v33, v229, v32, vcc
	v_lshlrev_b32_e32 v32, 2, v48
	v_cmp_gt_i32_e32 vcc, v32, v40
	v_lshlrev_b32_e32 v46, 2, v33
	v_sub_u32_e32 v33, v44, v49
	v_cndmask_b32_e32 v34, v230, v34, vcc
	v_cmp_ge_i32_e32 vcc, v32, v40
	v_or_b32_e32 v44, 2, v32
	s_waitcnt vmcnt(0)
	v_max_f32_e32 v36, v43, v43
	v_cndmask_b32_e32 v37, v230, v37, vcc
	v_cmp_gt_i32_e32 vcc, v44, v40
	v_or_b32_e32 v44, 3, v32
	v_mul_f32_e32 v39, 0x3e000000, v39
	v_cndmask_b32_e32 v38, v230, v38, vcc
	v_cmp_gt_i32_e32 vcc, v44, v40
	v_or_b32_e32 v49, 16, v32
	v_max_f32_e32 v36, v36, v34
	v_cndmask_b32_e32 v39, v230, v39, vcc
	v_cmp_gt_i32_e32 vcc, v49, v40
	v_mul_f32_e32 v28, 0x3e000000, v28
	v_max3_f32 v36, v36, v37, v38
	v_cndmask_b32_e32 v49, v230, v28, vcc
	v_max3_f32 v28, v36, v39, v49
	v_or_b32_e32 v36, 17, v32
	v_cmp_gt_i32_e32 vcc, v36, v40
	v_mul_f32_e32 v29, 0x3e000000, v29
	v_mul_f32_e32 v24, 0x3e000000, v24
	v_cndmask_b32_e32 v50, v230, v29, vcc
	v_or_b32_e32 v29, 18, v32
	v_cmp_gt_i32_e32 vcc, v29, v40
	v_mul_f32_e32 v29, 0x3e000000, v30
	v_mul_f32_e32 v25, 0x3e000000, v25
	v_cndmask_b32_e32 v51, v230, v29, vcc
	v_or_b32_e32 v29, 19, v32
	v_cmp_gt_i32_e32 vcc, v29, v40
	v_mul_f32_e32 v29, 0x3e000000, v31
	v_mul_f32_e32 v26, 0x3e000000, v26
	v_cndmask_b32_e32 v52, v230, v29, vcc
	v_or_b32_e32 v29, 32, v32
	v_cmp_gt_i32_e32 vcc, v29, v40
	v_or_b32_e32 v29, 33, v32
	v_mul_f32_e32 v27, 0x3e000000, v27
	v_cndmask_b32_e32 v24, v230, v24, vcc
	v_cmp_gt_i32_e32 vcc, v29, v40
	v_or_b32_e32 v29, 34, v32
	v_mul_f32_e32 v20, 0x3e000000, v20
	v_cndmask_b32_e32 v25, v230, v25, vcc
	v_cmp_gt_i32_e32 vcc, v29, v40
	v_or_b32_e32 v29, 35, v32
	v_max3_f32 v28, v28, v50, v51
	v_cndmask_b32_e32 v26, v230, v26, vcc
	v_cmp_gt_i32_e32 vcc, v29, v40
	v_or_b32_e32 v29, 48, v32
	v_mul_f32_e32 v21, 0x3e000000, v21
	v_cndmask_b32_e32 v27, v230, v27, vcc
	v_cmp_gt_i32_e32 vcc, v29, v40
	v_or_b32_e32 v29, 49, v32
	v_max3_f32 v28, v28, v52, v24
	v_cndmask_b32_e32 v20, v230, v20, vcc
	v_cmp_gt_i32_e32 vcc, v29, v40
	v_or_b32_e32 v29, 50, v32
	v_mul_f32_e32 v22, 0x3e000000, v22
	v_cndmask_b32_e32 v21, v230, v21, vcc
	v_cmp_gt_i32_e32 vcc, v29, v40
	v_or_b32_e32 v29, 51, v32
	v_max3_f32 v28, v28, v25, v26
	v_cndmask_b32_e32 v22, v230, v22, vcc
	v_cmp_gt_i32_e32 vcc, v29, v40
	v_mul_f32_e32 v23, 0x3e000000, v23
	v_or_b32_e32 v29, 64, v32
	v_max3_f32 v28, v28, v27, v20
	v_cndmask_b32_e32 v23, v230, v23, vcc
	v_cmp_gt_i32_e32 vcc, v29, v40
	v_mul_f32_e32 v16, 0x3e000000, v16
	v_max3_f32 v28, v28, v21, v22
	v_cndmask_b32_e32 v53, v230, v16, vcc
	v_max3_f32 v16, v28, v23, v53
	v_or_b32_e32 v28, 0x41, v32
	v_cmp_gt_i32_e32 vcc, v28, v40
	v_mul_f32_e32 v17, 0x3e000000, v17
	v_mul_f32_e32 v12, 0x3e000000, v12
	v_cndmask_b32_e32 v54, v230, v17, vcc
	v_or_b32_e32 v17, 0x42, v32
	v_cmp_gt_i32_e32 vcc, v17, v40
	v_mul_f32_e32 v17, 0x3e000000, v18
	v_mul_f32_e32 v13, 0x3e000000, v13
	v_cndmask_b32_e32 v18, v230, v17, vcc
	v_or_b32_e32 v17, 0x43, v32
	v_cmp_gt_i32_e32 vcc, v17, v40
	v_mul_f32_e32 v17, 0x3e000000, v19
	v_max3_f32 v16, v16, v54, v18
	v_cndmask_b32_e32 v19, v230, v17, vcc
	v_or_b32_e32 v17, 0x50, v32
	v_cmp_gt_i32_e32 vcc, v17, v40
	v_mul_f32_e32 v8, 0x3e000000, v8
	v_mul_f32_e32 v9, 0x3e000000, v9
	v_cndmask_b32_e32 v55, v230, v12, vcc
	v_max3_f32 v12, v16, v19, v55
	v_or_b32_e32 v16, 0x51, v32
	v_cmp_gt_i32_e32 vcc, v16, v40
	v_mul_f32_e32 v4, 0x3e000000, v4
	v_mul_f32_e32 v5, 0x3e000000, v5
	v_cndmask_b32_e32 v56, v230, v13, vcc
	v_or_b32_e32 v13, 0x52, v32
	v_cmp_gt_i32_e32 vcc, v13, v40
	v_mul_f32_e32 v13, 0x3e000000, v14
	s_movk_i32 s2, 0x84
	v_cndmask_b32_e32 v14, v230, v13, vcc
	v_or_b32_e32 v13, 0x53, v32
	v_cmp_gt_i32_e32 vcc, v13, v40
	v_mul_f32_e32 v13, 0x3e000000, v15
	v_max3_f32 v12, v12, v56, v14
	v_cndmask_b32_e32 v15, v230, v13, vcc
	v_or_b32_e32 v13, 0x60, v32
	v_cmp_gt_i32_e32 vcc, v13, v40
	v_cmp_le_i32_e64 s[4:5], v32, v40
	v_add_u32_e32 v35, 0x80, v40
	v_cndmask_b32_e32 v57, v230, v8, vcc
	v_max3_f32 v8, v12, v15, v57
	v_or_b32_e32 v12, 0x61, v32
	v_cmp_gt_i32_e32 vcc, v12, v40
	v_mul_f32_e32 v0, 0x3e000000, v0
	v_mul_f32_e32 v1, 0x3e000000, v1
	v_cndmask_b32_e32 v58, v230, v9, vcc
	v_or_b32_e32 v9, 0x62, v32
	v_cmp_gt_i32_e32 vcc, v9, v40
	v_mul_f32_e32 v9, 0x3e000000, v10
	v_mul_f32_e32 v2, 0x3e000000, v2
	v_cndmask_b32_e32 v59, v230, v9, vcc
	v_or_b32_e32 v9, 0x63, v32
	v_cmp_gt_i32_e32 vcc, v9, v40
	v_mul_f32_e32 v9, 0x3e000000, v11
	v_max3_f32 v8, v8, v58, v59
	v_cndmask_b32_e32 v60, v230, v9, vcc
	v_or_b32_e32 v9, 0x70, v32
	v_cmp_gt_i32_e32 vcc, v9, v40
	v_mul_f32_e32 v3, 0x3e000000, v3
	s_nop 0
	v_cndmask_b32_e32 v61, v230, v4, vcc
	v_max3_f32 v4, v8, v60, v61
	v_or_b32_e32 v8, 0x71, v32
	v_cmp_gt_i32_e32 vcc, v8, v40
	s_nop 1
	v_cndmask_b32_e32 v62, v230, v5, vcc
	v_or_b32_e32 v5, 0x72, v32
	v_cmp_gt_i32_e32 vcc, v5, v40
	v_mul_f32_e32 v5, 0x3e000000, v6
	s_nop 0
	v_cndmask_b32_e32 v63, v230, v5, vcc
	v_or_b32_e32 v5, 0x73, v32
	v_cmp_gt_i32_e32 vcc, v5, v40
	v_mul_f32_e32 v5, 0x3e000000, v7
	v_max3_f32 v4, v4, v62, v63
	v_cndmask_b32_e32 v64, v230, v5, vcc
	v_or_b32_e32 v5, 0x80, v32
	v_cmp_gt_u32_e32 vcc, s2, v5
	s_and_b64 vcc, vcc, s[4:5]
	v_or_b32_e32 v5, 0x81, v32
	v_cndmask_b32_e32 v0, v230, v0, vcc
	v_cmp_gt_u32_e32 vcc, s2, v5
	v_cmp_le_i32_e64 s[4:5], v5, v35
	s_and_b64 vcc, vcc, s[4:5]
	v_or_b32_e32 v5, 0x82, v32
	v_cndmask_b32_e32 v1, v230, v1, vcc
	v_cmp_gt_u32_e32 vcc, s2, v5
	v_cmp_le_i32_e64 s[4:5], v5, v35
	s_and_b64 vcc, vcc, s[4:5]
	v_cndmask_b32_e32 v65, v230, v2, vcc
	v_cmp_eq_u32_e32 vcc, 0, v48
	v_cmp_le_i32_e64 s[4:5], v44, v40
	v_max3_f32 v4, v4, v64, v0
	s_and_b64 vcc, vcc, s[4:5]
	v_max3_f32 v2, v4, v1, v65
	v_cndmask_b32_e32 v3, v230, v3, vcc
	s_mov_b32 s2, 0xf149f2ca
	v_max3_f32 v2, v2, v3, s2
	ds_bpermute_b32 v4, v47, v2
	s_waitcnt lgkmcnt(0)
	v_max_f32_e32 v4, v4, v4
	v_max_f32_e32 v2, v2, v4
	ds_bpermute_b32 v4, v46, v2
	s_waitcnt lgkmcnt(0)
	v_max_f32_e32 v4, v4, v4
	v_max_f32_e32 v44, v2, v4
	v_sub_f32_e32 v4, v37, v44
	v_mul_f32_e32 v4, 0x3fb8aa3b, v4
	v_exp_f32_e32 v30, v4
	v_sub_f32_e32 v4, v38, v44
	v_mul_f32_e32 v4, 0x3fb8aa3b, v4
	v_exp_f32_e32 v29, v4
	v_sub_f32_e32 v4, v39, v44
	v_mul_f32_e32 v4, 0x3fb8aa3b, v4
	v_exp_f32_e32 v31, v4
	v_sub_f32_e32 v4, v49, v44
	v_mul_f32_e32 v4, 0x3fb8aa3b, v4
	v_exp_f32_e32 v36, v4
	v_sub_f32_e32 v4, v50, v44
	v_mul_f32_e32 v4, 0x3fb8aa3b, v4
	v_exp_f32_e32 v38, v4
	v_sub_f32_e32 v4, v51, v44
	v_mul_f32_e32 v4, 0x3fb8aa3b, v4
	v_exp_f32_e32 v37, v4
	v_sub_f32_e32 v4, v52, v44
	v_mul_f32_e32 v4, 0x3fb8aa3b, v4
	v_exp_f32_e32 v39, v4
	v_sub_f32_e32 v4, v24, v44
	v_mul_f32_e32 v4, 0x3fb8aa3b, v4
	v_exp_f32_e32 v12, v4
	v_sub_f32_e32 v4, v25, v44
	v_mul_f32_e32 v4, 0x3fb8aa3b, v4
	v_exp_f32_e32 v16, v4
	v_sub_f32_e32 v4, v26, v44
	v_mul_f32_e32 v4, 0x3fb8aa3b, v4
	v_exp_f32_e32 v13, v4
	v_sub_f32_e32 v4, v27, v44
	v_mul_f32_e32 v4, 0x3fb8aa3b, v4
	v_sub_f32_e32 v2, v34, v44
	v_exp_f32_e32 v17, v4
	v_sub_f32_e32 v4, v20, v44
	v_mul_f32_e32 v2, 0x3fb8aa3b, v2
	v_mul_f32_e32 v4, 0x3fb8aa3b, v4
	v_exp_f32_e32 v28, v2
	v_exp_f32_e32 v26, v4
	v_sub_f32_e32 v4, v21, v44
	v_mul_f32_e32 v4, 0x3fb8aa3b, v4
	v_exp_f32_e32 v34, v4
	v_sub_f32_e32 v4, v22, v44
	v_mul_f32_e32 v4, 0x3fb8aa3b, v4
	v_add_f32_e32 v2, 0, v28
	v_exp_f32_e32 v27, v4
	v_sub_f32_e32 v4, v23, v44
	v_add_f32_e32 v2, v30, v2
	v_mul_f32_e32 v4, 0x3fb8aa3b, v4
	v_add_f32_e32 v2, v29, v2
	v_exp_f32_e32 v35, v4
	v_sub_f32_e32 v4, v53, v44
	v_add_f32_e32 v2, v31, v2
	v_mul_f32_e32 v4, 0x3fb8aa3b, v4
	v_add_f32_e32 v2, v36, v2
	v_exp_f32_e32 v8, v4
	v_sub_f32_e32 v4, v54, v44
	v_add_f32_e32 v2, v38, v2
	v_mul_f32_e32 v4, 0x3fb8aa3b, v4
	v_add_f32_e32 v2, v37, v2
	v_exp_f32_e32 v10, v4
	v_sub_f32_e32 v4, v18, v44
	v_add_f32_e32 v2, v39, v2
	v_mul_f32_e32 v4, 0x3fb8aa3b, v4
	v_add_f32_e32 v2, v12, v2
	v_exp_f32_e32 v9, v4
	v_sub_f32_e32 v4, v19, v44
	v_add_f32_e32 v2, v16, v2
	v_mul_f32_e32 v4, 0x3fb8aa3b, v4
	v_add_f32_e32 v2, v13, v2
	v_exp_f32_e32 v11, v4
	v_sub_f32_e32 v4, v55, v44
	v_add_f32_e32 v2, v17, v2
	v_mul_f32_e32 v4, 0x3fb8aa3b, v4
	v_add_f32_e32 v2, v26, v2
	v_exp_f32_e32 v22, v4
	v_sub_f32_e32 v4, v56, v44
	v_add_f32_e32 v2, v34, v2
	v_mul_f32_e32 v4, 0x3fb8aa3b, v4
	v_add_f32_e32 v2, v27, v2
	v_exp_f32_e32 v24, v4
	v_sub_f32_e32 v4, v14, v44
	v_add_f32_e32 v2, v35, v2
	v_mul_f32_e32 v4, 0x3fb8aa3b, v4
	v_add_f32_e32 v2, v8, v2
	v_exp_f32_e32 v23, v4
	v_sub_f32_e32 v4, v15, v44
	v_add_f32_e32 v2, v10, v2
	v_mul_f32_e32 v4, 0x3fb8aa3b, v4
	v_add_f32_e32 v2, v9, v2
	v_exp_f32_e32 v25, v4
	v_sub_f32_e32 v4, v57, v44
	v_sub_f32_e32 v5, v58, v44
	v_add_f32_e32 v2, v11, v2
	v_mul_f32_e32 v4, 0x3fb8aa3b, v4
	v_mul_f32_e32 v5, 0x3fb8aa3b, v5
	v_add_f32_e32 v2, v22, v2
	v_exp_f32_e32 v4, v4
	v_exp_f32_e32 v6, v5
	v_sub_f32_e32 v5, v59, v44
	v_add_f32_e32 v2, v24, v2
	v_mul_f32_e32 v5, 0x3fb8aa3b, v5
	v_sub_f32_e32 v7, v60, v44
	v_add_f32_e32 v2, v23, v2
	v_exp_f32_e32 v5, v5
	v_mul_f32_e32 v7, 0x3fb8aa3b, v7
	v_sub_f32_e32 v14, v61, v44
	v_sub_f32_e32 v15, v62, v44
	v_add_f32_e32 v2, v25, v2
	v_exp_f32_e32 v7, v7
	v_mul_f32_e32 v14, 0x3fb8aa3b, v14
	v_mul_f32_e32 v15, 0x3fb8aa3b, v15
	v_add_f32_e32 v2, v4, v2
	v_exp_f32_e32 v14, v14
	v_exp_f32_e32 v18, v15
	v_sub_f32_e32 v15, v63, v44
	v_add_f32_e32 v2, v6, v2
	v_mul_f32_e32 v15, 0x3fb8aa3b, v15
	v_sub_f32_e32 v19, v64, v44
	v_add_f32_e32 v2, v5, v2
	v_exp_f32_e32 v15, v15
	v_mul_f32_e32 v19, 0x3fb8aa3b, v19
	v_sub_f32_e32 v0, v0, v44
	v_add_f32_e32 v2, v7, v2
	v_exp_f32_e32 v19, v19
	v_mul_f32_e32 v0, 0x3fb8aa3b, v0
	v_add_f32_e32 v2, v14, v2
	v_exp_f32_e32 v0, v0
	v_add_f32_e32 v2, v18, v2
	v_add_f32_e32 v2, v15, v2
	v_sub_f32_e32 v1, v1, v44
	v_add_f32_e32 v2, v19, v2
	v_mul_f32_e32 v1, 0x3fb8aa3b, v1
	v_add_f32_e32 v20, v0, v2
	v_exp_f32_e32 v2, v1
	v_sub_f32_e32 v1, v65, v44
	v_mul_f32_e32 v1, 0x3fb8aa3b, v1
	v_sub_f32_e32 v3, v3, v44
	v_exp_f32_e32 v1, v1
	v_mul_f32_e32 v3, 0x3fb8aa3b, v3
	v_sub_f32_e32 v21, 0xf149f2ca, v44
	v_exp_f32_e32 v3, v3
	v_mul_f32_e32 v21, 0x3fb8aa3b, v21
	v_exp_f32_e32 v21, v21
	v_add_f32_e32 v20, v2, v20
	v_add_f32_e32 v20, v1, v20
	v_add_f32_e32 v20, v3, v20
	v_add_f32_e32 v20, v21, v20
	v_add_f32_e32 v20, v21, v20
	v_add_f32_e32 v20, v21, v20
	v_add_f32_e32 v20, v21, v20
	ds_bpermute_b32 v47, v47, v20
	v_sub_f32_e32 v43, v43, v44
	v_mul_f32_e32 v43, 0x3fb8aa3b, v43
	v_exp_f32_e32 v43, v43
	s_waitcnt lgkmcnt(0)
	v_add_f32_e32 v20, v20, v47
	ds_bpermute_b32 v46, v46, v20
	s_waitcnt lgkmcnt(0)
	v_add_f32_e32 v20, v20, v46
	v_add_f32_e32 v20, v43, v20
	v_div_scale_f32 v43, s[2:3], v20, v20, 1.0
	v_rcp_f32_e32 v44, v43
	v_div_scale_f32 v46, vcc, 1.0, v20, 1.0
	s_movk_i32 s2, 0x210
	v_fma_f32 v47, -v43, v44, 1.0
	v_fmac_f32_e32 v44, v47, v44
	v_mul_f32_e32 v47, v46, v44
	v_fma_f32 v48, -v43, v47, v46
	v_fmac_f32_e32 v47, v48, v44
	v_fma_f32 v43, -v43, v47, v46
	v_div_fmas_f32 v43, v43, v44, v47
	v_div_fixup_f32 v20, v43, v20, 1.0
	v_pk_mul_f32 v[30:31], v[30:31], v[20:21] op_sel_hi:[1,0]
	v_pk_mul_f32 v[38:39], v[38:39], v[20:21] op_sel_hi:[1,0]
	v_pk_mul_f32 v[28:29], v[28:29], v[20:21] op_sel_hi:[1,0]
	v_pk_mul_f32 v[36:37], v[36:37], v[20:21] op_sel_hi:[1,0]
	v_bfe_u32 v43, v39, 16, 1
	v_bfe_u32 v44, v38, 16, 1
	s_nop 0
	v_bfe_u32 v47, v30, 16, 1
	s_nop 0
	v_add3_u32 v38, v38, v44, s33
	v_add3_u32 v39, v39, v43, s33
	s_nop 0
	v_bfe_u32 v43, v36, 16, 1
	v_bfe_u32 v44, v37, 16, 1
	v_add3_u32 v47, v30, v47, s33
	v_bfe_u32 v30, v28, 16, 1
	v_add3_u32 v37, v37, v44, s33
	v_add3_u32 v36, v36, v43, s33
	s_nop 0
	v_add3_u32 v44, v28, v30, s33
	v_mad_u32_u24 v33, v45, s2, v33
	s_nop 0
	v_lshrrev_b32_e32 v37, 16, v37
	v_add_u32_e32 v60, 0x9000, v33
	v_lshrrev_b32_e32 v44, 16, v44
	v_lshrrev_b32_e32 v36, 16, v36
	v_and_or_b32 v39, v39, s29, v37
	v_cvt_pk_bf16_f32 v37, v29, v31
	v_add_u32_e32 v43, 0xb000, v33
	v_add_u32_e32 v61, 0xd000, v33
	v_add_u32_e32 v33, 0xf000, v33
	ds_read2_b64 v[28:31], v60 offset1:4
	v_and_or_b32 v38, v38, s29, v36
	v_and_or_b32 v36, v47, s29, v44
	ds_read2_b64 v[44:47], v43 offset0:32 offset1:36
	ds_read2_b64 v[48:51], v61 offset0:64 offset1:68
	ds_read2_b64 v[52:55], v33 offset0:96 offset1:100
	s_waitcnt lgkmcnt(3)
	v_mfma_f32_16x16x32_bf16 v[28:31], v[28:31], v[36:39], 0
	s_waitcnt lgkmcnt(2)
	v_mfma_f32_16x16x32_bf16 v[44:47], v[44:47], v[36:39], 0
	s_waitcnt lgkmcnt(1)
	v_mfma_f32_16x16x32_bf16 v[48:51], v[48:51], v[36:39], 0
	s_waitcnt lgkmcnt(0)
	v_mfma_f32_16x16x32_bf16 v[36:39], v[52:55], v[36:39], 0
	ds_read2_b64 v[132:135], v60 offset0:8 offset1:12
	ds_read2_b64 v[136:139], v43 offset0:40 offset1:44
	ds_read2_b64 v[140:143], v61 offset0:72 offset1:76
	ds_read2_b64 v[144:147], v33 offset0:104 offset1:108
	v_mul_f32_e64 v16, v16, v20
	v_mul_f32_e64 v17, v17, v20
	v_pk_mul_f32 v[34:35], v[34:35], v[20:21] op_sel_hi:[1,0]
	v_pk_mul_f32 v[12:13], v[12:13], v[20:21] op_sel_hi:[1,0]
	v_pk_mul_f32 v[26:27], v[26:27], v[20:21] op_sel_hi:[1,0]
	v_bfe_u32 v52, v35, 16, 1
	v_bfe_u32 v53, v34, 16, 1
	v_bfe_u32 v54, v17, 16, 1
	v_bfe_u32 v55, v16, 16, 1
	v_add3_u32 v16, v16, v55, s33
	v_add3_u32 v17, v17, v54, s33
	v_add3_u32 v34, v34, v53, s33
	v_add3_u32 v35, v35, v52, s33
	v_bfe_u32 v52, v12, 16, 1
	v_bfe_u32 v53, v13, 16, 1
	v_bfe_u32 v54, v26, 16, 1
	v_bfe_u32 v55, v27, 16, 1
	v_add3_u32 v27, v27, v55, s33
	v_add3_u32 v26, v26, v54, s33
	v_add3_u32 v13, v13, v53, s33
	v_add3_u32 v12, v12, v52, s33
	v_lshrrev_b32_e32 v12, 16, v12
	v_lshrrev_b32_e32 v13, 16, v13
	v_lshrrev_b32_e32 v26, 16, v26
	v_lshrrev_b32_e32 v27, 16, v27
	v_and_or_b32 v59, v35, s29, v27
	v_and_or_b32 v58, v34, s29, v26
	v_and_or_b32 v57, v17, s29, v13
	v_and_or_b32 v56, v16, s29, v12
	s_waitcnt lgkmcnt(3)
	s_nop 1
	v_mfma_f32_16x16x32_bf16 v[26:29], v[132:135], v[56:59], v[28:31]
	s_waitcnt lgkmcnt(2)
	v_mfma_f32_16x16x32_bf16 v[44:47], v[136:139], v[56:59], v[44:47]
	s_waitcnt lgkmcnt(1)
	v_mfma_f32_16x16x32_bf16 v[48:51], v[140:143], v[56:59], v[48:51]
	s_waitcnt lgkmcnt(0)
	v_mfma_f32_16x16x32_bf16 v[34:37], v[144:147], v[56:59], v[36:39]
	ds_read2_b64 v[116:119], v60 offset0:16 offset1:20
	ds_read2_b64 v[120:123], v43 offset0:48 offset1:52
	ds_read2_b64 v[124:127], v61 offset0:80 offset1:84
	ds_read2_b64 v[128:131], v33 offset0:112 offset1:116
	v_mul_f32_e64 v10, v10, v20
	v_mul_f32_e64 v11, v11, v20
	v_pk_mul_f32 v[16:17], v[24:25], v[20:21] op_sel_hi:[1,0]
	v_pk_mul_f32 v[8:9], v[8:9], v[20:21] op_sel_hi:[1,0]
	v_pk_mul_f32 v[12:13], v[22:23], v[20:21] op_sel_hi:[1,0]
	v_bfe_u32 v22, v17, 16, 1
	v_bfe_u32 v23, v16, 16, 1
	v_bfe_u32 v24, v11, 16, 1
	v_bfe_u32 v25, v10, 16, 1
	v_add3_u32 v30, v10, v25, s33
	v_add3_u32 v31, v11, v24, s33
	v_add3_u32 v16, v16, v23, s33
	v_add3_u32 v17, v17, v22, s33
	v_bfe_u32 v10, v8, 16, 1
	v_bfe_u32 v11, v9, 16, 1
	v_bfe_u32 v22, v12, 16, 1
	v_bfe_u32 v23, v13, 16, 1
	v_add3_u32 v13, v13, v23, s33
	v_add3_u32 v12, v12, v22, s33
	v_add3_u32 v22, v9, v11, s33
	v_add3_u32 v23, v8, v10, s33
	v_lshrrev_b32_e32 v38, 16, v23
	v_lshrrev_b32_e32 v22, 16, v22
	v_lshrrev_b32_e32 v12, 16, v12
	v_lshrrev_b32_e32 v13, 16, v13
	v_and_or_b32 v25, v17, s29, v13
	v_and_or_b32 v24, v16, s29, v12
	v_and_or_b32 v23, v31, s29, v22
	v_and_or_b32 v22, v30, s29, v38
	s_waitcnt lgkmcnt(3)
	s_nop 1
	v_mfma_f32_16x16x32_bf16 v[8:11], v[116:119], v[22:25], v[26:29]
	s_waitcnt lgkmcnt(2)
	v_mfma_f32_16x16x32_bf16 v[26:29], v[120:123], v[22:25], v[44:47]
	s_waitcnt lgkmcnt(1)
	v_mfma_f32_16x16x32_bf16 v[44:47], v[124:127], v[22:25], v[48:51]
	s_waitcnt lgkmcnt(0)
	v_mfma_f32_16x16x32_bf16 v[22:25], v[128:131], v[22:25], v[34:37]
	ds_read2_b64 v[132:135], v60 offset0:24 offset1:28
	ds_read2_b64 v[136:139], v43 offset0:56 offset1:60
	ds_read2_b64 v[140:143], v61 offset0:88 offset1:92
	ds_read2_b64 v[144:147], v33 offset0:120 offset1:124
	v_mul_f32_e64 v6, v6, v20
	v_mul_f32_e64 v7, v7, v20
	v_pk_mul_f32 v[12:13], v[14:15], v[20:21] op_sel_hi:[1,0]
	v_pk_mul_f32 v[14:15], v[18:19], v[20:21] op_sel_hi:[1,0]
	v_pk_mul_f32 v[4:5], v[4:5], v[20:21] op_sel_hi:[1,0]
	v_bfe_u32 v16, v15, 16, 1
	v_bfe_u32 v17, v14, 16, 1
	s_nop 0
	s_nop 0
	s_nop 0
	s_nop 0
	v_add3_u32 v14, v14, v17, s33
	v_add3_u32 v15, v15, v16, s33
	s_nop 0
	s_nop 0
	v_bfe_u32 v16, v12, 16, 1
	v_bfe_u32 v17, v13, 16, 1
	v_add3_u32 v13, v13, v17, s33
	v_add3_u32 v12, v12, v16, s33
	s_nop 0
	s_nop 0
	s_nop 0
	s_nop 0
	v_lshrrev_b32_e32 v12, 16, v12
	v_lshrrev_b32_e32 v13, 16, v13
	v_and_or_b32 v15, v15, s29, v13
	v_and_or_b32 v14, v14, s29, v12
	v_cvt_pk_bf16_f32 v13, v5, v7
	v_cvt_pk_bf16_f32 v12, v4, v6
	s_waitcnt lgkmcnt(3)
	s_nop 1
	v_mfma_f32_16x16x32_bf16 v[4:7], v[132:135], v[12:15], v[8:11]
	s_waitcnt lgkmcnt(2)
	v_mfma_f32_16x16x32_bf16 v[8:11], v[136:139], v[12:15], v[26:29]
	s_waitcnt lgkmcnt(1)
	v_mfma_f32_16x16x32_bf16 v[16:19], v[140:143], v[12:15], v[44:47]
	s_waitcnt lgkmcnt(0)
	v_mfma_f32_16x16x32_bf16 v[22:25], v[144:147], v[12:15], v[22:25]
	ds_read2_b64 v[116:119], v60 offset0:32 offset1:36
	ds_read2_b64 v[120:123], v43 offset0:64 offset1:68
	ds_read2_b64 v[124:127], v61 offset0:96 offset1:100
	ds_read2_b64 v[128:131], v33 offset0:128 offset1:132
	v_mul_f32_e64 v0, v0, v20
	v_mul_f32_e64 v1, v1, v20
	v_pk_mul_f32 v[2:3], v[2:3], v[20:21] op_sel_hi:[1,0]
	v_and_b32_sdwa v12, v1, v228 dst_sel:DWORD dst_unused:UNUSED_PAD src0_sel:WORD_1 src1_sel:DWORD
	v_and_b32_sdwa v13, v0, v228 dst_sel:DWORD dst_unused:UNUSED_PAD src0_sel:WORD_1 src1_sel:DWORD
	v_add3_u32 v13, v0, v13, s33
	v_add3_u32 v12, v1, v12, s33
	v_and_b32_sdwa v0, v3, v228 dst_sel:DWORD dst_unused:UNUSED_PAD src0_sel:WORD_1 src1_sel:DWORD
	v_and_b32_sdwa v1, v2, v228 dst_sel:DWORD dst_unused:UNUSED_PAD src0_sel:WORD_1 src1_sel:DWORD
	v_add3_u32 v0, v3, v0, s33
	v_add3_u32 v1, v2, v1, s33
	v_and_b32_e32 v14, 0xffff0000, v0
	v_and_b32_e32 v15, 0xffff0000, v1
	v_or_b32_sdwa v27, v14, v12 dst_sel:DWORD dst_unused:UNUSED_PAD src0_sel:DWORD src1_sel:WORD_1
	v_mul_f32_e32 v12, v21, v20
	v_or_b32_sdwa v26, v15, v13 dst_sel:DWORD dst_unused:UNUSED_PAD src0_sel:DWORD src1_sel:WORD_1
	s_nop 0
	s_nop 0
	s_nop 0
	v_cvt_pk_bf16_f32 v28, v12, v12
	v_mov_b32_e32 v29, v28
	s_waitcnt lgkmcnt(3)
	s_nop 1
	v_mfma_f32_16x16x32_bf16 v[12:15], v[116:119], v[26:29], v[4:7]
	s_waitcnt lgkmcnt(2)
	v_mfma_f32_16x16x32_bf16 v[8:11], v[120:123], v[26:29], v[8:11]
	s_waitcnt lgkmcnt(1)
	v_mfma_f32_16x16x32_bf16 v[4:7], v[124:127], v[26:29], v[16:19]
	s_waitcnt lgkmcnt(0)
	v_mfma_f32_16x16x32_bf16 v[0:3], v[128:131], v[26:29], v[22:25]
	s_and_b64 exec, exec, s[0:1]
	s_cbranch_execz .LBB0_249
	s_lshl_b32 s0, s17, 11
	s_add_u32 s0, s10, s0
	v_lshlrev_b64 v[16:17], 11, v[40:41]
	s_addc_u32 s1, s11, 0
	v_add_lshl_u32 v18, v42, s18, 6
	v_lshl_add_u64 v[16:17], s[0:1], 0, v[16:17]
	v_ashrrev_i32_e32 v19, 31, v18
	v_lshl_add_u64 v[16:17], v[18:19], 1, v[16:17]
	v_bfe_u32 v18, v12, 16, 1
	v_add3_u32 v12, v12, v18, s33
	v_bfe_u32 v18, v13, 16, 1
	v_add3_u32 v13, v13, v18, s33
	v_lshrrev_b32_e32 v12, 16, v12
	v_and_or_b32 v12, v13, s29, v12
	s_nop 0
	s_nop 0
	s_nop 0
	v_mov_b32_e32 v33, v80
	s_nop 0
	s_nop 0
	v_lshl_add_u64 v[16:17], v[32:33], 1, v[16:17]
	v_cvt_pk_bf16_f32 v13, v14, v15
	global_store_dwordx2 v[16:17], v[12:13], off
	v_bfe_u32 v12, v8, 16, 1
	v_add3_u32 v8, v8, v12, s33
	v_bfe_u32 v12, v9, 16, 1
	v_add3_u32 v9, v9, v12, s33
	v_lshrrev_b32_e32 v8, 16, v8
	v_and_or_b32 v8, v9, s29, v8
	s_nop 0
	s_nop 0
	s_nop 0
	s_nop 0
	s_nop 0
	v_cvt_pk_bf16_f32 v9, v10, v11
	global_store_dwordx2 v[16:17], v[8:9], off offset:32
	v_bfe_u32 v8, v4, 16, 1
	v_add3_u32 v4, v4, v8, s33
	v_bfe_u32 v8, v5, 16, 1
	v_add3_u32 v5, v5, v8, s33
	v_lshrrev_b32_e32 v4, 16, v4
	v_and_or_b32 v4, v5, s29, v4
	s_nop 0
	s_nop 0
	s_nop 0
	s_nop 0
	s_nop 0
	v_cvt_pk_bf16_f32 v5, v6, v7
	global_store_dwordx2 v[16:17], v[4:5], off offset:64
	v_bfe_u32 v4, v0, 16, 1
	v_add3_u32 v0, v0, v4, s33
	v_bfe_u32 v4, v1, 16, 1
	v_add3_u32 v1, v1, v4, s33
	v_lshrrev_b32_e32 v0, 16, v0
	v_and_or_b32 v0, v1, s29, v0
	s_nop 0
	s_nop 0
	s_nop 0
	s_nop 0
	s_nop 0
	v_cvt_pk_bf16_f32 v1, v2, v3
	global_store_dwordx2 v[16:17], v[0:1], off offset:96

.LBB0_256:
	ds_read_b128 v[116:119], v82
	ds_read_b128 v[120:123], v82 offset:64
	ds_read_b128 v[124:127], v82 offset:2304
	ds_read_b128 v[128:131], v82 offset:2368
	ds_read_b128 v[132:135], v82 offset:4608
	ds_read_b128 v[136:139], v82 offset:4672
	ds_read_b128 v[140:143], v82 offset:6912
	ds_read_b128 v[144:147], v82 offset:6976
	ds_read_b128 v[148:151], v82 offset:9216
	ds_read_b128 v[152:155], v82 offset:9280
	ds_read_b128 v[156:159], v82 offset:11520
	ds_read_b128 v[160:163], v82 offset:11584
	s_waitcnt lgkmcnt(6)
	v_mfma_f32_16x16x32_bf16 v[68:71], v[116:119], v[72:75], 0
	v_mfma_f32_16x16x32_bf16 v[64:67], v[124:127], v[72:75], 0
	v_mfma_f32_16x16x32_bf16 v[60:63], v[132:135], v[72:75], 0
	v_mfma_f32_16x16x32_bf16 v[68:71], v[120:123], v[8:11], v[68:71]
	v_mfma_f32_16x16x32_bf16 v[64:67], v[128:131], v[8:11], v[64:67]
	v_mfma_f32_16x16x32_bf16 v[60:63], v[136:139], v[8:11], v[60:63]
	ds_read_b128 v[116:119], v82 offset:13824
	ds_read_b128 v[120:123], v82 offset:13888
	ds_read_b128 v[124:127], v82 offset:16128
	ds_read_b128 v[128:131], v82 offset:16192
	ds_read_b128 v[132:135], v82 offset:18432
	ds_read_b128 v[136:139], v82 offset:18496
	s_waitcnt lgkmcnt(6)
	v_mfma_f32_16x16x32_bf16 v[56:59], v[140:143], v[72:75], 0
	v_mfma_f32_16x16x32_bf16 v[52:55], v[148:151], v[72:75], 0
	v_mfma_f32_16x16x32_bf16 v[48:51], v[156:159], v[72:75], 0
	v_mfma_f32_16x16x32_bf16 v[56:59], v[144:147], v[8:11], v[56:59]
	v_mfma_f32_16x16x32_bf16 v[52:55], v[152:155], v[8:11], v[52:55]
	v_mfma_f32_16x16x32_bf16 v[48:51], v[160:163], v[8:11], v[48:51]
	ds_read_b128 v[140:143], v82 offset:20736
	ds_read_b128 v[144:147], v82 offset:20800
	ds_read_b128 v[148:151], v82 offset:23040
	ds_read_b128 v[152:155], v82 offset:23104
	ds_read_b128 v[156:159], v82 offset:25344
	ds_read_b128 v[160:163], v82 offset:25408
	s_waitcnt lgkmcnt(6)
	v_mfma_f32_16x16x32_bf16 v[44:47], v[116:119], v[72:75], 0
	v_mfma_f32_16x16x32_bf16 v[40:43], v[124:127], v[72:75], 0
	v_mfma_f32_16x16x32_bf16 v[36:39], v[132:135], v[72:75], 0
	v_mfma_f32_16x16x32_bf16 v[44:47], v[120:123], v[8:11], v[44:47]
	v_mfma_f32_16x16x32_bf16 v[40:43], v[128:131], v[8:11], v[40:43]
	v_mfma_f32_16x16x32_bf16 v[36:39], v[136:139], v[8:11], v[36:39]
	ds_read_b128 v[116:119], v82 offset:27648
	ds_read_b128 v[120:123], v82 offset:27712
	ds_read_b128 v[124:127], v82 offset:29952
	ds_read_b128 v[128:131], v82 offset:30016
	ds_read_b128 v[132:135], v82 offset:32256
	ds_read_b128 v[136:139], v82 offset:32320
	s_waitcnt lgkmcnt(6)
	v_mfma_f32_16x16x32_bf16 v[32:35], v[140:143], v[72:75], 0
	v_mfma_f32_16x16x32_bf16 v[28:31], v[148:151], v[72:75], 0
	v_mfma_f32_16x16x32_bf16 v[24:27], v[156:159], v[72:75], 0
	v_mfma_f32_16x16x32_bf16 v[32:35], v[144:147], v[8:11], v[32:35]
	v_mfma_f32_16x16x32_bf16 v[28:31], v[152:155], v[8:11], v[28:31]
	v_mfma_f32_16x16x32_bf16 v[24:27], v[160:163], v[8:11], v[24:27]
	s_waitcnt lgkmcnt(0)
	v_mfma_f32_16x16x32_bf16 v[20:23], v[116:119], v[72:75], 0
	v_mfma_f32_16x16x32_bf16 v[16:19], v[124:127], v[72:75], 0
	v_mfma_f32_16x16x32_bf16 v[12:15], v[132:135], v[72:75], 0
	v_mfma_f32_16x16x32_bf16 v[20:23], v[120:123], v[8:11], v[20:23]
	v_mfma_f32_16x16x32_bf16 v[16:19], v[128:131], v[8:11], v[16:19]
	v_mfma_f32_16x16x32_bf16 v[12:15], v[136:139], v[8:11], v[12:15]
	ds_read_b128 v[116:119], v82 offset:34560
	ds_read_b128 v[120:123], v82 offset:34624
	s_waitcnt lgkmcnt(0)
	v_mfma_f32_16x16x32_bf16 v[124:127], v[116:119], v[72:75], 0
	v_mfma_f32_16x16x32_bf16 v[8:11], v[120:123], v[8:11], v[124:127]
	s_nop 4
	v_mul_f32_e32 v72, 0x3e000000, v68
	v_mul_f32_e32 v73, 0x3e000000, v69
	s_mov_b32 s2, 0xff61b1e6
	v_max3_f32 v72, v72, s2, v73
	v_mul_f32_e32 v73, 0x3e000000, v70
	v_mul_f32_e32 v74, 0x3e000000, v71
	v_max3_f32 v72, v72, v73, v74
	v_mul_f32_e32 v73, 0x3e000000, v64
	v_mul_f32_e32 v74, 0x3e000000, v65
	v_max3_f32 v72, v72, v73, v74
	v_mul_f32_e32 v73, 0x3e000000, v66
	v_mul_f32_e32 v74, 0x3e000000, v67
	v_max3_f32 v72, v72, v73, v74
	v_mul_f32_e32 v73, 0x3e000000, v60
	v_mul_f32_e32 v74, 0x3e000000, v61
	v_max3_f32 v72, v72, v73, v74
	v_mul_f32_e32 v73, 0x3e000000, v62
	v_mul_f32_e32 v74, 0x3e000000, v63
	v_max3_f32 v72, v72, v73, v74
	v_mul_f32_e32 v73, 0x3e000000, v56
	v_mul_f32_e32 v74, 0x3e000000, v57
	v_max3_f32 v72, v72, v73, v74
	v_mul_f32_e32 v73, 0x3e000000, v58
	v_mul_f32_e32 v74, 0x3e000000, v59
	v_max3_f32 v72, v72, v73, v74
	v_mul_f32_e32 v73, 0x3e000000, v52
	v_mul_f32_e32 v74, 0x3e000000, v53
	v_max3_f32 v72, v72, v73, v74
	v_mul_f32_e32 v73, 0x3e000000, v54
	v_mul_f32_e32 v74, 0x3e000000, v55
	v_max3_f32 v72, v72, v73, v74
	v_mul_f32_e32 v73, 0x3e000000, v48
	v_mul_f32_e32 v74, 0x3e000000, v49
	v_max3_f32 v72, v72, v73, v74
	v_mul_f32_e32 v73, 0x3e000000, v50
	v_mul_f32_e32 v74, 0x3e000000, v51
	v_max3_f32 v72, v72, v73, v74
	v_mul_f32_e32 v73, 0x3e000000, v44
	v_mul_f32_e32 v74, 0x3e000000, v45
	v_max3_f32 v72, v72, v73, v74
	v_mul_f32_e32 v73, 0x3e000000, v46
	v_mul_f32_e32 v74, 0x3e000000, v47
	v_max3_f32 v72, v72, v73, v74
	v_mul_f32_e32 v73, 0x3e000000, v40
	v_mul_f32_e32 v74, 0x3e000000, v41
	v_max3_f32 v72, v72, v73, v74
	v_mul_f32_e32 v73, 0x3e000000, v42
	v_mul_f32_e32 v74, 0x3e000000, v43
	v_max3_f32 v72, v72, v73, v74
	v_mul_f32_e32 v73, 0x3e000000, v36
	v_mul_f32_e32 v74, 0x3e000000, v37
	v_max3_f32 v72, v72, v73, v74
	v_mul_f32_e32 v73, 0x3e000000, v38
	v_mul_f32_e32 v74, 0x3e000000, v39
	v_max3_f32 v72, v72, v73, v74
	v_mul_f32_e32 v73, 0x3e000000, v32
	v_mul_f32_e32 v74, 0x3e000000, v33
	v_max3_f32 v72, v72, v73, v74
	v_mul_f32_e32 v73, 0x3e000000, v34
	v_mul_f32_e32 v74, 0x3e000000, v35
	v_max3_f32 v72, v72, v73, v74
	v_mul_f32_e32 v73, 0x3e000000, v28
	v_mul_f32_e32 v74, 0x3e000000, v29
	v_max3_f32 v72, v72, v73, v74
	v_mul_f32_e32 v73, 0x3e000000, v30
	v_mul_f32_e32 v74, 0x3e000000, v31
	v_max3_f32 v72, v72, v73, v74
	v_mul_f32_e32 v73, 0x3e000000, v24
	v_mul_f32_e32 v74, 0x3e000000, v25
	v_max3_f32 v72, v72, v73, v74
	v_mul_f32_e32 v73, 0x3e000000, v26
	v_mul_f32_e32 v74, 0x3e000000, v27
	v_max3_f32 v72, v72, v73, v74
	v_mul_f32_e32 v73, 0x3e000000, v20
	v_mul_f32_e32 v74, 0x3e000000, v21
	v_max3_f32 v72, v72, v73, v74
	v_mul_f32_e32 v73, 0x3e000000, v22
	v_mul_f32_e32 v74, 0x3e000000, v23
	v_max3_f32 v72, v72, v73, v74
	v_mul_f32_e32 v73, 0x3e000000, v16
	v_mul_f32_e32 v74, 0x3e000000, v17
	v_max3_f32 v72, v72, v73, v74
	v_mul_f32_e32 v73, 0x3e000000, v18
	v_mul_f32_e32 v74, 0x3e000000, v19
	v_max3_f32 v72, v72, v73, v74
	v_mul_f32_e32 v73, 0x3e000000, v12
	v_mul_f32_e32 v74, 0x3e000000, v13
	v_max3_f32 v72, v72, v73, v74
	v_mul_f32_e32 v73, 0x3e000000, v14
	v_mul_f32_e32 v74, 0x3e000000, v15
	v_max3_f32 v72, v72, v73, v74
	v_mul_f32_e32 v73, 0x3e000000, v8
	v_mul_f32_e32 v74, 0x3e000000, v9
	v_max3_f32 v72, v72, v73, v74
	v_mul_f32_e32 v73, 0x3e000000, v10
	v_mul_f32_e32 v74, 0x3e000000, v11
	v_max3_f32 v72, v72, v73, v74
	ds_bpermute_b32 v73, v83, v72
	s_mov_b32 s2, 0x3e000000
	s_waitcnt lgkmcnt(0)
	v_max_f32_e32 v73, v73, v73
	v_max_f32_e32 v72, v72, v73
	ds_bpermute_b32 v73, v84, v72
	s_waitcnt lgkmcnt(0)
	v_max_f32_e32 v73, v73, v73
	v_max_f32_e32 v86, v72, v73
	v_fma_f32 v68, v68, s2, -v86
	v_fma_f32 v69, v69, s2, -v86
	v_mul_f32_e32 v68, 0x3fb8aa3b, v68
	v_mul_f32_e32 v69, 0x3fb8aa3b, v69
	v_exp_f32_e32 v68, v68
	v_exp_f32_e32 v72, v69
	v_fma_f32 v69, v70, s2, -v86
	v_mul_f32_e32 v69, 0x3fb8aa3b, v69
	v_fma_f32 v70, v71, s2, -v86
	v_exp_f32_e32 v69, v69
	v_mul_f32_e32 v70, 0x3fb8aa3b, v70
	v_exp_f32_e32 v73, v70
	v_add_f32_e32 v70, 0, v68
	v_add_f32_e32 v70, v72, v70
	v_fma_f32 v64, v64, s2, -v86
	v_add_f32_e32 v70, v69, v70
	v_mul_f32_e32 v64, 0x3fb8aa3b, v64
	v_add_f32_e32 v87, v73, v70
	v_exp_f32_e32 v70, v64
	v_fma_f32 v64, v65, s2, -v86
	v_mul_f32_e32 v64, 0x3fb8aa3b, v64
	v_exp_f32_e32 v74, v64
	v_fma_f32 v64, v66, s2, -v86
	v_mul_f32_e32 v64, 0x3fb8aa3b, v64
	v_exp_f32_e32 v71, v64
	v_fma_f32 v64, v67, s2, -v86
	v_mul_f32_e32 v64, 0x3fb8aa3b, v64
	v_exp_f32_e32 v75, v64
	v_add_f32_e32 v64, v70, v87
	v_add_f32_e32 v64, v74, v64
	v_fma_f32 v60, v60, s2, -v86
	v_fma_f32 v61, v61, s2, -v86
	v_add_f32_e32 v64, v71, v64
	v_mul_f32_e32 v60, 0x3fb8aa3b, v60
	v_mul_f32_e32 v61, 0x3fb8aa3b, v61
	v_add_f32_e32 v66, v75, v64
	v_exp_f32_e32 v60, v60
	v_exp_f32_e32 v64, v61
	v_fma_f32 v61, v62, s2, -v86
	v_mul_f32_e32 v61, 0x3fb8aa3b, v61
	v_fma_f32 v62, v63, s2, -v86
	v_exp_f32_e32 v61, v61
	v_mul_f32_e32 v62, 0x3fb8aa3b, v62
	v_exp_f32_e32 v65, v62
	v_add_f32_e32 v62, v60, v66
	v_add_f32_e32 v62, v64, v62
	v_fma_f32 v56, v56, s2, -v86
	v_add_f32_e32 v62, v61, v62
	v_mul_f32_e32 v56, 0x3fb8aa3b, v56
	v_add_f32_e32 v87, v65, v62
	v_exp_f32_e32 v62, v56
	v_fma_f32 v56, v57, s2, -v86
	v_mul_f32_e32 v56, 0x3fb8aa3b, v56
	v_exp_f32_e32 v66, v56
	v_fma_f32 v56, v58, s2, -v86
	v_mul_f32_e32 v56, 0x3fb8aa3b, v56
	v_exp_f32_e32 v63, v56
	v_fma_f32 v56, v59, s2, -v86
	v_mul_f32_e32 v56, 0x3fb8aa3b, v56
	v_exp_f32_e32 v67, v56
	v_add_f32_e32 v56, v62, v87
	v_add_f32_e32 v56, v66, v56
	v_fma_f32 v52, v52, s2, -v86
	v_fma_f32 v53, v53, s2, -v86
	v_add_f32_e32 v56, v63, v56
	v_mul_f32_e32 v52, 0x3fb8aa3b, v52
	v_mul_f32_e32 v53, 0x3fb8aa3b, v53
	v_add_f32_e32 v58, v67, v56
	v_exp_f32_e32 v52, v52
	v_exp_f32_e32 v56, v53
	v_fma_f32 v53, v54, s2, -v86
	v_mul_f32_e32 v53, 0x3fb8aa3b, v53
	v_fma_f32 v54, v55, s2, -v86
	v_exp_f32_e32 v53, v53
	v_mul_f32_e32 v54, 0x3fb8aa3b, v54
	v_exp_f32_e32 v57, v54
	v_add_f32_e32 v54, v52, v58
	v_add_f32_e32 v54, v56, v54
	v_fma_f32 v48, v48, s2, -v86
	v_add_f32_e32 v54, v53, v54
	v_mul_f32_e32 v48, 0x3fb8aa3b, v48
	v_add_f32_e32 v87, v57, v54
	v_exp_f32_e32 v54, v48
	v_fma_f32 v48, v49, s2, -v86
	v_mul_f32_e32 v48, 0x3fb8aa3b, v48
	v_exp_f32_e32 v58, v48
	v_fma_f32 v48, v50, s2, -v86
	v_mul_f32_e32 v48, 0x3fb8aa3b, v48
	v_exp_f32_e32 v55, v48
	v_fma_f32 v48, v51, s2, -v86
	v_mul_f32_e32 v48, 0x3fb8aa3b, v48
	v_exp_f32_e32 v59, v48
	v_add_f32_e32 v48, v54, v87
	v_add_f32_e32 v48, v58, v48
	v_fma_f32 v44, v44, s2, -v86
	v_fma_f32 v45, v45, s2, -v86
	v_add_f32_e32 v48, v55, v48
	v_mul_f32_e32 v44, 0x3fb8aa3b, v44
	v_mul_f32_e32 v45, 0x3fb8aa3b, v45
	v_add_f32_e32 v50, v59, v48
	v_exp_f32_e32 v44, v44
	v_exp_f32_e32 v48, v45
	v_fma_f32 v45, v46, s2, -v86
	v_mul_f32_e32 v45, 0x3fb8aa3b, v45
	v_fma_f32 v46, v47, s2, -v86
	v_exp_f32_e32 v45, v45
	v_mul_f32_e32 v46, 0x3fb8aa3b, v46
	v_exp_f32_e32 v49, v46
	v_add_f32_e32 v46, v44, v50
	v_add_f32_e32 v46, v48, v46
	v_fma_f32 v40, v40, s2, -v86
	v_add_f32_e32 v46, v45, v46
	v_mul_f32_e32 v40, 0x3fb8aa3b, v40
	v_add_f32_e32 v87, v49, v46
	v_exp_f32_e32 v46, v40
	v_fma_f32 v40, v41, s2, -v86
	v_mul_f32_e32 v40, 0x3fb8aa3b, v40
	v_exp_f32_e32 v50, v40
	v_fma_f32 v40, v42, s2, -v86
	v_mul_f32_e32 v40, 0x3fb8aa3b, v40
	v_exp_f32_e32 v47, v40
	v_fma_f32 v40, v43, s2, -v86
	v_mul_f32_e32 v40, 0x3fb8aa3b, v40
	v_exp_f32_e32 v51, v40
	v_add_f32_e32 v40, v46, v87
	v_add_f32_e32 v40, v50, v40
	v_fma_f32 v36, v36, s2, -v86
	v_fma_f32 v37, v37, s2, -v86
	v_add_f32_e32 v40, v47, v40
	v_mul_f32_e32 v36, 0x3fb8aa3b, v36
	v_mul_f32_e32 v37, 0x3fb8aa3b, v37
	v_add_f32_e32 v42, v51, v40
	v_exp_f32_e32 v36, v36
	v_exp_f32_e32 v40, v37
	v_fma_f32 v37, v38, s2, -v86
	v_mul_f32_e32 v37, 0x3fb8aa3b, v37
	v_fma_f32 v38, v39, s2, -v86
	v_exp_f32_e32 v37, v37
	v_mul_f32_e32 v38, 0x3fb8aa3b, v38
	v_exp_f32_e32 v41, v38
	v_add_f32_e32 v38, v36, v42
	v_add_f32_e32 v38, v40, v38
	v_fma_f32 v32, v32, s2, -v86
	v_add_f32_e32 v38, v37, v38
	v_mul_f32_e32 v32, 0x3fb8aa3b, v32
	v_add_f32_e32 v87, v41, v38
	v_exp_f32_e32 v38, v32
	v_fma_f32 v32, v33, s2, -v86
	v_mul_f32_e32 v32, 0x3fb8aa3b, v32
	v_exp_f32_e32 v42, v32
	v_fma_f32 v32, v34, s2, -v86
	v_mul_f32_e32 v32, 0x3fb8aa3b, v32
	v_exp_f32_e32 v39, v32
	v_fma_f32 v32, v35, s2, -v86
	v_mul_f32_e32 v32, 0x3fb8aa3b, v32
	v_exp_f32_e32 v43, v32
	v_add_f32_e32 v32, v38, v87
	v_add_f32_e32 v32, v42, v32
	v_fma_f32 v28, v28, s2, -v86
	v_fma_f32 v29, v29, s2, -v86
	v_add_f32_e32 v32, v39, v32
	v_mul_f32_e32 v28, 0x3fb8aa3b, v28
	v_mul_f32_e32 v29, 0x3fb8aa3b, v29
	v_add_f32_e32 v34, v43, v32
	v_exp_f32_e32 v28, v28
	v_exp_f32_e32 v32, v29
	v_fma_f32 v29, v30, s2, -v86
	v_mul_f32_e32 v29, 0x3fb8aa3b, v29
	v_fma_f32 v30, v31, s2, -v86
	v_exp_f32_e32 v29, v29
	v_mul_f32_e32 v30, 0x3fb8aa3b, v30
	v_exp_f32_e32 v33, v30
	v_add_f32_e32 v30, v28, v34
	v_add_f32_e32 v30, v32, v30
	v_fma_f32 v24, v24, s2, -v86
	v_add_f32_e32 v30, v29, v30
	v_mul_f32_e32 v24, 0x3fb8aa3b, v24
	v_add_f32_e32 v87, v33, v30
	v_exp_f32_e32 v30, v24
	v_fma_f32 v24, v25, s2, -v86
	v_mul_f32_e32 v24, 0x3fb8aa3b, v24
	v_exp_f32_e32 v34, v24
	v_fma_f32 v24, v26, s2, -v86
	v_mul_f32_e32 v24, 0x3fb8aa3b, v24
	v_exp_f32_e32 v31, v24
	v_fma_f32 v24, v27, s2, -v86
	v_mul_f32_e32 v24, 0x3fb8aa3b, v24
	v_exp_f32_e32 v35, v24
	v_add_f32_e32 v24, v30, v87
	v_add_f32_e32 v24, v34, v24
	v_fma_f32 v20, v20, s2, -v86
	v_fma_f32 v21, v21, s2, -v86
	v_add_f32_e32 v24, v31, v24
	v_mul_f32_e32 v20, 0x3fb8aa3b, v20
	v_mul_f32_e32 v21, 0x3fb8aa3b, v21
	v_add_f32_e32 v26, v35, v24
	v_exp_f32_e32 v20, v20
	v_exp_f32_e32 v24, v21
	v_fma_f32 v21, v22, s2, -v86
	v_mul_f32_e32 v21, 0x3fb8aa3b, v21
	v_fma_f32 v22, v23, s2, -v86
	v_exp_f32_e32 v21, v21
	v_mul_f32_e32 v22, 0x3fb8aa3b, v22
	v_exp_f32_e32 v25, v22
	v_add_f32_e32 v22, v20, v26
	v_add_f32_e32 v22, v24, v22
	v_fma_f32 v16, v16, s2, -v86
	v_add_f32_e32 v22, v21, v22
	v_mul_f32_e32 v16, 0x3fb8aa3b, v16
	v_add_f32_e32 v87, v25, v22
	v_exp_f32_e32 v22, v16
	v_fma_f32 v16, v17, s2, -v86
	v_mul_f32_e32 v16, 0x3fb8aa3b, v16
	v_exp_f32_e32 v26, v16
	v_fma_f32 v16, v18, s2, -v86
	v_mul_f32_e32 v16, 0x3fb8aa3b, v16
	v_exp_f32_e32 v23, v16
	v_fma_f32 v16, v19, s2, -v86
	v_mul_f32_e32 v16, 0x3fb8aa3b, v16
	v_exp_f32_e32 v27, v16
	v_add_f32_e32 v16, v22, v87
	v_add_f32_e32 v16, v26, v16
	v_fma_f32 v12, v12, s2, -v86
	v_fma_f32 v13, v13, s2, -v86
	v_add_f32_e32 v16, v23, v16
	v_mul_f32_e32 v12, 0x3fb8aa3b, v12
	v_mul_f32_e32 v13, 0x3fb8aa3b, v13
	v_add_f32_e32 v18, v27, v16
	v_exp_f32_e32 v12, v12
	v_exp_f32_e32 v16, v13
	v_fma_f32 v13, v14, s2, -v86
	v_mul_f32_e32 v13, 0x3fb8aa3b, v13
	v_fma_f32 v14, v15, s2, -v86
	v_exp_f32_e32 v13, v13
	v_mul_f32_e32 v14, 0x3fb8aa3b, v14
	v_exp_f32_e32 v17, v14
	v_add_f32_e32 v14, v12, v18
	v_add_f32_e32 v14, v16, v14
	v_fma_f32 v8, v8, s2, -v86
	v_fma_f32 v9, v9, s2, -v86
	v_add_f32_e32 v14, v13, v14
	v_mul_f32_e32 v8, 0x3fb8aa3b, v8
	v_mul_f32_e32 v9, 0x3fb8aa3b, v9
	v_add_f32_e32 v18, v17, v14
	v_exp_f32_e32 v8, v8
	v_exp_f32_e32 v14, v9
	v_fma_f32 v9, v10, s2, -v86
	v_mul_f32_e32 v9, 0x3fb8aa3b, v9
	v_fma_f32 v10, v11, s2, -v86
	v_exp_f32_e32 v9, v9
	v_mul_f32_e32 v10, 0x3fb8aa3b, v10
	v_exp_f32_e32 v15, v10
	v_add_f32_e32 v10, v8, v18
	v_add_f32_e32 v10, v14, v10
	v_add_f32_e32 v10, v9, v10
	v_add_f32_e32 v10, v15, v10
	ds_bpermute_b32 v11, v83, v10
	s_waitcnt lgkmcnt(0)
	v_add_f32_e32 v10, v10, v11
	ds_bpermute_b32 v11, v84, v10
	s_waitcnt lgkmcnt(0)
	v_add_f32_e32 v10, v10, v11
	v_div_scale_f32 v11, s[2:3], v10, v10, 1.0
	v_rcp_f32_e32 v18, v11
	v_div_scale_f32 v19, vcc, 1.0, v10, 1.0
	v_fma_f32 v86, -v11, v18, 1.0
	v_fmac_f32_e32 v18, v86, v18
	v_mul_f32_e32 v86, v19, v18
	v_fma_f32 v87, -v11, v86, v19
	v_fmac_f32_e32 v86, v87, v18
	v_fma_f32 v11, -v11, v86, v19
	v_div_fmas_f32 v11, v11, v18, v86
	v_div_fixup_f32 v10, v11, v10, 1.0
	v_pk_mul_f32 v[18:19], v[68:69], v[10:11] op_sel_hi:[1,0]
	v_pk_mul_f32 v[68:69], v[72:73], v[10:11] op_sel_hi:[1,0]
	v_pk_mul_f32 v[72:73], v[74:75], v[10:11] op_sel_hi:[1,0]
	v_pk_mul_f32 v[70:71], v[70:71], v[10:11] op_sel_hi:[1,0]
	v_bfe_u32 v11, v73, 16, 1
	v_bfe_u32 v74, v72, 16, 1
	v_bfe_u32 v75, v69, 16, 1
	v_bfe_u32 v86, v68, 16, 1
	v_add3_u32 v73, v73, v11, s33
	v_bfe_u32 v11, v18, 16, 1
	v_add3_u32 v86, v68, v86, s33
	v_add3_u32 v87, v69, v75, s33
	v_add3_u32 v72, v72, v74, s33
	v_bfe_u32 v68, v19, 16, 1
	v_bfe_u32 v69, v70, 16, 1
	v_bfe_u32 v74, v71, 16, 1
	v_add3_u32 v18, v18, v11, s33
	v_add_u32_e32 v11, 0x9000, v85
	v_add3_u32 v74, v71, v74, s33
	v_add3_u32 v75, v70, v69, s33
	v_add3_u32 v19, v19, v68, s33
	ds_read2_b64 v[68:71], v11 offset1:4
	v_lshrrev_b32_e32 v18, 16, v18
	v_lshrrev_b32_e32 v19, 16, v19
	v_lshrrev_b32_e32 v88, 16, v75
	v_lshrrev_b32_e32 v74, 16, v74
	v_and_or_b32 v75, v73, s29, v74
	v_and_or_b32 v74, v72, s29, v88
	v_and_or_b32 v73, v87, s29, v19
	v_and_or_b32 v72, v86, s29, v18
	v_add_u32_e32 v18, 0xb000, v85
	s_waitcnt lgkmcnt(0)
	v_mfma_f32_16x16x32_bf16 v[86:89], v[68:71], v[72:75], 0
	ds_read2_b64 v[68:71], v18 offset0:32 offset1:36
	s_waitcnt lgkmcnt(0)
	v_mfma_f32_16x16x32_bf16 v[90:93], v[68:71], v[72:75], 0
	v_add_u32_e32 v68, 0xd000, v85
	v_add_u32_e32 v69, 0xf000, v85
	ds_read2_b64 v[94:97], v68 offset0:64 offset1:68
	ds_read2_b64 v[98:101], v69 offset0:96 offset1:100
	s_waitcnt lgkmcnt(1)
	v_mfma_f32_16x16x32_bf16 v[94:97], v[94:97], v[72:75], 0
	s_waitcnt lgkmcnt(0)
	v_mfma_f32_16x16x32_bf16 v[70:73], v[98:101], v[72:75], 0
	ds_read2_b64 v[132:135], v11 offset0:8 offset1:12
	ds_read2_b64 v[136:139], v18 offset0:40 offset1:44
	ds_read2_b64 v[140:143], v68 offset0:72 offset1:76
	ds_read2_b64 v[144:147], v69 offset0:104 offset1:108
	v_mul_f32_e64 v64, v64, v10
	v_mul_f32_e64 v65, v65, v10
	v_pk_mul_f32 v[66:67], v[66:67], v[10:11] op_sel_hi:[1,0]
	v_pk_mul_f32 v[60:61], v[60:61], v[10:11] op_sel_hi:[1,0]
	v_pk_mul_f32 v[62:63], v[62:63], v[10:11] op_sel_hi:[1,0]
	v_bfe_u32 v19, v67, 16, 1
	v_bfe_u32 v74, v66, 16, 1
	v_bfe_u32 v75, v65, 16, 1
	v_bfe_u32 v98, v64, 16, 1
	v_add3_u32 v64, v64, v98, s33
	v_add3_u32 v65, v65, v75, s33
	v_add3_u32 v66, v66, v74, s33
	v_add3_u32 v19, v67, v19, s33
	v_bfe_u32 v67, v60, 16, 1
	v_bfe_u32 v74, v61, 16, 1
	v_bfe_u32 v75, v62, 16, 1
	v_bfe_u32 v98, v63, 16, 1
	v_add3_u32 v98, v63, v98, s33
	v_add3_u32 v75, v62, v75, s33
	v_add3_u32 v74, v61, v74, s33
	v_add3_u32 v67, v60, v67, s33
	v_lshrrev_b32_e32 v99, 16, v67
	v_lshrrev_b32_e32 v74, 16, v74
	v_lshrrev_b32_e32 v75, 16, v75
	v_lshrrev_b32_e32 v67, 16, v98
	v_and_or_b32 v67, v19, s29, v67
	v_and_or_b32 v66, v66, s29, v75
	v_and_or_b32 v65, v65, s29, v74
	v_and_or_b32 v64, v64, s29, v99
	s_waitcnt lgkmcnt(3)
	s_nop 1
	v_mfma_f32_16x16x32_bf16 v[60:63], v[132:135], v[64:67], v[86:89]
	s_waitcnt lgkmcnt(2)
	v_mfma_f32_16x16x32_bf16 v[86:89], v[136:139], v[64:67], v[90:93]
	s_waitcnt lgkmcnt(1)
	v_mfma_f32_16x16x32_bf16 v[90:93], v[140:143], v[64:67], v[94:97]
	s_waitcnt lgkmcnt(0)
	v_mfma_f32_16x16x32_bf16 v[64:67], v[144:147], v[64:67], v[70:73]
	ds_read2_b64 v[116:119], v11 offset0:16 offset1:20
	ds_read2_b64 v[120:123], v18 offset0:48 offset1:52
	ds_read2_b64 v[124:127], v68 offset0:80 offset1:84
	ds_read2_b64 v[128:131], v69 offset0:112 offset1:116
	v_mul_f32_e64 v56, v56, v10
	v_mul_f32_e64 v57, v57, v10
	v_pk_mul_f32 v[58:59], v[58:59], v[10:11] op_sel_hi:[1,0]
	v_pk_mul_f32 v[52:53], v[52:53], v[10:11] op_sel_hi:[1,0]
	v_pk_mul_f32 v[54:55], v[54:55], v[10:11] op_sel_hi:[1,0]
	v_bfe_u32 v19, v59, 16, 1
	v_bfe_u32 v70, v58, 16, 1
	s_nop 0
	v_bfe_u32 v72, v56, 16, 1
	v_add3_u32 v56, v56, v72, s33
	s_nop 0
	v_add3_u32 v58, v58, v70, s33
	v_add3_u32 v19, v59, v19, s33
	v_bfe_u32 v59, v52, 16, 1
	s_nop 0
	v_bfe_u32 v71, v54, 16, 1
	v_bfe_u32 v72, v55, 16, 1
	v_add3_u32 v72, v55, v72, s33
	v_add3_u32 v71, v54, v71, s33
	s_nop 0
	v_add3_u32 v59, v52, v59, s33
	v_lshrrev_b32_e32 v73, 16, v59
	s_nop 0
	v_lshrrev_b32_e32 v71, 16, v71
	v_lshrrev_b32_e32 v59, 16, v72
	v_and_or_b32 v59, v19, s29, v59
	v_and_or_b32 v58, v58, s29, v71
	v_cvt_pk_bf16_f32 v57, v53, v57
	v_and_or_b32 v56, v56, s29, v73
	s_waitcnt lgkmcnt(3)
	s_nop 1
	v_mfma_f32_16x16x32_bf16 v[52:55], v[116:119], v[56:59], v[60:63]
	s_waitcnt lgkmcnt(2)
	v_mfma_f32_16x16x32_bf16 v[60:63], v[120:123], v[56:59], v[86:89]
	s_waitcnt lgkmcnt(1)
	v_mfma_f32_16x16x32_bf16 v[70:73], v[124:127], v[56:59], v[90:93]
	s_waitcnt lgkmcnt(0)
	v_mfma_f32_16x16x32_bf16 v[56:59], v[128:131], v[56:59], v[64:67]
	ds_read2_b64 v[132:135], v11 offset0:24 offset1:28
	ds_read2_b64 v[136:139], v18 offset0:56 offset1:60
	ds_read2_b64 v[140:143], v68 offset0:88 offset1:92
	ds_read2_b64 v[144:147], v69 offset0:120 offset1:124
	v_mul_f32_e64 v48, v48, v10
	v_mul_f32_e64 v49, v49, v10
	v_pk_mul_f32 v[50:51], v[50:51], v[10:11] op_sel_hi:[1,0]
	v_pk_mul_f32 v[44:45], v[44:45], v[10:11] op_sel_hi:[1,0]
	v_pk_mul_f32 v[46:47], v[46:47], v[10:11] op_sel_hi:[1,0]
	v_bfe_u32 v19, v51, 16, 1
	v_bfe_u32 v64, v50, 16, 1
	v_bfe_u32 v65, v49, 16, 1
	v_bfe_u32 v66, v48, 16, 1
	v_add3_u32 v48, v48, v66, s33
	v_add3_u32 v49, v49, v65, s33
	v_add3_u32 v50, v50, v64, s33
	v_add3_u32 v19, v51, v19, s33
	v_bfe_u32 v51, v44, 16, 1
	v_bfe_u32 v64, v45, 16, 1
	v_bfe_u32 v65, v46, 16, 1
	v_bfe_u32 v66, v47, 16, 1
	v_add3_u32 v66, v47, v66, s33
	v_add3_u32 v65, v46, v65, s33
	v_add3_u32 v64, v45, v64, s33
	v_add3_u32 v51, v44, v51, s33
	v_lshrrev_b32_e32 v67, 16, v51
	v_lshrrev_b32_e32 v64, 16, v64
	v_lshrrev_b32_e32 v65, 16, v65
	v_lshrrev_b32_e32 v51, 16, v66
	v_and_or_b32 v51, v19, s29, v51
	v_and_or_b32 v50, v50, s29, v65
	v_and_or_b32 v49, v49, s29, v64
	v_and_or_b32 v48, v48, s29, v67
	s_waitcnt lgkmcnt(3)
	s_nop 1
	v_mfma_f32_16x16x32_bf16 v[44:47], v[132:135], v[48:51], v[52:55]
	s_waitcnt lgkmcnt(2)
	v_mfma_f32_16x16x32_bf16 v[52:55], v[136:139], v[48:51], v[60:63]
	s_waitcnt lgkmcnt(1)
	v_mfma_f32_16x16x32_bf16 v[60:63], v[140:143], v[48:51], v[70:73]
	s_waitcnt lgkmcnt(0)
	v_mfma_f32_16x16x32_bf16 v[48:51], v[144:147], v[48:51], v[56:59]
	ds_read2_b64 v[116:119], v11 offset0:32 offset1:36
	ds_read2_b64 v[120:123], v18 offset0:64 offset1:68
	ds_read2_b64 v[124:127], v68 offset0:96 offset1:100
	ds_read2_b64 v[128:131], v69 offset0:128 offset1:132
	v_mul_f32_e64 v40, v40, v10
	v_mul_f32_e64 v41, v41, v10
	v_pk_mul_f32 v[42:43], v[42:43], v[10:11] op_sel_hi:[1,0]
	v_pk_mul_f32 v[36:37], v[36:37], v[10:11] op_sel_hi:[1,0]
	v_pk_mul_f32 v[38:39], v[38:39], v[10:11] op_sel_hi:[1,0]
	v_bfe_u32 v19, v43, 16, 1
	v_bfe_u32 v56, v42, 16, 1
	v_bfe_u32 v57, v41, 16, 1
	v_bfe_u32 v58, v40, 16, 1
	v_add3_u32 v40, v40, v58, s33
	v_add3_u32 v41, v41, v57, s33
	v_add3_u32 v42, v42, v56, s33
	v_add3_u32 v19, v43, v19, s33
	v_bfe_u32 v43, v36, 16, 1
	v_bfe_u32 v56, v37, 16, 1
	v_bfe_u32 v57, v38, 16, 1
	v_bfe_u32 v58, v39, 16, 1
	v_add3_u32 v58, v39, v58, s33
	v_add3_u32 v57, v38, v57, s33
	v_add3_u32 v56, v37, v56, s33
	v_add3_u32 v43, v36, v43, s33
	v_lshrrev_b32_e32 v59, 16, v43
	v_lshrrev_b32_e32 v56, 16, v56
	v_lshrrev_b32_e32 v57, 16, v57
	v_lshrrev_b32_e32 v43, 16, v58
	v_and_or_b32 v43, v19, s29, v43
	v_and_or_b32 v42, v42, s29, v57
	v_and_or_b32 v41, v41, s29, v56
	v_and_or_b32 v40, v40, s29, v59
	s_waitcnt lgkmcnt(3)
	s_nop 1
	v_mfma_f32_16x16x32_bf16 v[36:39], v[116:119], v[40:43], v[44:47]
	s_waitcnt lgkmcnt(2)
	v_mfma_f32_16x16x32_bf16 v[44:47], v[120:123], v[40:43], v[52:55]
	s_waitcnt lgkmcnt(1)
	v_mfma_f32_16x16x32_bf16 v[52:55], v[124:127], v[40:43], v[60:63]
	s_waitcnt lgkmcnt(0)
	v_mfma_f32_16x16x32_bf16 v[40:43], v[128:131], v[40:43], v[48:51]
	ds_read2_b64 v[132:135], v11 offset0:40 offset1:44
	ds_read2_b64 v[136:139], v18 offset0:72 offset1:76
	ds_read2_b64 v[140:143], v68 offset0:104 offset1:108
	ds_read2_b64 v[144:147], v69 offset0:136 offset1:140
	v_mul_f32_e64 v32, v32, v10
	v_mul_f32_e64 v33, v33, v10
	v_pk_mul_f32 v[34:35], v[34:35], v[10:11] op_sel_hi:[1,0]
	v_pk_mul_f32 v[28:29], v[28:29], v[10:11] op_sel_hi:[1,0]
	v_pk_mul_f32 v[30:31], v[30:31], v[10:11] op_sel_hi:[1,0]
	v_bfe_u32 v19, v35, 16, 1
	v_bfe_u32 v48, v34, 16, 1
	v_bfe_u32 v49, v33, 16, 1
	v_bfe_u32 v50, v32, 16, 1
	v_add3_u32 v32, v32, v50, s33
	v_add3_u32 v33, v33, v49, s33
	v_add3_u32 v34, v34, v48, s33
	v_add3_u32 v19, v35, v19, s33
	v_bfe_u32 v35, v28, 16, 1
	v_bfe_u32 v48, v29, 16, 1
	v_bfe_u32 v49, v30, 16, 1
	v_bfe_u32 v50, v31, 16, 1
	v_add3_u32 v50, v31, v50, s33
	v_add3_u32 v49, v30, v49, s33
	v_add3_u32 v48, v29, v48, s33
	v_add3_u32 v35, v28, v35, s33
	v_lshrrev_b32_e32 v51, 16, v35
	v_lshrrev_b32_e32 v48, 16, v48
	v_lshrrev_b32_e32 v49, 16, v49
	v_lshrrev_b32_e32 v35, 16, v50
	v_and_or_b32 v35, v19, s29, v35
	v_and_or_b32 v34, v34, s29, v49
	v_and_or_b32 v33, v33, s29, v48
	v_and_or_b32 v32, v32, s29, v51
	s_waitcnt lgkmcnt(3)
	s_nop 1
	v_mfma_f32_16x16x32_bf16 v[28:31], v[132:135], v[32:35], v[36:39]
	s_waitcnt lgkmcnt(2)
	v_mfma_f32_16x16x32_bf16 v[36:39], v[136:139], v[32:35], v[44:47]
	s_waitcnt lgkmcnt(1)
	v_mfma_f32_16x16x32_bf16 v[44:47], v[140:143], v[32:35], v[52:55]
	s_waitcnt lgkmcnt(0)
	v_mfma_f32_16x16x32_bf16 v[32:35], v[144:147], v[32:35], v[40:43]
	ds_read2_b64 v[116:119], v11 offset0:48 offset1:52
	ds_read2_b64 v[120:123], v18 offset0:80 offset1:84
	ds_read2_b64 v[124:127], v68 offset0:112 offset1:116
	ds_read2_b64 v[128:131], v69 offset0:144 offset1:148
	v_mul_f32_e64 v24, v24, v10
	v_mul_f32_e64 v25, v25, v10
	v_pk_mul_f32 v[26:27], v[26:27], v[10:11] op_sel_hi:[1,0]
	v_pk_mul_f32 v[20:21], v[20:21], v[10:11] op_sel_hi:[1,0]
	v_pk_mul_f32 v[22:23], v[22:23], v[10:11] op_sel_hi:[1,0]
	v_bfe_u32 v19, v27, 16, 1
	v_bfe_u32 v40, v26, 16, 1
	v_bfe_u32 v41, v25, 16, 1
	v_bfe_u32 v42, v24, 16, 1
	v_add3_u32 v24, v24, v42, s33
	v_add3_u32 v25, v25, v41, s33
	v_add3_u32 v26, v26, v40, s33
	v_add3_u32 v19, v27, v19, s33
	v_bfe_u32 v27, v20, 16, 1
	v_bfe_u32 v40, v21, 16, 1
	v_bfe_u32 v41, v22, 16, 1
	v_bfe_u32 v42, v23, 16, 1
	v_add3_u32 v42, v23, v42, s33
	v_add3_u32 v41, v22, v41, s33
	v_add3_u32 v40, v21, v40, s33
	v_add3_u32 v27, v20, v27, s33
	v_lshrrev_b32_e32 v43, 16, v27
	v_lshrrev_b32_e32 v40, 16, v40
	v_lshrrev_b32_e32 v41, 16, v41
	v_lshrrev_b32_e32 v27, 16, v42
	v_and_or_b32 v27, v19, s29, v27
	v_and_or_b32 v26, v26, s29, v41
	v_and_or_b32 v25, v25, s29, v40
	v_and_or_b32 v24, v24, s29, v43
	s_waitcnt lgkmcnt(3)
	s_nop 1
	v_mfma_f32_16x16x32_bf16 v[20:23], v[116:119], v[24:27], v[28:31]
	s_waitcnt lgkmcnt(2)
	v_mfma_f32_16x16x32_bf16 v[28:31], v[120:123], v[24:27], v[36:39]
	s_waitcnt lgkmcnt(1)
	v_mfma_f32_16x16x32_bf16 v[36:39], v[124:127], v[24:27], v[44:47]
	s_waitcnt lgkmcnt(0)
	v_mfma_f32_16x16x32_bf16 v[24:27], v[128:131], v[24:27], v[32:35]
	ds_read2_b64 v[132:135], v11 offset0:56 offset1:60
	ds_read2_b64 v[136:139], v18 offset0:88 offset1:92
	ds_read2_b64 v[140:143], v68 offset0:120 offset1:124
	ds_read2_b64 v[144:147], v69 offset0:152 offset1:156
	v_mul_f32_e64 v16, v16, v10
	v_mul_f32_e64 v17, v17, v10
	v_pk_mul_f32 v[14:15], v[14:15], v[10:11] op_sel_hi:[1,0]
	v_pk_mul_f32 v[12:13], v[12:13], v[10:11] op_sel_hi:[1,0]
	v_pk_mul_f32 v[8:9], v[8:9], v[10:11] op_sel_hi:[1,0]
	s_nop 0
	s_nop 0
	v_bfe_u32 v33, v16, 16, 1
	v_add3_u32 v16, v16, v33, s33
	s_nop 0
	s_nop 0
	v_bfe_u32 v10, v12, 16, 1
	v_bfe_u32 v32, v8, 16, 1
	s_nop 0
	s_nop 0
	v_add3_u32 v32, v8, v32, s33
	v_add3_u32 v12, v12, v10, s33
	v_bfe_u32 v19, v14, 16, 1
	v_add3_u32 v14, v14, v19, s33
	s_nop 0
	s_nop 0
	v_lshrrev_b32_e32 v12, 16, v12
	s_nop 0
	v_lshrrev_b32_e32 v19, 16, v32
	s_nop 0
	v_cvt_pk_bf16_f32 v35, v9, v15
	v_and_or_b32 v34, v14, s29, v19
	v_cvt_pk_bf16_f32 v33, v13, v17
	v_and_or_b32 v32, v16, s29, v12
	s_waitcnt lgkmcnt(3)
	s_nop 1
	v_mfma_f32_16x16x32_bf16 v[20:23], v[132:135], v[32:35], v[20:23]
	s_waitcnt lgkmcnt(2)
	v_mfma_f32_16x16x32_bf16 v[16:19], v[136:139], v[32:35], v[28:31]
	s_waitcnt lgkmcnt(1)
	v_mfma_f32_16x16x32_bf16 v[12:15], v[140:143], v[32:35], v[36:39]
	s_waitcnt lgkmcnt(0)
	v_mfma_f32_16x16x32_bf16 v[8:11], v[144:147], v[32:35], v[24:27]
	s_and_saveexec_b64 s[2:3], s[0:1]
	s_cbranch_execz .LBB0_253
	s_nop 0
	v_bfe_u32 v26, v20, 16, 1
	v_add3_u32 v20, v20, v26, s33
	v_bfe_u32 v26, v21, 16, 1
	v_add3_u32 v21, v21, v26, s33
	v_lshrrev_b32_e32 v20, 16, v20
	v_add_u32_e32 v24, s6, v81
	v_and_or_b32 v20, v21, s29, v20
	s_nop 0
	v_ashrrev_i32_e32 v25, 31, v24
	s_nop 0
	s_nop 0
	v_lshlrev_b64 v[24:25], 11, v[24:25]
	s_nop 0
	s_nop 0
	v_lshl_add_u64 v[24:25], v[76:77], 0, v[24:25]
	v_cvt_pk_bf16_f32 v21, v22, v23
	global_store_dwordx2 v[24:25], v[20:21], off offset:1536
	v_bfe_u32 v20, v16, 16, 1
	v_add3_u32 v16, v16, v20, s33
	v_bfe_u32 v20, v17, 16, 1
	v_add3_u32 v17, v17, v20, s33
	v_lshrrev_b32_e32 v16, 16, v16
	v_and_or_b32 v16, v17, s29, v16
	s_nop 0
	s_nop 0
	s_nop 0
	s_nop 0
	s_nop 0
	v_cvt_pk_bf16_f32 v17, v18, v19
	global_store_dwordx2 v[24:25], v[16:17], off offset:1568
	v_bfe_u32 v16, v12, 16, 1
	v_add3_u32 v12, v12, v16, s33
	v_bfe_u32 v16, v13, 16, 1
	v_add3_u32 v13, v13, v16, s33
	v_lshrrev_b32_e32 v12, 16, v12
	v_and_or_b32 v12, v13, s29, v12
	s_nop 0
	s_nop 0
	s_nop 0
	s_nop 0
	s_nop 0
	v_cvt_pk_bf16_f32 v13, v14, v15
	global_store_dwordx2 v[24:25], v[12:13], off offset:1600
	v_bfe_u32 v12, v8, 16, 1
	v_add3_u32 v8, v8, v12, s33
	v_bfe_u32 v12, v9, 16, 1
	v_add3_u32 v9, v9, v12, s33
	v_lshrrev_b32_e32 v8, 16, v8
	v_and_or_b32 v8, v9, s29, v8
	s_nop 0
	s_nop 0
	s_nop 0
	s_nop 0
	s_nop 0
	v_cvt_pk_bf16_f32 v9, v10, v11
	global_store_dwordx2 v[24:25], v[8:9], off offset:1632
	s_branch .LBB0_253

.LBB0_319:
	v_readlane_b32 s8, v249, 63
	v_mul_f32_e32 v8, 0x3e000000, v8
	v_readlane_b32 s9, v248, 0
	v_mul_f32_e32 v9, 0x3e000000, v9
	v_mul_f32_e32 v10, 0x3e000000, v10
	v_cndmask_b32_e64 v8, v230, v8, s[8:9]
	v_readlane_b32 s8, v248, 1
	v_readlane_b32 s9, v248, 2
	v_mul_f32_e32 v34, 0x3e000000, v37
	v_mul_f32_e32 v11, 0x3e000000, v11
	v_cndmask_b32_e64 v9, v230, v9, s[8:9]
	v_readlane_b32 s8, v248, 3
	v_readlane_b32 s9, v248, 4
	v_cndmask_b32_e64 v69, v230, v34, s[44:45]
	v_mul_f32_e32 v34, 0x3e000000, v38
	v_cndmask_b32_e64 v10, v230, v10, s[8:9]
	v_readlane_b32 s8, v248, 5
	v_readlane_b32 s9, v248, 6
	v_cndmask_b32_e64 v70, v230, v34, s[46:47]
	v_mul_f32_e32 v34, 0x3e000000, v39
	v_cndmask_b32_e64 v11, v230, v11, s[8:9]
	v_readlane_b32 s8, v248, 7
	v_max3_f32 v32, v68, v8, v9
	v_mul_f32_e32 v12, 0x3e000000, v12
	v_readlane_b32 s9, v248, 8
	v_mul_f32_e32 v13, 0x3e000000, v13
	v_cndmask_b32_e64 v71, v230, v34, s[48:49]
	v_mul_f32_e32 v34, 0x3e000000, v40
	v_max3_f32 v32, v32, v10, v11
	v_cndmask_b32_e64 v12, v230, v12, s[8:9]
	v_cndmask_b32_e64 v13, v230, v13, s[10:11]
	v_mul_f32_e32 v14, 0x3e000000, v14
	v_mul_f32_e32 v15, 0x3e000000, v15
	v_cndmask_b32_e64 v75, v230, v34, s[50:51]
	v_mul_f32_e32 v34, 0x3e000000, v41
	v_max3_f32 v32, v32, v12, v13
	v_cndmask_b32_e64 v14, v230, v14, s[12:13]
	v_cndmask_b32_e64 v15, v230, v15, s[14:15]
	v_mul_f32_e32 v20, 0x3e000000, v20
	v_mul_f32_e32 v21, 0x3e000000, v21
	v_cndmask_b32_e64 v76, v230, v34, s[52:53]
	v_mul_f32_e32 v34, 0x3e000000, v42
	v_max3_f32 v32, v32, v14, v15
	v_cndmask_b32_e64 v20, v230, v20, s[16:17]
	v_cndmask_b32_e64 v21, v230, v21, s[18:19]
	v_mul_f32_e32 v22, 0x3e000000, v22
	v_mul_f32_e32 v23, 0x3e000000, v23
	v_cndmask_b32_e64 v77, v230, v34, s[54:55]
	v_mul_f32_e32 v34, 0x3e000000, v43
	v_max3_f32 v32, v32, v20, v21
	v_cndmask_b32_e64 v22, v230, v22, s[20:21]
	v_cndmask_b32_e64 v23, v230, v23, s[22:23]
	v_mul_f32_e32 v24, 0x3e000000, v24
	v_mul_f32_e32 v25, 0x3e000000, v25
	v_cndmask_b32_e64 v78, v230, v34, s[56:57]
	v_mul_f32_e32 v34, 0x3e000000, v44
	v_max3_f32 v32, v32, v22, v23
	v_cndmask_b32_e64 v24, v230, v24, s[24:25]
	v_cndmask_b32_e64 v25, v230, v25, s[26:27]
	v_mul_f32_e32 v26, 0x3e000000, v26
	v_mul_f32_e32 v27, 0x3e000000, v27
	v_cndmask_b32_e64 v79, v230, v34, s[58:59]
	v_mul_f32_e32 v34, 0x3e000000, v45
	v_max3_f32 v32, v32, v24, v25
	v_cndmask_b32_e64 v26, v230, v26, s[4:5]
	v_cndmask_b32_e64 v27, v230, v27, s[30:31]
	v_mul_f32_e32 v28, 0x3e000000, v28
	v_mul_f32_e32 v29, 0x3e000000, v29
	v_cndmask_b32_e64 v81, v230, v34, s[60:61]
	v_mul_f32_e32 v34, 0x3e000000, v46
	v_max3_f32 v32, v32, v26, v27
	v_cndmask_b32_e64 v28, v230, v28, s[34:35]
	v_cndmask_b32_e64 v29, v230, v29, s[36:37]
	v_mul_f32_e32 v30, 0x3e000000, v30
	v_mul_f32_e32 v31, 0x3e000000, v31
	v_cndmask_b32_e64 v82, v230, v34, s[62:63]
	v_mul_f32_e32 v34, 0x3e000000, v47
	v_max3_f32 v32, v32, v28, v29
	v_cndmask_b32_e64 v30, v230, v30, s[38:39]
	v_cndmask_b32_e64 v31, v230, v31, s[40:41]
	v_mul_f32_e32 v33, 0x3e000000, v36
	v_cndmask_b32_e64 v83, v230, v34, s[64:65]
	v_mul_f32_e32 v34, 0x3e000000, v48
	v_max3_f32 v32, v32, v30, v31
	v_cndmask_b32_e64 v33, v230, v33, s[42:43]
	v_cndmask_b32_e64 v84, v230, v34, s[66:67]
	v_mul_f32_e32 v34, 0x3e000000, v49
	v_max3_f32 v32, v32, v33, v69
	v_cndmask_b32_e64 v85, v230, v34, s[68:69]
	v_mul_f32_e32 v34, 0x3e000000, v50
	v_max3_f32 v32, v32, v70, v71
	v_cndmask_b32_e64 v86, v230, v34, s[70:71]
	v_mul_f32_e32 v34, 0x3e000000, v51
	v_max3_f32 v32, v32, v75, v76
	v_cndmask_b32_e64 v87, v230, v34, s[72:73]
	v_mul_f32_e32 v34, 0x3e000000, v52
	v_max3_f32 v32, v32, v77, v78
	v_cndmask_b32_e64 v88, v230, v34, s[74:75]
	v_mul_f32_e32 v34, 0x3e000000, v53
	v_max3_f32 v32, v32, v79, v81
	v_cndmask_b32_e64 v89, v230, v34, s[76:77]
	v_mul_f32_e32 v34, 0x3e000000, v54
	v_max3_f32 v32, v32, v82, v83
	v_cndmask_b32_e64 v90, v230, v34, s[78:79]
	v_mul_f32_e32 v34, 0x3e000000, v55
	v_max3_f32 v32, v32, v84, v85
	v_cndmask_b32_e64 v91, v230, v34, s[80:81]
	v_mul_f32_e32 v34, 0x3e000000, v56
	v_max3_f32 v32, v32, v86, v87
	v_cndmask_b32_e64 v92, v230, v34, s[82:83]
	v_mul_f32_e32 v34, 0x3e000000, v57
	v_max3_f32 v32, v32, v88, v89
	v_cndmask_b32_e64 v93, v230, v34, s[84:85]
	v_mul_f32_e32 v34, 0x3e000000, v58
	v_max3_f32 v32, v32, v90, v91
	v_cndmask_b32_e64 v58, v230, v34, s[86:87]
	v_mul_f32_e32 v34, 0x3e000000, v59
	v_mul_f32_e32 v16, 0x3e000000, v16
	v_max3_f32 v32, v32, v92, v93
	v_cndmask_b32_e64 v59, v230, v34, s[88:89]
	v_cndmask_b32_e64 v94, v230, v16, s[90:91]
	v_mul_f32_e32 v16, 0x3e000000, v17
	v_mul_f32_e32 v17, 0x3e000000, v18
	v_max3_f32 v32, v32, v58, v59
	v_cndmask_b32_e64 v95, v230, v16, s[92:93]
	v_cndmask_b32_e64 v96, v230, v17, s[94:95]
	v_mul_f32_e32 v17, 0x3e000000, v19
	v_max3_f32 v16, v32, v94, v95
	v_cndmask_b32_e64 v97, v230, v17, s[96:97]
	v_max3_f32 v16, v16, v96, v97
	ds_bpermute_b32 v17, v64, v16
	s_waitcnt lgkmcnt(0)
	v_max_f32_e32 v17, v17, v17
	v_max_f32_e32 v16, v16, v17
	ds_bpermute_b32 v17, v65, v16
	s_waitcnt lgkmcnt(0)
	v_max_f32_e32 v17, v17, v17
	v_max_f32_e32 v98, v16, v17
	v_sub_f32_e32 v8, v8, v98
	v_mul_f32_e32 v8, 0x3fb8aa3b, v8
	v_exp_f32_e32 v50, v8
	v_sub_f32_e32 v8, v9, v98
	v_sub_f32_e32 v9, v12, v98
	v_mul_f32_e32 v9, 0x3fb8aa3b, v9
	v_exp_f32_e32 v54, v9
	v_sub_f32_e32 v9, v13, v98
	v_mul_f32_e32 v9, 0x3fb8aa3b, v9
	v_exp_f32_e32 v56, v9
	v_sub_f32_e32 v9, v14, v98
	v_mul_f32_e32 v9, 0x3fb8aa3b, v9
	v_exp_f32_e32 v55, v9
	v_sub_f32_e32 v9, v15, v98
	v_mul_f32_e32 v9, 0x3fb8aa3b, v9
	v_exp_f32_e32 v57, v9
	v_sub_f32_e32 v9, v20, v98
	v_mul_f32_e32 v9, 0x3fb8aa3b, v9
	v_exp_f32_e32 v42, v9
	v_sub_f32_e32 v9, v21, v98
	v_mul_f32_e32 v9, 0x3fb8aa3b, v9
	v_exp_f32_e32 v44, v9
	v_sub_f32_e32 v9, v22, v98
	v_mul_f32_e32 v9, 0x3fb8aa3b, v9
	v_exp_f32_e32 v43, v9
	v_sub_f32_e32 v9, v23, v98
	v_mul_f32_e32 v9, 0x3fb8aa3b, v9
	v_exp_f32_e32 v45, v9
	v_sub_f32_e32 v9, v24, v98
	v_mul_f32_e32 v9, 0x3fb8aa3b, v9
	v_exp_f32_e32 v46, v9
	v_sub_f32_e32 v9, v25, v98
	v_mul_f32_e32 v9, 0x3fb8aa3b, v9
	v_exp_f32_e32 v48, v9
	v_sub_f32_e32 v9, v26, v98
	v_mul_f32_e32 v9, 0x3fb8aa3b, v9
	v_exp_f32_e32 v47, v9
	v_sub_f32_e32 v9, v27, v98
	v_mul_f32_e32 v9, 0x3fb8aa3b, v9
	v_exp_f32_e32 v49, v9
	v_sub_f32_e32 v9, v28, v98
	v_mul_f32_e32 v9, 0x3fb8aa3b, v9
	v_exp_f32_e32 v34, v9
	v_sub_f32_e32 v9, v29, v98
	v_mul_f32_e32 v9, 0x3fb8aa3b, v9
	v_exp_f32_e32 v36, v9
	v_sub_f32_e32 v9, v30, v98
	v_mul_f32_e32 v9, 0x3fb8aa3b, v9
	v_exp_f32_e32 v35, v9
	v_sub_f32_e32 v9, v31, v98
	v_mul_f32_e32 v8, 0x3fb8aa3b, v8
	v_mul_f32_e32 v9, 0x3fb8aa3b, v9
	v_exp_f32_e32 v52, v8
	v_sub_f32_e32 v8, v10, v98
	v_exp_f32_e32 v37, v9
	v_sub_f32_e32 v9, v33, v98
	v_mul_f32_e32 v8, 0x3fb8aa3b, v8
	v_mul_f32_e32 v9, 0x3fb8aa3b, v9
	v_exp_f32_e32 v51, v8
	v_sub_f32_e32 v8, v11, v98
	v_exp_f32_e32 v38, v9
	v_sub_f32_e32 v9, v69, v98
	v_mul_f32_e32 v8, 0x3fb8aa3b, v8
	v_mul_f32_e32 v9, 0x3fb8aa3b, v9
	v_exp_f32_e32 v53, v8
	v_exp_f32_e32 v40, v9
	v_sub_f32_e32 v9, v70, v98
	v_add_f32_e32 v8, 0, v50
	v_mul_f32_e32 v9, 0x3fb8aa3b, v9
	v_add_f32_e32 v8, v52, v8
	v_exp_f32_e32 v39, v9
	v_sub_f32_e32 v9, v71, v98
	v_add_f32_e32 v8, v51, v8
	v_mul_f32_e32 v9, 0x3fb8aa3b, v9
	v_add_f32_e32 v8, v53, v8
	v_exp_f32_e32 v41, v9
	v_sub_f32_e32 v9, v75, v98
	v_add_f32_e32 v8, v54, v8
	v_mul_f32_e32 v9, 0x3fb8aa3b, v9
	v_add_f32_e32 v8, v56, v8
	v_exp_f32_e32 v26, v9
	v_sub_f32_e32 v9, v76, v98
	v_add_f32_e32 v8, v55, v8
	v_mul_f32_e32 v9, 0x3fb8aa3b, v9
	v_add_f32_e32 v8, v57, v8
	v_exp_f32_e32 v28, v9
	v_sub_f32_e32 v9, v77, v98
	v_add_f32_e32 v8, v42, v8
	v_mul_f32_e32 v9, 0x3fb8aa3b, v9
	v_add_f32_e32 v8, v44, v8
	v_exp_f32_e32 v27, v9
	v_sub_f32_e32 v9, v78, v98
	v_add_f32_e32 v8, v43, v8
	v_mul_f32_e32 v9, 0x3fb8aa3b, v9
	v_add_f32_e32 v8, v45, v8
	v_exp_f32_e32 v29, v9
	v_sub_f32_e32 v9, v79, v98
	v_add_f32_e32 v8, v46, v8
	v_mul_f32_e32 v9, 0x3fb8aa3b, v9
	v_add_f32_e32 v8, v48, v8
	v_exp_f32_e32 v30, v9
	v_sub_f32_e32 v9, v81, v98
	v_add_f32_e32 v8, v47, v8
	v_mul_f32_e32 v9, 0x3fb8aa3b, v9
	v_add_f32_e32 v8, v49, v8
	v_exp_f32_e32 v32, v9
	v_sub_f32_e32 v9, v82, v98
	v_add_f32_e32 v8, v34, v8
	v_mul_f32_e32 v9, 0x3fb8aa3b, v9
	v_add_f32_e32 v8, v36, v8
	v_exp_f32_e32 v31, v9
	v_sub_f32_e32 v9, v83, v98
	v_add_f32_e32 v8, v35, v8
	v_mul_f32_e32 v9, 0x3fb8aa3b, v9
	v_add_f32_e32 v8, v37, v8
	v_exp_f32_e32 v33, v9
	v_sub_f32_e32 v9, v84, v98
	v_add_f32_e32 v8, v38, v8
	v_mul_f32_e32 v9, 0x3fb8aa3b, v9
	v_add_f32_e32 v8, v40, v8
	v_exp_f32_e32 v16, v9
	v_sub_f32_e32 v9, v85, v98
	v_add_f32_e32 v8, v39, v8
	v_mul_f32_e32 v9, 0x3fb8aa3b, v9
	v_add_f32_e32 v8, v41, v8
	v_exp_f32_e32 v18, v9
	v_sub_f32_e32 v9, v86, v98
	v_add_f32_e32 v8, v26, v8
	v_mul_f32_e32 v9, 0x3fb8aa3b, v9
	v_add_f32_e32 v8, v28, v8
	v_exp_f32_e32 v17, v9
	v_sub_f32_e32 v9, v87, v98
	v_add_f32_e32 v8, v27, v8
	v_mul_f32_e32 v9, 0x3fb8aa3b, v9
	v_add_f32_e32 v8, v29, v8
	v_exp_f32_e32 v19, v9
	v_sub_f32_e32 v9, v88, v98
	v_add_f32_e32 v8, v30, v8
	v_mul_f32_e32 v9, 0x3fb8aa3b, v9
	v_add_f32_e32 v8, v32, v8
	v_exp_f32_e32 v22, v9
	v_sub_f32_e32 v9, v89, v98
	v_add_f32_e32 v8, v31, v8
	v_mul_f32_e32 v9, 0x3fb8aa3b, v9
	v_add_f32_e32 v8, v33, v8
	v_exp_f32_e32 v24, v9
	v_sub_f32_e32 v9, v90, v98
	v_add_f32_e32 v8, v16, v8
	v_mul_f32_e32 v9, 0x3fb8aa3b, v9
	v_add_f32_e32 v8, v18, v8
	v_exp_f32_e32 v23, v9
	v_sub_f32_e32 v9, v91, v98
	v_add_f32_e32 v8, v17, v8
	v_mul_f32_e32 v9, 0x3fb8aa3b, v9
	v_add_f32_e32 v8, v19, v8
	v_exp_f32_e32 v25, v9
	v_add_f32_e32 v8, v22, v8
	v_add_f32_e32 v8, v24, v8
	v_add_f32_e32 v8, v23, v8
	v_add_f32_e32 v12, v25, v8
	v_sub_f32_e32 v8, v92, v98
	v_sub_f32_e32 v9, v93, v98
	v_mul_f32_e32 v8, 0x3fb8aa3b, v8
	v_mul_f32_e32 v9, 0x3fb8aa3b, v9
	v_exp_f32_e32 v8, v8
	v_exp_f32_e32 v10, v9
	v_sub_f32_e32 v9, v58, v98
	v_mul_f32_e32 v9, 0x3fb8aa3b, v9
	v_sub_f32_e32 v11, v59, v98
	v_exp_f32_e32 v9, v9
	v_mul_f32_e32 v11, 0x3fb8aa3b, v11
	v_exp_f32_e32 v11, v11
	v_add_f32_e32 v12, v8, v12
	v_add_f32_e32 v12, v10, v12
	v_add_f32_e32 v12, v9, v12
	v_add_f32_e32 v20, v11, v12
	v_sub_f32_e32 v12, v94, v98
	v_sub_f32_e32 v13, v95, v98
	v_mul_f32_e32 v12, 0x3fb8aa3b, v12
	v_mul_f32_e32 v13, 0x3fb8aa3b, v13
	v_exp_f32_e32 v12, v12
	v_exp_f32_e32 v14, v13
	v_sub_f32_e32 v13, v96, v98
	v_mul_f32_e32 v13, 0x3fb8aa3b, v13
	v_sub_f32_e32 v15, v97, v98
	v_exp_f32_e32 v13, v13
	v_mul_f32_e32 v15, 0x3fb8aa3b, v15
	v_exp_f32_e32 v15, v15
	v_add_f32_e32 v20, v12, v20
	v_add_f32_e32 v20, v14, v20
	v_add_f32_e32 v20, v13, v20
	v_add_f32_e32 v20, v15, v20
	ds_bpermute_b32 v21, v64, v20
	v_sub_f32_e32 v58, v68, v98
	v_mul_f32_e32 v58, 0x3fb8aa3b, v58
	v_exp_f32_e32 v58, v58
	s_waitcnt lgkmcnt(0)
	v_add_f32_e32 v20, v20, v21
	ds_bpermute_b32 v21, v65, v20
	s_waitcnt lgkmcnt(0)
	v_add_f32_e32 v20, v20, v21
	v_add_f32_e32 v20, v58, v20
	v_div_scale_f32 v21, vcc, v20, v20, 1.0
	v_rcp_f32_e32 v58, v21
	v_div_scale_f32 v59, vcc, 1.0, v20, 1.0
	v_add_u32_e32 v75, 0x9000, v67
	v_fma_f32 v68, -v21, v58, 1.0
	v_fmac_f32_e32 v58, v68, v58
	v_mul_f32_e32 v68, v59, v58
	v_fma_f32 v69, -v21, v68, v59
	v_fmac_f32_e32 v68, v69, v58
	v_fma_f32 v21, -v21, v68, v59
	v_div_fmas_f32 v21, v21, v58, v68
	v_div_fixup_f32 v20, v21, v20, 1.0
	v_pk_mul_f32 v[52:53], v[52:53], v[20:21] op_sel_hi:[1,0]
	v_pk_mul_f32 v[56:57], v[56:57], v[20:21] op_sel_hi:[1,0]
	v_pk_mul_f32 v[50:51], v[50:51], v[20:21] op_sel_hi:[1,0]
	v_pk_mul_f32 v[54:55], v[54:55], v[20:21] op_sel_hi:[1,0]
	v_bfe_u32 v21, v57, 16, 1
	v_bfe_u32 v58, v56, 16, 1
	v_bfe_u32 v59, v53, 16, 1
	s_nop 0
	s_nop 0
	v_add3_u32 v59, v53, v59, s33
	v_add3_u32 v56, v56, v58, s33
	v_add3_u32 v21, v57, v21, s33
	s_nop 0
	v_bfe_u32 v53, v51, 16, 1
	v_bfe_u32 v57, v54, 16, 1
	v_bfe_u32 v58, v55, 16, 1
	v_add3_u32 v55, v55, v58, s33
	v_add3_u32 v54, v54, v57, s33
	v_add3_u32 v57, v51, v53, s33
	s_nop 0
	s_nop 0
	v_lshrrev_b32_e32 v69, 16, v57
	v_lshrrev_b32_e32 v54, 16, v54
	v_lshrrev_b32_e32 v55, 16, v55
	v_and_or_b32 v57, v21, s29, v55
	v_and_or_b32 v56, v56, s29, v54
	v_and_or_b32 v55, v59, s29, v69
	v_cvt_pk_bf16_f32 v54, v50, v52
	v_add_u32_e32 v58, 0xb000, v67
	v_add_u32_e32 v59, 0xd000, v67
	v_add_u32_e32 v81, 0xf000, v67
	ds_read2_b64 v[50:53], v75 offset1:4
	ds_read2_b64 v[68:71], v58 offset0:32 offset1:36
	ds_read2_b64 v[76:79], v59 offset0:64 offset1:68
	ds_read2_b64 v[82:85], v81 offset0:96 offset1:100
	s_waitcnt lgkmcnt(3)
	v_mfma_f32_16x16x32_bf16 v[50:53], v[50:53], v[54:57], 0
	s_waitcnt lgkmcnt(2)
	v_mfma_f32_16x16x32_bf16 v[68:71], v[68:71], v[54:57], 0
	s_waitcnt lgkmcnt(1)
	v_mfma_f32_16x16x32_bf16 v[76:79], v[76:79], v[54:57], 0
	s_waitcnt lgkmcnt(0)
	v_mfma_f32_16x16x32_bf16 v[54:57], v[82:85], v[54:57], 0
	ds_read2_b64 v[116:119], v75 offset0:8 offset1:12
	ds_read2_b64 v[120:123], v58 offset0:40 offset1:44
	ds_read2_b64 v[124:127], v59 offset0:72 offset1:76
	ds_read2_b64 v[128:131], v81 offset0:104 offset1:108
	v_mul_f32_e64 v44, v44, v20
	v_mul_f32_e64 v45, v45, v20
	v_pk_mul_f32 v[48:49], v[48:49], v[20:21] op_sel_hi:[1,0]
	v_pk_mul_f32 v[42:43], v[42:43], v[20:21] op_sel_hi:[1,0]
	v_pk_mul_f32 v[46:47], v[46:47], v[20:21] op_sel_hi:[1,0]
	v_bfe_u32 v21, v49, 16, 1
	v_bfe_u32 v82, v48, 16, 1
	v_bfe_u32 v83, v45, 16, 1
	v_bfe_u32 v84, v44, 16, 1
	v_add3_u32 v84, v44, v84, s33
	v_add3_u32 v83, v45, v83, s33
	v_add3_u32 v48, v48, v82, s33
	v_add3_u32 v21, v49, v21, s33
	v_bfe_u32 v44, v42, 16, 1
	v_bfe_u32 v45, v43, 16, 1
	v_bfe_u32 v49, v46, 16, 1
	v_bfe_u32 v82, v47, 16, 1
	v_add3_u32 v47, v47, v82, s33
	v_add3_u32 v46, v46, v49, s33
	v_add3_u32 v49, v43, v45, s33
	v_add3_u32 v82, v42, v44, s33
	v_lshrrev_b32_e32 v82, 16, v82
	v_lshrrev_b32_e32 v85, 16, v49
	v_lshrrev_b32_e32 v46, 16, v46
	v_lshrrev_b32_e32 v47, 16, v47
	v_and_or_b32 v49, v21, s29, v47
	v_and_or_b32 v48, v48, s29, v46
	v_and_or_b32 v47, v83, s29, v85
	v_and_or_b32 v46, v84, s29, v82
	s_waitcnt lgkmcnt(3)
	s_nop 1
	v_mfma_f32_16x16x32_bf16 v[42:45], v[116:119], v[46:49], v[50:53]
	s_waitcnt lgkmcnt(2)
	v_mfma_f32_16x16x32_bf16 v[50:53], v[120:123], v[46:49], v[68:71]
	s_waitcnt lgkmcnt(1)
	v_mfma_f32_16x16x32_bf16 v[68:71], v[124:127], v[46:49], v[76:79]
	s_waitcnt lgkmcnt(0)
	v_mfma_f32_16x16x32_bf16 v[46:49], v[128:131], v[46:49], v[54:57]
	ds_read2_b64 v[132:135], v75 offset0:16 offset1:20
	ds_read2_b64 v[136:139], v58 offset0:48 offset1:52
	ds_read2_b64 v[140:143], v59 offset0:80 offset1:84
	ds_read2_b64 v[144:147], v81 offset0:112 offset1:116
	v_mul_f32_e64 v36, v36, v20
	v_mul_f32_e64 v37, v37, v20
	v_pk_mul_f32 v[40:41], v[40:41], v[20:21] op_sel_hi:[1,0]
	v_pk_mul_f32 v[34:35], v[34:35], v[20:21] op_sel_hi:[1,0]
	v_pk_mul_f32 v[38:39], v[38:39], v[20:21] op_sel_hi:[1,0]
	v_bfe_u32 v21, v41, 16, 1
	v_bfe_u32 v54, v40, 16, 1
	v_bfe_u32 v55, v37, 16, 1
	v_bfe_u32 v56, v36, 16, 1
	v_add3_u32 v56, v36, v56, s33
	v_add3_u32 v55, v37, v55, s33
	v_add3_u32 v40, v40, v54, s33
	v_add3_u32 v21, v41, v21, s33
	v_bfe_u32 v36, v34, 16, 1
	v_bfe_u32 v37, v35, 16, 1
	v_bfe_u32 v41, v38, 16, 1
	v_bfe_u32 v54, v39, 16, 1
	v_add3_u32 v39, v39, v54, s33
	v_add3_u32 v38, v38, v41, s33
	v_add3_u32 v41, v35, v37, s33
	v_add3_u32 v54, v34, v36, s33
	v_lshrrev_b32_e32 v54, 16, v54
	v_lshrrev_b32_e32 v57, 16, v41
	v_lshrrev_b32_e32 v38, 16, v38
	v_lshrrev_b32_e32 v39, 16, v39
	v_and_or_b32 v41, v21, s29, v39
	v_and_or_b32 v40, v40, s29, v38
	v_and_or_b32 v39, v55, s29, v57
	v_and_or_b32 v38, v56, s29, v54
	s_waitcnt lgkmcnt(3)
	s_nop 1
	v_mfma_f32_16x16x32_bf16 v[34:37], v[132:135], v[38:41], v[42:45]
	s_waitcnt lgkmcnt(2)
	v_mfma_f32_16x16x32_bf16 v[42:45], v[136:139], v[38:41], v[50:53]
	s_waitcnt lgkmcnt(1)
	v_mfma_f32_16x16x32_bf16 v[50:53], v[140:143], v[38:41], v[68:71]
	s_waitcnt lgkmcnt(0)
	v_mfma_f32_16x16x32_bf16 v[38:41], v[144:147], v[38:41], v[46:49]
	ds_read2_b64 v[116:119], v75 offset0:24 offset1:28
	ds_read2_b64 v[120:123], v58 offset0:56 offset1:60
	ds_read2_b64 v[124:127], v59 offset0:88 offset1:92
	ds_read2_b64 v[128:131], v81 offset0:120 offset1:124
	v_mul_f32_e64 v28, v28, v20
	v_mul_f32_e64 v29, v29, v20
	v_pk_mul_f32 v[32:33], v[32:33], v[20:21] op_sel_hi:[1,0]
	v_pk_mul_f32 v[26:27], v[26:27], v[20:21] op_sel_hi:[1,0]
	v_pk_mul_f32 v[30:31], v[30:31], v[20:21] op_sel_hi:[1,0]
	v_bfe_u32 v21, v33, 16, 1
	v_bfe_u32 v46, v32, 16, 1
	v_bfe_u32 v47, v29, 16, 1
	v_bfe_u32 v48, v28, 16, 1
	v_add3_u32 v48, v28, v48, s33
	v_add3_u32 v47, v29, v47, s33
	v_add3_u32 v32, v32, v46, s33
	v_add3_u32 v21, v33, v21, s33
	v_bfe_u32 v28, v26, 16, 1
	v_bfe_u32 v29, v27, 16, 1
	v_bfe_u32 v33, v30, 16, 1
	v_bfe_u32 v46, v31, 16, 1
	v_add3_u32 v31, v31, v46, s33
	v_add3_u32 v30, v30, v33, s33
	v_add3_u32 v33, v27, v29, s33
	v_add3_u32 v46, v26, v28, s33
	v_lshrrev_b32_e32 v46, 16, v46
	v_lshrrev_b32_e32 v49, 16, v33
	v_lshrrev_b32_e32 v30, 16, v30
	v_lshrrev_b32_e32 v31, 16, v31
	v_and_or_b32 v33, v21, s29, v31
	v_and_or_b32 v32, v32, s29, v30
	v_and_or_b32 v31, v47, s29, v49
	v_and_or_b32 v30, v48, s29, v46
	s_waitcnt lgkmcnt(3)
	s_nop 1
	v_mfma_f32_16x16x32_bf16 v[26:29], v[116:119], v[30:33], v[34:37]
	s_waitcnt lgkmcnt(2)
	v_mfma_f32_16x16x32_bf16 v[34:37], v[120:123], v[30:33], v[42:45]
	s_waitcnt lgkmcnt(1)
	v_mfma_f32_16x16x32_bf16 v[42:45], v[124:127], v[30:33], v[50:53]
	s_waitcnt lgkmcnt(0)
	v_mfma_f32_16x16x32_bf16 v[30:33], v[128:131], v[30:33], v[38:41]
	ds_read2_b64 v[132:135], v75 offset0:32 offset1:36
	ds_read2_b64 v[136:139], v58 offset0:64 offset1:68
	ds_read2_b64 v[140:143], v59 offset0:96 offset1:100
	ds_read2_b64 v[144:147], v81 offset0:128 offset1:132
	v_mul_f32_e64 v18, v18, v20
	v_mul_f32_e64 v19, v19, v20
	v_pk_mul_f32 v[24:25], v[24:25], v[20:21] op_sel_hi:[1,0]
	v_pk_mul_f32 v[16:17], v[16:17], v[20:21] op_sel_hi:[1,0]
	v_pk_mul_f32 v[22:23], v[22:23], v[20:21] op_sel_hi:[1,0]
	v_bfe_u32 v21, v25, 16, 1
	v_bfe_u32 v38, v24, 16, 1
	v_bfe_u32 v39, v19, 16, 1
	s_nop 0
	s_nop 0
	v_add3_u32 v39, v19, v39, s33
	v_add3_u32 v24, v24, v38, s33
	v_add3_u32 v21, v25, v21, s33
	s_nop 0
	v_bfe_u32 v19, v17, 16, 1
	v_bfe_u32 v25, v22, 16, 1
	v_bfe_u32 v38, v23, 16, 1
	v_add3_u32 v23, v23, v38, s33
	v_add3_u32 v22, v22, v25, s33
	v_add3_u32 v25, v17, v19, s33
	s_nop 0
	s_nop 0
	v_lshrrev_b32_e32 v41, 16, v25
	v_lshrrev_b32_e32 v22, 16, v22
	v_lshrrev_b32_e32 v23, 16, v23
	v_and_or_b32 v25, v21, s29, v23
	v_and_or_b32 v24, v24, s29, v22
	v_and_or_b32 v23, v39, s29, v41
	v_cvt_pk_bf16_f32 v22, v16, v18
	s_waitcnt lgkmcnt(3)
	s_nop 1
	v_mfma_f32_16x16x32_bf16 v[16:19], v[132:135], v[22:25], v[26:29]
	s_waitcnt lgkmcnt(2)
	v_mfma_f32_16x16x32_bf16 v[26:29], v[136:139], v[22:25], v[34:37]
	s_waitcnt lgkmcnt(1)
	v_mfma_f32_16x16x32_bf16 v[34:37], v[140:143], v[22:25], v[42:45]
	s_waitcnt lgkmcnt(0)
	v_mfma_f32_16x16x32_bf16 v[30:33], v[144:147], v[22:25], v[30:33]
	ds_read2_b64 v[116:119], v75 offset0:40 offset1:44
	ds_read2_b64 v[120:123], v58 offset0:72 offset1:76
	ds_read2_b64 v[124:127], v59 offset0:104 offset1:108
	ds_read2_b64 v[128:131], v81 offset0:136 offset1:140
	v_mul_f32_e64 v10, v10, v20
	v_mul_f32_e64 v11, v11, v20
	v_pk_mul_f32 v[14:15], v[14:15], v[20:21] op_sel_hi:[1,0]
	v_pk_mul_f32 v[8:9], v[8:9], v[20:21] op_sel_hi:[1,0]
	v_pk_mul_f32 v[12:13], v[12:13], v[20:21] op_sel_hi:[1,0]
	v_bfe_u32 v20, v15, 16, 1
	v_bfe_u32 v21, v14, 16, 1
	s_nop 0
	s_nop 0
	s_nop 0
	s_nop 0
	v_add3_u32 v14, v14, v21, s33
	v_add3_u32 v15, v15, v20, s33
	s_nop 0
	s_nop 0
	v_bfe_u32 v20, v12, 16, 1
	v_bfe_u32 v21, v13, 16, 1
	v_add3_u32 v13, v13, v21, s33
	v_add3_u32 v12, v12, v20, s33
	s_nop 0
	s_nop 0
	s_nop 0
	s_nop 0
	v_lshrrev_b32_e32 v12, 16, v12
	v_lshrrev_b32_e32 v13, 16, v13
	v_and_or_b32 v41, v15, s29, v13
	v_and_or_b32 v40, v14, s29, v12
	v_cvt_pk_bf16_f32 v39, v9, v11
	v_cvt_pk_bf16_f32 v38, v8, v10
	s_waitcnt lgkmcnt(3)
	s_nop 1
	v_mfma_f32_16x16x32_bf16 v[20:23], v[116:119], v[38:41], v[16:19]
	s_waitcnt lgkmcnt(2)
	v_mfma_f32_16x16x32_bf16 v[16:19], v[120:123], v[38:41], v[26:29]
	s_waitcnt lgkmcnt(1)
	v_mfma_f32_16x16x32_bf16 v[12:15], v[124:127], v[38:41], v[34:37]
	s_waitcnt lgkmcnt(0)
	v_mfma_f32_16x16x32_bf16 v[8:11], v[128:131], v[38:41], v[30:33]
	s_and_saveexec_b64 vcc, s[0:1]
	s_cbranch_execz .LBB0_311
	v_bfe_u32 v26, v20, 16, 1
	v_add3_u32 v20, v20, v26, s33
	v_bfe_u32 v26, v21, 16, 1
	v_add3_u32 v21, v21, v26, s33
	v_lshrrev_b32_e32 v20, 16, v20
	v_and_or_b32 v20, v21, s29, v20
	s_nop 0
	s_nop 0
	s_nop 0
	s_nop 0
	s_nop 0
	v_lshl_add_u64 v[24:25], v[60:61], 0, s[2:3]
	v_cvt_pk_bf16_f32 v21, v22, v23
	global_store_dwordx2 v[24:25], v[20:21], off
	v_bfe_u32 v20, v16, 16, 1
	v_add3_u32 v16, v16, v20, s33
	v_bfe_u32 v20, v17, 16, 1
	v_add3_u32 v17, v17, v20, s33
	v_lshrrev_b32_e32 v16, 16, v16
	v_and_or_b32 v16, v17, s29, v16
	s_nop 0
	s_nop 0
	s_nop 0
	s_nop 0
	s_nop 0
	v_cvt_pk_bf16_f32 v17, v18, v19
	global_store_dwordx2 v[24:25], v[16:17], off offset:32
	v_bfe_u32 v16, v12, 16, 1
	v_add3_u32 v12, v12, v16, s33
	v_bfe_u32 v16, v13, 16, 1
	v_add3_u32 v13, v13, v16, s33
	v_lshrrev_b32_e32 v12, 16, v12
	v_and_or_b32 v12, v13, s29, v12
	s_nop 0
	s_nop 0
	s_nop 0
	s_nop 0
	s_nop 0
	v_cvt_pk_bf16_f32 v13, v14, v15
	global_store_dwordx2 v[24:25], v[12:13], off offset:64
	v_bfe_u32 v12, v8, 16, 1
	v_add3_u32 v8, v8, v12, s33
	v_bfe_u32 v12, v9, 16, 1
	v_add3_u32 v9, v9, v12, s33
	v_lshrrev_b32_e32 v8, 16, v8
	v_and_or_b32 v8, v9, s29, v8
	s_nop 0
	s_nop 0
	s_nop 0
	s_nop 0
	s_nop 0
	v_cvt_pk_bf16_f32 v9, v10, v11
	global_store_dwordx2 v[24:25], v[8:9], off offset:96
	s_branch .LBB0_311

.LBB0_341:
	s_andn2_saveexec_b64 s[2:3], s[2:3]
	s_cbranch_execz .LBB0_327
	s_andn2_b64 vcc, exec, s[20:21]
	s_cbranch_vccnz .LBB0_327
	v_bfe_u32 v17, v32, 16, 1
	v_add3_u32 v22, v32, v17, s33
	v_bfe_u32 v17, v44, 16, 1
	v_bfe_u32 v18, v45, 16, 1
	v_bfe_u32 v19, v48, 16, 1
	v_bfe_u32 v23, v49, 16, 1
	v_bfe_u32 v6, v29, 16, 1
	v_bfe_u32 v7, v28, 16, 1
	v_bfe_u32 v16, v33, 16, 1
	v_add3_u32 v23, v49, v23, s33
	v_add3_u32 v19, v48, v19, s33
	v_add3_u32 v18, v45, v18, s33
	v_add3_u32 v17, v44, v17, s33
	v_add3_u32 v16, v33, v16, s33
	v_add3_u32 v7, v28, v7, s33
	v_add3_u32 v6, v29, v6, s33
	v_lshrrev_b32_e32 v26, 16, v17
	v_lshrrev_b32_e32 v17, 16, v18
	v_lshrrev_b32_e32 v18, 16, v19
	v_lshrrev_b32_e32 v19, 16, v23
	v_and_or_b32 v19, v6, s29, v19
	v_and_or_b32 v18, v7, s29, v18
	v_and_or_b32 v17, v16, s29, v17
	v_and_or_b32 v16, v22, s29, v26
	v_bfe_u32 v7, v20, 16, 1
	global_store_dwordx4 v[134:135], v[16:19], off
	v_add3_u32 v7, v20, v7, s33
	v_bfe_u32 v20, v11, 16, 1
	v_bfe_u32 v17, v24, 16, 1
	v_bfe_u32 v19, v10, 16, 1
	v_bfe_u32 v6, v21, 16, 1
	v_add3_u32 v22, v24, v17, s33
	v_bfe_u32 v17, v40, 16, 1
	v_bfe_u32 v18, v41, 16, 1
	v_add3_u32 v11, v11, v20, s33
	v_add3_u32 v10, v10, v19, s33
	v_add3_u32 v6, v21, v6, s33
	v_add3_u32 v18, v41, v18, s33
	v_add3_u32 v17, v40, v17, s33
	v_lshrrev_b32_e32 v10, 16, v10
	v_lshrrev_b32_e32 v11, 16, v11
	v_lshrrev_b32_e32 v20, 16, v17
	v_lshrrev_b32_e32 v17, 16, v18
	v_and_or_b32 v19, v6, s29, v11
	v_and_or_b32 v18, v7, s29, v10
	v_bfe_u32 v6, v9, 16, 1
	v_bfe_u32 v7, v8, 16, 1
	v_bfe_u32 v10, v13, 16, 1
	v_bfe_u32 v11, v12, 16, 1
	v_add3_u32 v11, v12, v11, s33
	v_add3_u32 v10, v13, v10, s33
	v_add3_u32 v7, v8, v7, s33
	v_add3_u32 v6, v9, v6, s33
	v_bfe_u32 v8, v0, 16, 1
	v_bfe_u32 v9, v1, 16, 1
	v_bfe_u32 v12, v36, 16, 1
	v_bfe_u32 v13, v37, 16, 1
	v_add3_u32 v13, v37, v13, s33
	v_add3_u32 v12, v36, v12, s33
	v_add3_u32 v1, v1, v9, s33
	v_add3_u32 v0, v0, v8, s33
	v_lshrrev_b32_e32 v0, 16, v0
	v_lshrrev_b32_e32 v1, 16, v1
	v_lshrrev_b32_e32 v8, 16, v12
	v_lshrrev_b32_e32 v9, 16, v13
	v_and_or_b32 v9, v6, s29, v9
	v_and_or_b32 v8, v7, s29, v8
	v_and_or_b32 v7, v10, s29, v1
	v_and_or_b32 v6, v11, s29, v0
	global_store_dwordx4 v[134:135], v[6:9], off offset:32
	s_nop 0
	s_nop 0
	v_bfe_u32 v6, v3, 16, 1
	v_bfe_u32 v7, v2, 16, 1
	v_add3_u32 v7, v2, v7, s33
	v_add3_u32 v6, v3, v6, s33
	s_nop 0
	s_nop 0
	v_bfe_u32 v2, v14, 16, 1
	v_bfe_u32 v3, v15, 16, 1
	s_nop 0
	s_nop 0
	v_bfe_u32 v16, v25, 16, 1
	s_nop 0
	s_nop 0
	v_add3_u32 v3, v15, v3, s33
	v_add3_u32 v2, v14, v2, s33
	v_add3_u32 v16, v25, v16, s33
	v_lshrrev_b32_e32 v8, 16, v2
	v_lshrrev_b32_e32 v9, 16, v3
	s_nop 0
	s_nop 0
	v_and_or_b32 v17, v16, s29, v17
	v_and_or_b32 v16, v22, s29, v20
	v_cvt_pk_bf16_f32 v3, v35, v5
	v_cvt_pk_bf16_f32 v2, v34, v4
	v_and_or_b32 v1, v6, s29, v9
	v_and_or_b32 v0, v7, s29, v8
	global_store_dwordx4 v[134:135], v[16:19], off offset:16
	global_store_dwordx4 v[134:135], v[0:3], off offset:48
	s_branch .LBB0_327
